# branch-gate logits stored fragment-major (each wave store/load = 2x512 contiguous bytes instead of 16 scattered 64-byte row pieces): cheaper store issue in the input projection, 4x cheaper gate loads
# speedup vs baseline: 1.0175x; 1.0136x over previous
; DI bf16_t f2bf(float x) { return (bf16_t)(pk2(x, 0.f) & 0xffffu); }
;     DI void operator()(Acc& acc, const Unit& u, int wr, int wc, int fr, int fq) const {
;         asm volatile("" : "+v"(fr), "+v"(fq));
;         const int pn = u.pn;
;         f32x4 lbv[2][2];
;         if (u.pm < 132 && (pn == 5 || pn == 6)) {
; #pragma unroll
;             for (int bj = 0; bj < 2; ++bj) { const int c = (pn - 5) * 256 + bj * 128 + wc * 32 + fq * 8; lbv[bj][0] = *(const f32x4*)(lb + c); lbv[bj][1] = *(const f32x4*)(lb + c + 4); }
;         }
;         if (u.pm >= 132) {
;             const int b = u.pm - 132, kv = (pn - 25) >> 1;
; #pragma unroll
;             for (int ai = 0; ai < 2; ++ai)
; #pragma unroll
;                 for (int m = 0; m < 4; ++m) { const int s = ai * 128 + wr * 64 + m * 16 + fr;
; #pragma unroll
;                     for (int bj = 0; bj < 2; ++bj) { const int h = 2 * ((pn - 25) & 1) + bj, d = wc * 32 + fq * 8;
;                         const f32x4 v0 = acc[ai][bj][m][0], v1 = acc[ai][bj][m][1];
;                         float* o = out + (kv ? O_MVP : O_MKP) + ((size_t)(b * 256 + s) * 4 + h) * 128 + d;
;                         *(f32x4*)o = v0; *(f32x4*)(o + 4) = v1;
;                         if (kv == 0) *(u32x4*)(mkb + ((((((size_t)(b * 4 + h) * 8 + (s >> 5)) * 8 + (d >> 4)) * 2 + ((d >> 3) & 1)) * 32 + (s & 31)) * 8)) = pack8(v0, v1);
;                         else { const int w16 = s & 15; bf16_t* t = mvt + (((((size_t)(b * 4 + h) * 16 + (s >> 4)) * 2 + ((w16 >> 2) & 1)) * 128 + d) * 8) + (w16 & 3) + 4 * (w16 >> 3);
; #pragma unroll
;                             for (int j = 0; j < 4; ++j) { t[j * 8] = f2bf(v0[j]); t[(4 + j) * 8] = f2bf(v1[j]); } } } }
;             return;
;         }
; #pragma unroll
;         for (int ai = 0; ai < 2; ++ai)
; #pragma unroll
;             for (int m = 0; m < 4; ++m) { const int row = u.pm * 256 + ai * 128 + wr * 64 + m * 16 + fr;
;                 bf16_t* prow = proj + (size_t)row * NPJ + pn * 256 + wc * 32 + fq * 8;
; #pragma unroll
;                 for (int bj = 0; bj < 2; ++bj) { f32x4 v0 = acc[ai][bj][m][0], v1 = acc[ai][bj][m][1];
;     ...
;                     const u32x4 w8 = pack8(v0, v1);
;                     if (mode == 0) *(u32x4*)(prow + bj * 128) = w8; else asm volatile("" :: "v"(w8));
.LBB0_122:
	s_mov_b64 s[4:5], -1
	s_cmpk_gt_i32 s96, 0x83
	v_lshlrev_b32_e32 v193, 5, v154
	v_and_b32_e32 v194, 31, v192
	s_cbranch_scc1 .LBB0_639
	s_lshl_b32 s4, s96, 8
	s_lshl_b32 s54, s94, 8
	s_add_i32 s4, s4, s23
	s_ashr_i32 s55, s54, 31
	s_cmp_lg_u32 s94, 2
	v_add_u32_e32 v200, s4, v192
	s_cselect_b64 s[4:5], -1, 0
	s_cmp_gt_i32 s94, 1
	s_cselect_b64 s[40:41], -1, 0
	s_cmp_gt_u32 s94, 6
	s_cselect_b64 s[52:53], -1, 0
	s_cmp_gt_u32 s94, 8
	v_mov_b64_e32 v[162:163], s[48:49]
	s_cselect_b64 s[18:19], -1, 0
	s_cmp_gt_u32 s94, 12
	v_mad_i64_i32 v[162:163], s[6:7], v200, s50, v[162:163]
	s_cselect_b64 s[16:17], -1, 0
	s_andn2_b64 s[18:19], s[18:19], s[16:17]
	v_lshrrev_b32_e32 v246, 8, v183
	v_lshlrev_b32_e32 v246, 6, v246
	v_bfe_u32 v247, v183, 5, 3
	s_lshl_b32 s100, s96, 8
	v_add3_u32 v246, v246, v247, s100
	v_mul_u32_u24_e32 v246, 0x3200, v246
	v_and_b32_e32 v247, 31, v183
	v_lshlrev_b32_e32 v247, 4, v247
	s_lshl_b32 s100, s94, 9
	v_add3_u32 v246, v246, v247, s100
	v_mov_b32_e32 v247, 0
	v_lshl_add_u64 v[244:245], s[48:49], 0, v[246:247]
	v_lshl_add_u64 v[162:163], s[54:55], 1, v[162:163]
	s_lshl_b32 s28, s33, 1
	v_ashrrev_i32_e32 v161, 31, v160
	v_lshl_add_u64 v[162:163], v[162:163], 0, s[28:29]
	v_and_b32_e32 v154, 0xfff, v200
	v_lshl_add_u64 v[164:165], v[160:161], 1, v[162:163]
	v_cmp_gt_i32_e64 s[8:9], s14, v200
	v_cmp_lt_u32_e64 s[10:11], s51, v154
	s_mov_b64 s[6:7], -1
	s_and_b64 vcc, exec, s[4:5]
	s_cbranch_vccz .LBB0_136
	s_and_b64 vcc, exec, s[40:41]
	s_cbranch_vccz .LBB0_133
	s_cmp_lt_i32 s94, 9
	s_cbranch_scc1 .LBB0_127
	s_cmp_gt_i32 s94, 10
	s_cselect_b64 s[78:79], -1, 0
	s_cbranch_execz .LBB0_128
	s_branch .LBB0_129

; DI u32x4 pack8(f32x4 a, f32x4 b) { u32x4 w; w.x = pk2(a[0], a[1]); w.y = pk2(a[2], a[3]); w.z = pk2(b[0], b[1]); w.w = pk2(b[2], b[3]); return w; }
;     DI void operator()(Acc& acc, const Unit& u, int wr, int wc, int fr, int fq) const {
;     ...
;                     const u32x4 w8 = pack8(v0, v1);
;                     if (mode == 0) *(u32x4*)(prow + bj * 128) = w8; else asm volatile("" :: "v"(w8));
.LBB0_135:
	v_cvt_pk_bf16_f32 v172, v162, v163
	v_cvt_pk_bf16_f32 v173, v166, v167
	v_cvt_pk_bf16_f32 v174, v168, v169
	v_cvt_pk_bf16_f32 v175, v170, v171
	s_mov_b64 s[6:7], 0
	s_mov_b32 s100, 0x0
	s_mov_b32 s101, 0
	v_lshl_add_u64 v[246:247], v[244:245], 0, s[100:101]
	v_cndmask_b32_e64 v164, v164, v246, s[16:17]
	v_cndmask_b32_e64 v165, v165, v247, s[16:17]
	global_store_dwordx4 v[164:165], v[172:175], off

; DI u32x4 pack8(f32x4 a, f32x4 b) { u32x4 w; w.x = pk2(a[0], a[1]); w.y = pk2(a[2], a[3]); w.z = pk2(b[0], b[1]); w.w = pk2(b[2], b[3]); return w; }
;     DI void operator()(Acc& acc, const Unit& u, int wr, int wc, int fr, int fq) const {
;     ...
;                     const u32x4 w8 = pack8(v0, v1);
;                     if (mode == 0) *(u32x4*)(prow + bj * 128) = w8; else asm volatile("" :: "v"(w8));
.LBB0_168:
	v_cvt_pk_bf16_f32 v174, v174, v175
	v_cvt_pk_bf16_f32 v175, v176, v177
	v_cvt_pk_bf16_f32 v176, v178, v179
	v_cvt_pk_bf16_f32 v177, v180, v181
	s_mov_b64 s[78:79], 0
	s_mov_b32 s100, 0x18f00
	s_mov_b32 s101, 0
	v_lshl_add_u64 v[246:247], v[244:245], 0, s[100:101]
	v_cndmask_b32_e64 v164, v164, v246, s[16:17]
	v_cndmask_b32_e64 v165, v165, v247, s[16:17]
	global_store_dwordx4 v[164:165], v[174:177], off offset:256

; DI u32x4 pack8(f32x4 a, f32x4 b) { u32x4 w; w.x = pk2(a[0], a[1]); w.y = pk2(a[2], a[3]); w.z = pk2(b[0], b[1]); w.w = pk2(b[2], b[3]); return w; }
;     DI void operator()(Acc& acc, const Unit& u, int wr, int wc, int fr, int fq) const {
;     ...
;                     const u32x4 w8 = pack8(v0, v1);
;                     if (mode == 0) *(u32x4*)(prow + bj * 128) = w8; else asm volatile("" :: "v"(w8));
.LBB0_201:
	v_cvt_pk_bf16_f32 v170, v170, v171
	v_cvt_pk_bf16_f32 v171, v172, v173
	v_cvt_pk_bf16_f32 v172, v174, v175
	v_cvt_pk_bf16_f32 v173, v176, v177
	s_mov_b64 s[40:41], 0
	s_mov_b32 s100, 0x32000
	s_mov_b32 s101, 0
	v_lshl_add_u64 v[246:247], v[244:245], 0, s[100:101]
	v_cndmask_b32_e64 v168, v168, v246, s[16:17]
	v_cndmask_b32_e64 v169, v169, v247, s[16:17]
	global_store_dwordx4 v[168:169], v[170:173], off

; DI u32x4 pack8(f32x4 a, f32x4 b) { u32x4 w; w.x = pk2(a[0], a[1]); w.y = pk2(a[2], a[3]); w.z = pk2(b[0], b[1]); w.w = pk2(b[2], b[3]); return w; }
;     DI void operator()(Acc& acc, const Unit& u, int wr, int wc, int fr, int fq) const {
;     ...
;                     const u32x4 w8 = pack8(v0, v1);
;                     if (mode == 0) *(u32x4*)(prow + bj * 128) = w8; else asm volatile("" :: "v"(w8));
.LBB0_235:
	v_cvt_pk_bf16_f32 v176, v176, v177
	v_cvt_pk_bf16_f32 v177, v178, v179
	v_cvt_pk_bf16_f32 v178, v180, v181
	v_cvt_pk_bf16_f32 v179, v184, v185
	s_mov_b32 s100, 0x4af00
	s_mov_b32 s101, 0
	v_lshl_add_u64 v[246:247], v[244:245], 0, s[100:101]
	v_cndmask_b32_e64 v168, v168, v246, s[16:17]
	v_cndmask_b32_e64 v169, v169, v247, s[16:17]
	global_store_dwordx4 v[168:169], v[176:179], off offset:256
	s_branch .LBB0_242

; DI u32x4 pack8(f32x4 a, f32x4 b) { u32x4 w; w.x = pk2(a[0], a[1]); w.y = pk2(a[2], a[3]); w.z = pk2(b[0], b[1]); w.w = pk2(b[2], b[3]); return w; }
;     DI void operator()(Acc& acc, const Unit& u, int wr, int wc, int fr, int fq) const {
;     ...
;                     const u32x4 w8 = pack8(v0, v1);
;                     if (mode == 0) *(u32x4*)(prow + bj * 128) = w8; else asm volatile("" :: "v"(w8));
.LBB0_267:
	v_cvt_pk_bf16_f32 v170, v170, v171
	v_cvt_pk_bf16_f32 v171, v172, v173
	v_cvt_pk_bf16_f32 v172, v174, v175
	v_cvt_pk_bf16_f32 v173, v176, v177
	s_mov_b64 s[40:41], 0
	s_mov_b32 s100, 0x64000
	s_mov_b32 s101, 0
	v_lshl_add_u64 v[246:247], v[244:245], 0, s[100:101]
	v_cndmask_b32_e64 v168, v168, v246, s[16:17]
	v_cndmask_b32_e64 v169, v169, v247, s[16:17]
	global_store_dwordx4 v[168:169], v[170:173], off

; DI u32x4 pack8(f32x4 a, f32x4 b) { u32x4 w; w.x = pk2(a[0], a[1]); w.y = pk2(a[2], a[3]); w.z = pk2(b[0], b[1]); w.w = pk2(b[2], b[3]); return w; }
;     DI void operator()(Acc& acc, const Unit& u, int wr, int wc, int fr, int fq) const {
;     ...
;                     const u32x4 w8 = pack8(v0, v1);
;                     if (mode == 0) *(u32x4*)(prow + bj * 128) = w8; else asm volatile("" :: "v"(w8));
.LBB0_301:
	v_cvt_pk_bf16_f32 v176, v176, v177
	v_cvt_pk_bf16_f32 v177, v178, v179
	v_cvt_pk_bf16_f32 v178, v180, v181
	v_cvt_pk_bf16_f32 v179, v184, v185
	s_mov_b32 s100, 0x7cf00
	s_mov_b32 s101, 0
	v_lshl_add_u64 v[246:247], v[244:245], 0, s[100:101]
	v_cndmask_b32_e64 v168, v168, v246, s[16:17]
	v_cndmask_b32_e64 v169, v169, v247, s[16:17]
	global_store_dwordx4 v[168:169], v[176:179], off offset:256
	s_branch .LBB0_308

; DI u32x4 pack8(f32x4 a, f32x4 b) { u32x4 w; w.x = pk2(a[0], a[1]); w.y = pk2(a[2], a[3]); w.z = pk2(b[0], b[1]); w.w = pk2(b[2], b[3]); return w; }
;     DI void operator()(Acc& acc, const Unit& u, int wr, int wc, int fr, int fq) const {
;     ...
;                     const u32x4 w8 = pack8(v0, v1);
;                     if (mode == 0) *(u32x4*)(prow + bj * 128) = w8; else asm volatile("" :: "v"(w8));
.LBB0_333:
	v_cvt_pk_bf16_f32 v170, v170, v171
	v_cvt_pk_bf16_f32 v171, v172, v173
	v_cvt_pk_bf16_f32 v172, v174, v175
	v_cvt_pk_bf16_f32 v173, v176, v177
	s_mov_b64 s[40:41], 0
	s_mov_b32 s100, 0x96000
	s_mov_b32 s101, 0
	v_lshl_add_u64 v[246:247], v[244:245], 0, s[100:101]
	v_cndmask_b32_e64 v168, v168, v246, s[16:17]
	v_cndmask_b32_e64 v169, v169, v247, s[16:17]
	global_store_dwordx4 v[168:169], v[170:173], off

; DI u32x4 pack8(f32x4 a, f32x4 b) { u32x4 w; w.x = pk2(a[0], a[1]); w.y = pk2(a[2], a[3]); w.z = pk2(b[0], b[1]); w.w = pk2(b[2], b[3]); return w; }
;     DI void operator()(Acc& acc, const Unit& u, int wr, int wc, int fr, int fq) const {
;     ...
;                     const u32x4 w8 = pack8(v0, v1);
;                     if (mode == 0) *(u32x4*)(prow + bj * 128) = w8; else asm volatile("" :: "v"(w8));
.LBB0_367:
	v_cvt_pk_bf16_f32 v176, v176, v177
	v_cvt_pk_bf16_f32 v177, v178, v179
	v_cvt_pk_bf16_f32 v178, v180, v181
	v_cvt_pk_bf16_f32 v179, v184, v185
	s_mov_b32 s100, 0xaef00
	s_mov_b32 s101, 0
	v_lshl_add_u64 v[246:247], v[244:245], 0, s[100:101]
	v_cndmask_b32_e64 v168, v168, v246, s[16:17]
	v_cndmask_b32_e64 v169, v169, v247, s[16:17]
	global_store_dwordx4 v[168:169], v[176:179], off offset:256
	s_branch .LBB0_374

; DI u32x4 pack8(f32x4 a, f32x4 b) { u32x4 w; w.x = pk2(a[0], a[1]); w.y = pk2(a[2], a[3]); w.z = pk2(b[0], b[1]); w.w = pk2(b[2], b[3]); return w; }
;     DI void operator()(Acc& acc, const Unit& u, int wr, int wc, int fr, int fq) const {
;     ...
;                     const u32x4 w8 = pack8(v0, v1);
;                     if (mode == 0) *(u32x4*)(prow + bj * 128) = w8; else asm volatile("" :: "v"(w8));
.LBB0_399:
	v_cvt_pk_bf16_f32 v170, v170, v171
	v_cvt_pk_bf16_f32 v171, v172, v173
	v_cvt_pk_bf16_f32 v172, v174, v175
	v_cvt_pk_bf16_f32 v173, v176, v177
	s_mov_b64 s[40:41], 0
	s_mov_b32 s100, 0x190000
	s_mov_b32 s101, 0
	v_lshl_add_u64 v[246:247], v[244:245], 0, s[100:101]
	v_cndmask_b32_e64 v168, v168, v246, s[16:17]
	v_cndmask_b32_e64 v169, v169, v247, s[16:17]
	global_store_dwordx4 v[168:169], v[170:173], off

; DI u32x4 pack8(f32x4 a, f32x4 b) { u32x4 w; w.x = pk2(a[0], a[1]); w.y = pk2(a[2], a[3]); w.z = pk2(b[0], b[1]); w.w = pk2(b[2], b[3]); return w; }
;     DI void operator()(Acc& acc, const Unit& u, int wr, int wc, int fr, int fq) const {
;     ...
;                     const u32x4 w8 = pack8(v0, v1);
;                     if (mode == 0) *(u32x4*)(prow + bj * 128) = w8; else asm volatile("" :: "v"(w8));
.LBB0_433:
	v_cvt_pk_bf16_f32 v176, v176, v177
	v_cvt_pk_bf16_f32 v177, v178, v179
	v_cvt_pk_bf16_f32 v178, v180, v181
	v_cvt_pk_bf16_f32 v179, v184, v185
	s_mov_b32 s100, 0x1a8f00
	s_mov_b32 s101, 0
	v_lshl_add_u64 v[246:247], v[244:245], 0, s[100:101]
	v_cndmask_b32_e64 v168, v168, v246, s[16:17]
	v_cndmask_b32_e64 v169, v169, v247, s[16:17]
	global_store_dwordx4 v[168:169], v[176:179], off offset:256
	s_branch .LBB0_440

; DI u32x4 pack8(f32x4 a, f32x4 b) { u32x4 w; w.x = pk2(a[0], a[1]); w.y = pk2(a[2], a[3]); w.z = pk2(b[0], b[1]); w.w = pk2(b[2], b[3]); return w; }
;     DI void operator()(Acc& acc, const Unit& u, int wr, int wc, int fr, int fq) const {
;     ...
;                     const u32x4 w8 = pack8(v0, v1);
;                     if (mode == 0) *(u32x4*)(prow + bj * 128) = w8; else asm volatile("" :: "v"(w8));
.LBB0_465:
	v_cvt_pk_bf16_f32 v170, v170, v171
	v_cvt_pk_bf16_f32 v171, v172, v173
	v_cvt_pk_bf16_f32 v172, v174, v175
	v_cvt_pk_bf16_f32 v173, v176, v177
	s_mov_b64 s[40:41], 0
	s_mov_b32 s100, 0x1c2000
	s_mov_b32 s101, 0
	v_lshl_add_u64 v[246:247], v[244:245], 0, s[100:101]
	v_cndmask_b32_e64 v168, v168, v246, s[16:17]
	v_cndmask_b32_e64 v169, v169, v247, s[16:17]
	global_store_dwordx4 v[168:169], v[170:173], off

; DI u32x4 pack8(f32x4 a, f32x4 b) { u32x4 w; w.x = pk2(a[0], a[1]); w.y = pk2(a[2], a[3]); w.z = pk2(b[0], b[1]); w.w = pk2(b[2], b[3]); return w; }
;     DI void operator()(Acc& acc, const Unit& u, int wr, int wc, int fr, int fq) const {
;     ...
;                     const u32x4 w8 = pack8(v0, v1);
;                     if (mode == 0) *(u32x4*)(prow + bj * 128) = w8; else asm volatile("" :: "v"(w8));
.LBB0_499:
	v_cvt_pk_bf16_f32 v176, v176, v177
	v_cvt_pk_bf16_f32 v177, v178, v179
	v_cvt_pk_bf16_f32 v178, v180, v181
	v_cvt_pk_bf16_f32 v179, v184, v185
	s_mov_b32 s100, 0x1daf00
	s_mov_b32 s101, 0
	v_lshl_add_u64 v[246:247], v[244:245], 0, s[100:101]
	v_cndmask_b32_e64 v168, v168, v246, s[16:17]
	v_cndmask_b32_e64 v169, v169, v247, s[16:17]
	global_store_dwordx4 v[168:169], v[176:179], off offset:256
	s_branch .LBB0_506

; DI u32x4 pack8(f32x4 a, f32x4 b) { u32x4 w; w.x = pk2(a[0], a[1]); w.y = pk2(a[2], a[3]); w.z = pk2(b[0], b[1]); w.w = pk2(b[2], b[3]); return w; }
;     DI void operator()(Acc& acc, const Unit& u, int wr, int wc, int fr, int fq) const {
;     ...
;                     const u32x4 w8 = pack8(v0, v1);
;                     if (mode == 0) *(u32x4*)(prow + bj * 128) = w8; else asm volatile("" :: "v"(w8));
.LBB0_531:
	v_cvt_pk_bf16_f32 v170, v170, v171
	v_cvt_pk_bf16_f32 v171, v172, v173
	v_cvt_pk_bf16_f32 v172, v174, v175
	v_cvt_pk_bf16_f32 v173, v176, v177
	s_mov_b64 s[40:41], 0
	s_mov_b32 s100, 0x1f4000
	s_mov_b32 s101, 0
	v_lshl_add_u64 v[246:247], v[244:245], 0, s[100:101]
	v_cndmask_b32_e64 v168, v168, v246, s[16:17]
	v_cndmask_b32_e64 v169, v169, v247, s[16:17]
	global_store_dwordx4 v[168:169], v[170:173], off

; DI u32x4 pack8(f32x4 a, f32x4 b) { u32x4 w; w.x = pk2(a[0], a[1]); w.y = pk2(a[2], a[3]); w.z = pk2(b[0], b[1]); w.w = pk2(b[2], b[3]); return w; }
;     DI void operator()(Acc& acc, const Unit& u, int wr, int wc, int fr, int fq) const {
;     ...
;                     const u32x4 w8 = pack8(v0, v1);
;                     if (mode == 0) *(u32x4*)(prow + bj * 128) = w8; else asm volatile("" :: "v"(w8));
.LBB0_565:
	v_cvt_pk_bf16_f32 v176, v176, v177
	v_cvt_pk_bf16_f32 v177, v178, v179
	v_cvt_pk_bf16_f32 v178, v180, v181
	v_cvt_pk_bf16_f32 v179, v184, v185
	s_mov_b32 s100, 0x20cf00
	s_mov_b32 s101, 0
	v_lshl_add_u64 v[246:247], v[244:245], 0, s[100:101]
	v_cndmask_b32_e64 v168, v168, v246, s[16:17]
	v_cndmask_b32_e64 v169, v169, v247, s[16:17]
	global_store_dwordx4 v[168:169], v[176:179], off offset:256
	s_branch .LBB0_572

; DI u32x4 pack8(f32x4 a, f32x4 b) { u32x4 w; w.x = pk2(a[0], a[1]); w.y = pk2(a[2], a[3]); w.z = pk2(b[0], b[1]); w.w = pk2(b[2], b[3]); return w; }
;     DI void operator()(Acc& acc, const Unit& u, int wr, int wc, int fr, int fq) const {
;     ...
;                     const u32x4 w8 = pack8(v0, v1);
;                     if (mode == 0) *(u32x4*)(prow + bj * 128) = w8; else asm volatile("" :: "v"(w8));
.LBB0_597:
	s_waitcnt vmcnt(0)
	v_cvt_pk_bf16_f32 v138, v170, v171
	v_cvt_pk_bf16_f32 v139, v172, v173
	v_cvt_pk_bf16_f32 v140, v174, v175
	v_cvt_pk_bf16_f32 v141, v176, v177
	s_mov_b64 s[40:41], 0
	s_mov_b32 s100, 0x226000
	s_mov_b32 s101, 0
	v_lshl_add_u64 v[246:247], v[244:245], 0, s[100:101]
	v_cndmask_b32_e64 v168, v168, v246, s[16:17]
	v_cndmask_b32_e64 v169, v169, v247, s[16:17]
	global_store_dwordx4 v[168:169], v[138:141], off

; DI u32x4 pack8(f32x4 a, f32x4 b) { u32x4 w; w.x = pk2(a[0], a[1]); w.y = pk2(a[2], a[3]); w.z = pk2(b[0], b[1]); w.w = pk2(b[2], b[3]); return w; }
;     DI void operator()(Acc& acc, const Unit& u, int wr, int wc, int fr, int fq) const {
;     ...
;                     const u32x4 w8 = pack8(v0, v1);
;                     if (mode == 0) *(u32x4*)(prow + bj * 128) = w8; else asm volatile("" :: "v"(w8));
.LBB0_631:
	v_cvt_pk_bf16_f32 v130, v144, v145
	v_cvt_pk_bf16_f32 v131, v166, v167
	v_cvt_pk_bf16_f32 v132, v170, v171
	v_cvt_pk_bf16_f32 v133, v172, v173
	s_mov_b32 s100, 0x23ef00
	s_mov_b32 s101, 0
	v_lshl_add_u64 v[246:247], v[244:245], 0, s[100:101]
	v_cndmask_b32_e64 v168, v168, v246, s[16:17]
	v_cndmask_b32_e64 v169, v169, v247, s[16:17]
	global_store_dwordx4 v[168:169], v[130:133], off offset:256
	s_branch .LBB0_638

; DI float bflo(unsigned w) { return __uint_as_float(w << 16); }
; DI float bfhi(unsigned w) { return __uint_as_float(w & 0xffff0000u); }
;     DI void operator()(Acc& acc, const Unit& u, int wr, int wc, int fr, int fq) const {
;     ...
;         bf16_t* base = proj + (size_t)(u.pm * 256 + wr * 64 + fr) * NPJ + C_GL + u.pn * 256 + wc * 32 + fq * 8;
;         {
;             u32x4 g[2][4][2];
; #pragma unroll
;             for (int ai = 0; ai < 2; ++ai)
; #pragma unroll
;                 for (int m = 0; m < 4; ++m)
; #pragma unroll
;                     for (int bj = 0; bj < 2; ++bj) g[ai][m][bj] = *(const u32x4*)(base + (size_t)(ai * 128 + m * 16) * NPJ + u.k * 1024 + bj * 128);
; #pragma unroll
;             for (int ai = 0; ai < 2; ++ai)
; #pragma unroll
;                 for (int m = 0; m < 4; ++m)
; #pragma unroll
;                     for (int bj = 0; bj < 2; ++bj) { const u32x4 q = g[ai][m][bj]; f32x4& v0 = acc[ai][bj][m][0]; f32x4& v1 = acc[ai][bj][m][1];
;                         v0[0] *= bflo(q.x); v0[1] *= bfhi(q.x); v0[2] *= bflo(q.y); v0[3] *= bfhi(q.y); v1[0] *= bflo(q.z); v1[1] *= bfhi(q.z); v1[2] *= bflo(q.w); v1[3] *= bfhi(q.w); }
.LBB0_948:
	v_mov_b32_e32 v130, v1
	v_mov_b32_e32 v132, v172
	s_lshl_b32 s8, s30, 1
	v_add_u32_e32 v133, s39, v130
	v_mov_b64_e32 v[130:131], s[48:49]
	v_mad_i64_i32 v[130:131], s[24:25], v133, s41, v[130:131]
	v_lshl_add_u64 v[130:131], v[130:131], 0, s[8:9]
	s_mov_b32 s17, s9
	v_lshlrev_b32_e32 v132, 3, v132
	v_lshl_add_u64 v[130:131], v[130:131], 0, s[16:17]
	v_ashrrev_i32_e32 v133, 31, v132
	v_lshl_add_u64 v[130:131], v[132:133], 1, v[130:131]
	v_lshl_add_u64 v[166:167], v[130:131], 0, s[18:19]
	s_lshl_b32 s8, s84, 10
	v_lshl_add_u64 v[130:131], s[8:9], 1, v[166:167]
	s_nop 0
	v_readfirstlane_b32 s98, v130
	v_readfirstlane_b32 s99, v131
	v_bfe_u32 v146, v183, 5, 3
	v_mul_u32_u24_e32 v146, 0x3200, v146
	v_and_b32_e32 v147, 31, v183
	v_lshl_add_u32 v146, v147, 4, v146
	v_bfe_u32 v147, v183, 6, 2
	v_lshlrev_b32_e32 v147, 6, v147
	v_sub_u32_e32 v243, v146, v147
	v_mov_b32_e32 v240, 0xbfb8aa3b
	s_cmp_eq_u32 s84, 2
	s_cbranch_scc1 .Lup3_final
	s_add_u32 s100, s98, 0x0
	s_addc_u32 s101, s99, 0
	global_load_dwordx4 v[184:187], v243, s[100:101]
	s_add_u32 s100, s98, 0x19000
	s_addc_u32 s101, s99, 0
	global_load_dwordx4 v[188:191], v243, s[100:101]
	s_add_u32 s100, s98, 0x0
	s_addc_u32 s101, s99, 0
	global_load_dwordx4 v[192:195], v243, s[100:101] offset:2048
	s_add_u32 s100, s98, 0x19000
	s_addc_u32 s101, s99, 0
	global_load_dwordx4 v[196:199], v243, s[100:101] offset:2048
	s_add_u32 s100, s98, 0x32000
	s_addc_u32 s101, s99, 0
	global_load_dwordx4 v[200:203], v243, s[100:101]
	s_add_u32 s100, s98, 0x4b000
	s_addc_u32 s101, s99, 0
	global_load_dwordx4 v[204:207], v243, s[100:101]
	s_add_u32 s100, s98, 0x32000
	s_addc_u32 s101, s99, 0
	global_load_dwordx4 v[208:211], v243, s[100:101] offset:2048
	s_add_u32 s100, s98, 0x4b000
	s_addc_u32 s101, s99, 0
	global_load_dwordx4 v[212:215], v243, s[100:101] offset:2048
	s_add_u32 s100, s98, 0x64000
	s_addc_u32 s101, s99, 0
	global_load_dwordx4 v[216:219], v243, s[100:101]
	s_add_u32 s100, s98, 0x7d000
	s_addc_u32 s101, s99, 0
	global_load_dwordx4 v[220:223], v243, s[100:101]
	s_add_u32 s100, s98, 0x64000
	s_addc_u32 s101, s99, 0
	global_load_dwordx4 v[224:227], v243, s[100:101] offset:2048
	s_add_u32 s100, s98, 0x7d000
	s_addc_u32 s101, s99, 0
	global_load_dwordx4 v[228:231], v243, s[100:101] offset:2048
	s_waitcnt vmcnt(8)
	v_lshlrev_b32_e32 v146, 16, v184
	v_and_b32_e32 v147, 0xffff0000, v184
	v_lshlrev_b32_e32 v148, 16, v192
	v_and_b32_e32 v149, 0xffff0000, v192
	v_lshlrev_b32_e32 v150, 16, v185
	v_and_b32_e32 v151, 0xffff0000, v185
	v_lshlrev_b32_e32 v152, 16, v193
	v_and_b32_e32 v153, 0xffff0000, v193
	v_pk_mul_f32 v[146:147], v[146:147], v[240:241] op_sel_hi:[1,0]
	v_pk_mul_f32 v[148:149], v[148:149], v[240:241] op_sel_hi:[1,0]
	v_pk_mul_f32 v[150:151], v[150:151], v[240:241] op_sel_hi:[1,0]
	v_pk_mul_f32 v[152:153], v[152:153], v[240:241] op_sel_hi:[1,0]
	v_min_f32_e32 v146, 0x42b80000, v146
	v_min_f32_e32 v147, 0x42b80000, v147
	v_min_f32_e32 v148, 0x42b80000, v148
	v_min_f32_e32 v149, 0x42b80000, v149
	v_min_f32_e32 v150, 0x42b80000, v150
	v_min_f32_e32 v151, 0x42b80000, v151
	v_min_f32_e32 v152, 0x42b80000, v152
	v_min_f32_e32 v153, 0x42b80000, v153
	v_exp_f32_e32 v146, v146
	v_exp_f32_e32 v147, v147
	v_exp_f32_e32 v148, v148
	v_exp_f32_e32 v149, v149
	v_exp_f32_e32 v150, v150
	v_exp_f32_e32 v151, v151
	v_exp_f32_e32 v152, v152
	v_exp_f32_e32 v153, v153
	s_nop 0
	v_add_f32_e32 v146, 1.0, v146
	v_add_f32_e32 v147, 1.0, v147
	v_add_f32_e32 v148, 1.0, v148
	v_add_f32_e32 v149, 1.0, v149
	v_add_f32_e32 v150, 1.0, v150
	v_add_f32_e32 v151, 1.0, v151
	v_add_f32_e32 v152, 1.0, v152
	v_add_f32_e32 v153, 1.0, v153
	v_rcp_f32_e32 v146, v146
	v_rcp_f32_e32 v147, v147
	v_rcp_f32_e32 v150, v150
	v_rcp_f32_e32 v151, v151
	s_nop 0
	v_pk_mul_f32 v[146:147], v[146:147], v[148:149]
	v_pk_mul_f32 v[150:151], v[150:151], v[152:153]
	v_pk_mul_f32 v[126:127], v[126:127], v[146:147]
	v_pk_mul_f32 v[128:129], v[128:129], v[150:151]
	v_lshlrev_b32_e32 v168, 16, v186
	v_and_b32_e32 v169, 0xffff0000, v186
	v_lshlrev_b32_e32 v178, 16, v194
	v_and_b32_e32 v179, 0xffff0000, v194
	v_lshlrev_b32_e32 v180, 16, v187
	v_and_b32_e32 v181, 0xffff0000, v187
	v_lshlrev_b32_e32 v244, 16, v195
	v_and_b32_e32 v245, 0xffff0000, v195
	v_pk_mul_f32 v[168:169], v[168:169], v[240:241] op_sel_hi:[1,0]
	v_pk_mul_f32 v[178:179], v[178:179], v[240:241] op_sel_hi:[1,0]
	v_pk_mul_f32 v[180:181], v[180:181], v[240:241] op_sel_hi:[1,0]
	v_pk_mul_f32 v[244:245], v[244:245], v[240:241] op_sel_hi:[1,0]
	v_min_f32_e32 v168, 0x42b80000, v168
	v_min_f32_e32 v169, 0x42b80000, v169
	v_min_f32_e32 v178, 0x42b80000, v178
	v_min_f32_e32 v179, 0x42b80000, v179
	v_min_f32_e32 v180, 0x42b80000, v180
	v_min_f32_e32 v181, 0x42b80000, v181
	v_min_f32_e32 v244, 0x42b80000, v244
	v_min_f32_e32 v245, 0x42b80000, v245
	v_exp_f32_e32 v168, v168
	v_exp_f32_e32 v169, v169
	v_exp_f32_e32 v178, v178
	v_exp_f32_e32 v179, v179
	v_exp_f32_e32 v180, v180
	v_exp_f32_e32 v181, v181
	v_exp_f32_e32 v244, v244
	v_exp_f32_e32 v245, v245
	s_nop 0
	v_add_f32_e32 v168, 1.0, v168
	v_add_f32_e32 v169, 1.0, v169
	v_add_f32_e32 v178, 1.0, v178
	v_add_f32_e32 v179, 1.0, v179
	v_add_f32_e32 v180, 1.0, v180
	v_add_f32_e32 v181, 1.0, v181
	v_add_f32_e32 v244, 1.0, v244
	v_add_f32_e32 v245, 1.0, v245
	v_rcp_f32_e32 v168, v168
	v_rcp_f32_e32 v169, v169
	v_rcp_f32_e32 v180, v180
	v_rcp_f32_e32 v181, v181
	s_nop 0
	v_pk_mul_f32 v[168:169], v[168:169], v[178:179]
	v_pk_mul_f32 v[180:181], v[180:181], v[244:245]
	v_pk_mul_f32 v[122:123], v[122:123], v[168:169]
	v_pk_mul_f32 v[124:125], v[124:125], v[180:181]
	v_lshlrev_b32_e32 v168, 16, v188
	v_and_b32_e32 v169, 0xffff0000, v188
; DI float bflo(unsigned w) { return __uint_as_float(w << 16); }
; DI float bfhi(unsigned w) { return __uint_as_float(w & 0xffff0000u); }
;     DI void operator()(Acc& acc, const Unit& u, int wr, int wc, int fr, int fq) const {
;     ...
;             for (int ai = 0; ai < 2; ++ai)
; #pragma unroll
;                 for (int m = 0; m < 4; ++m)
; #pragma unroll
;                     for (int bj = 0; bj < 2; ++bj) g[ai][m][bj] = *(const u32x4*)(base + (size_t)(ai * 128 + m * 16) * NPJ + u.k * 1024 + bj * 128);
; #pragma unroll
;             for (int ai = 0; ai < 2; ++ai)
; #pragma unroll
;                 for (int m = 0; m < 4; ++m)
; #pragma unroll
;                     for (int bj = 0; bj < 2; ++bj) { const u32x4 q = g[ai][m][bj]; f32x4& v0 = acc[ai][bj][m][0]; f32x4& v1 = acc[ai][bj][m][1];
;                         v0[0] *= bflo(q.x); v0[1] *= bfhi(q.x); v0[2] *= bflo(q.y); v0[3] *= bfhi(q.y); v1[0] *= bflo(q.z); v1[1] *= bfhi(q.z); v1[2] *= bflo(q.w); v1[3] *= bfhi(q.w); }
	v_lshlrev_b32_e32 v178, 16, v196
	v_and_b32_e32 v179, 0xffff0000, v196
	v_lshlrev_b32_e32 v180, 16, v189
	v_and_b32_e32 v181, 0xffff0000, v189
	v_lshlrev_b32_e32 v244, 16, v197
	v_and_b32_e32 v245, 0xffff0000, v197
	v_pk_mul_f32 v[168:169], v[168:169], v[240:241] op_sel_hi:[1,0]
	v_pk_mul_f32 v[178:179], v[178:179], v[240:241] op_sel_hi:[1,0]
	v_pk_mul_f32 v[180:181], v[180:181], v[240:241] op_sel_hi:[1,0]
	v_pk_mul_f32 v[244:245], v[244:245], v[240:241] op_sel_hi:[1,0]
	v_min_f32_e32 v168, 0x42b80000, v168
	v_min_f32_e32 v169, 0x42b80000, v169
	v_min_f32_e32 v178, 0x42b80000, v178
	v_min_f32_e32 v179, 0x42b80000, v179
	v_min_f32_e32 v180, 0x42b80000, v180
	v_min_f32_e32 v181, 0x42b80000, v181
	v_min_f32_e32 v244, 0x42b80000, v244
	v_min_f32_e32 v245, 0x42b80000, v245
	v_exp_f32_e32 v168, v168
	v_exp_f32_e32 v169, v169
	v_exp_f32_e32 v178, v178
	v_exp_f32_e32 v179, v179
	v_exp_f32_e32 v180, v180
	v_exp_f32_e32 v181, v181
	v_exp_f32_e32 v244, v244
	v_exp_f32_e32 v245, v245
	s_nop 0
	v_add_f32_e32 v168, 1.0, v168
	v_add_f32_e32 v169, 1.0, v169
	v_add_f32_e32 v178, 1.0, v178
	v_add_f32_e32 v179, 1.0, v179
	v_add_f32_e32 v180, 1.0, v180
	v_add_f32_e32 v181, 1.0, v181
	v_add_f32_e32 v244, 1.0, v244
	v_add_f32_e32 v245, 1.0, v245
	v_rcp_f32_e32 v168, v168
	v_rcp_f32_e32 v169, v169
	v_rcp_f32_e32 v180, v180
	v_rcp_f32_e32 v181, v181
	s_nop 0
	v_pk_mul_f32 v[168:169], v[168:169], v[178:179]
	v_pk_mul_f32 v[180:181], v[180:181], v[244:245]
	v_pk_mul_f32 v[114:115], v[114:115], v[168:169]
	v_pk_mul_f32 v[116:117], v[116:117], v[180:181]
	v_lshlrev_b32_e32 v146, 16, v190
	v_and_b32_e32 v147, 0xffff0000, v190
	v_lshlrev_b32_e32 v148, 16, v198
	v_and_b32_e32 v149, 0xffff0000, v198
	v_lshlrev_b32_e32 v150, 16, v191
	v_and_b32_e32 v151, 0xffff0000, v191
	v_lshlrev_b32_e32 v152, 16, v199
	v_and_b32_e32 v153, 0xffff0000, v199
	v_pk_mul_f32 v[146:147], v[146:147], v[240:241] op_sel_hi:[1,0]
	v_pk_mul_f32 v[148:149], v[148:149], v[240:241] op_sel_hi:[1,0]
	v_pk_mul_f32 v[150:151], v[150:151], v[240:241] op_sel_hi:[1,0]
	v_pk_mul_f32 v[152:153], v[152:153], v[240:241] op_sel_hi:[1,0]
	v_min_f32_e32 v146, 0x42b80000, v146
	v_min_f32_e32 v147, 0x42b80000, v147
	v_min_f32_e32 v148, 0x42b80000, v148
	v_min_f32_e32 v149, 0x42b80000, v149
	v_min_f32_e32 v150, 0x42b80000, v150
	v_min_f32_e32 v151, 0x42b80000, v151
	v_min_f32_e32 v152, 0x42b80000, v152
	v_min_f32_e32 v153, 0x42b80000, v153
	v_exp_f32_e32 v146, v146
	v_exp_f32_e32 v147, v147
	v_exp_f32_e32 v148, v148
	v_exp_f32_e32 v149, v149
	v_exp_f32_e32 v150, v150
	v_exp_f32_e32 v151, v151
	v_exp_f32_e32 v152, v152
	v_exp_f32_e32 v153, v153
	s_nop 0
	v_add_f32_e32 v146, 1.0, v146
	v_add_f32_e32 v147, 1.0, v147
	v_add_f32_e32 v148, 1.0, v148
	v_add_f32_e32 v149, 1.0, v149
	v_add_f32_e32 v150, 1.0, v150
	v_add_f32_e32 v151, 1.0, v151
	v_add_f32_e32 v152, 1.0, v152
	v_add_f32_e32 v153, 1.0, v153
	v_rcp_f32_e32 v146, v146
	v_rcp_f32_e32 v147, v147
	v_rcp_f32_e32 v150, v150
	v_rcp_f32_e32 v151, v151
	s_nop 0
	v_pk_mul_f32 v[146:147], v[146:147], v[148:149]
	v_pk_mul_f32 v[150:151], v[150:151], v[152:153]
	v_pk_mul_f32 v[110:111], v[110:111], v[146:147]
	v_pk_mul_f32 v[112:113], v[112:113], v[150:151]
	s_add_u32 s100, s98, 0x96000
	s_addc_u32 s101, s99, 0
	global_load_dwordx4 v[184:187], v243, s[100:101]
	s_add_u32 s100, s98, 0xaf000
	s_addc_u32 s101, s99, 0
	global_load_dwordx4 v[188:191], v243, s[100:101]
	s_add_u32 s100, s98, 0x96000
	s_addc_u32 s101, s99, 0
	global_load_dwordx4 v[192:195], v243, s[100:101] offset:2048
	s_add_u32 s100, s98, 0xaf000
	s_addc_u32 s101, s99, 0
	global_load_dwordx4 v[196:199], v243, s[100:101] offset:2048
	s_waitcnt vmcnt(8)
	v_lshlrev_b32_e32 v146, 16, v200
	v_and_b32_e32 v147, 0xffff0000, v200
	v_lshlrev_b32_e32 v148, 16, v208
	v_and_b32_e32 v149, 0xffff0000, v208
	v_lshlrev_b32_e32 v150, 16, v201
	v_and_b32_e32 v151, 0xffff0000, v201
	v_lshlrev_b32_e32 v152, 16, v209
	v_and_b32_e32 v153, 0xffff0000, v209
	v_pk_mul_f32 v[146:147], v[146:147], v[240:241] op_sel_hi:[1,0]
	v_pk_mul_f32 v[148:149], v[148:149], v[240:241] op_sel_hi:[1,0]
	v_pk_mul_f32 v[150:151], v[150:151], v[240:241] op_sel_hi:[1,0]
	v_pk_mul_f32 v[152:153], v[152:153], v[240:241] op_sel_hi:[1,0]
	v_min_f32_e32 v146, 0x42b80000, v146
	v_min_f32_e32 v147, 0x42b80000, v147
	v_min_f32_e32 v148, 0x42b80000, v148
	v_min_f32_e32 v149, 0x42b80000, v149
	v_min_f32_e32 v150, 0x42b80000, v150
	v_min_f32_e32 v151, 0x42b80000, v151
	v_min_f32_e32 v152, 0x42b80000, v152
	v_min_f32_e32 v153, 0x42b80000, v153
	v_exp_f32_e32 v146, v146
	v_exp_f32_e32 v147, v147
	v_exp_f32_e32 v148, v148
	v_exp_f32_e32 v149, v149
	v_exp_f32_e32 v150, v150
	v_exp_f32_e32 v151, v151
	v_exp_f32_e32 v152, v152
	v_exp_f32_e32 v153, v153
	s_nop 0
	v_add_f32_e32 v146, 1.0, v146
	v_add_f32_e32 v147, 1.0, v147
	v_add_f32_e32 v148, 1.0, v148
	v_add_f32_e32 v149, 1.0, v149
	v_add_f32_e32 v150, 1.0, v150
	v_add_f32_e32 v151, 1.0, v151
	v_add_f32_e32 v152, 1.0, v152
	v_add_f32_e32 v153, 1.0, v153
	v_rcp_f32_e32 v146, v146
	v_rcp_f32_e32 v147, v147
	v_rcp_f32_e32 v150, v150
	v_rcp_f32_e32 v151, v151
	s_nop 0
	v_pk_mul_f32 v[146:147], v[146:147], v[148:149]
	v_pk_mul_f32 v[150:151], v[150:151], v[152:153]
	v_pk_mul_f32 v[118:119], v[118:119], v[146:147]
	v_pk_mul_f32 v[120:121], v[120:121], v[150:151]
	v_lshlrev_b32_e32 v168, 16, v202
	v_and_b32_e32 v169, 0xffff0000, v202
	v_lshlrev_b32_e32 v178, 16, v210
	v_and_b32_e32 v179, 0xffff0000, v210
	v_lshlrev_b32_e32 v180, 16, v203
	v_and_b32_e32 v181, 0xffff0000, v203
	v_lshlrev_b32_e32 v244, 16, v211
	v_and_b32_e32 v245, 0xffff0000, v211
	v_pk_mul_f32 v[168:169], v[168:169], v[240:241] op_sel_hi:[1,0]
; DI float bflo(unsigned w) { return __uint_as_float(w << 16); }
; DI float bfhi(unsigned w) { return __uint_as_float(w & 0xffff0000u); }
;     DI void operator()(Acc& acc, const Unit& u, int wr, int wc, int fr, int fq) const {
;     ...
;             for (int ai = 0; ai < 2; ++ai)
; #pragma unroll
;                 for (int m = 0; m < 4; ++m)
; #pragma unroll
;                     for (int bj = 0; bj < 2; ++bj) g[ai][m][bj] = *(const u32x4*)(base + (size_t)(ai * 128 + m * 16) * NPJ + u.k * 1024 + bj * 128);
; #pragma unroll
;             for (int ai = 0; ai < 2; ++ai)
; #pragma unroll
;                 for (int m = 0; m < 4; ++m)
; #pragma unroll
;                     for (int bj = 0; bj < 2; ++bj) { const u32x4 q = g[ai][m][bj]; f32x4& v0 = acc[ai][bj][m][0]; f32x4& v1 = acc[ai][bj][m][1];
;                         v0[0] *= bflo(q.x); v0[1] *= bfhi(q.x); v0[2] *= bflo(q.y); v0[3] *= bfhi(q.y); v1[0] *= bflo(q.z); v1[1] *= bfhi(q.z); v1[2] *= bflo(q.w); v1[3] *= bfhi(q.w); }
	v_pk_mul_f32 v[178:179], v[178:179], v[240:241] op_sel_hi:[1,0]
	v_pk_mul_f32 v[180:181], v[180:181], v[240:241] op_sel_hi:[1,0]
	v_pk_mul_f32 v[244:245], v[244:245], v[240:241] op_sel_hi:[1,0]
	v_min_f32_e32 v168, 0x42b80000, v168
	v_min_f32_e32 v169, 0x42b80000, v169
	v_min_f32_e32 v178, 0x42b80000, v178
	v_min_f32_e32 v179, 0x42b80000, v179
	v_min_f32_e32 v180, 0x42b80000, v180
	v_min_f32_e32 v181, 0x42b80000, v181
	v_min_f32_e32 v244, 0x42b80000, v244
	v_min_f32_e32 v245, 0x42b80000, v245
	v_exp_f32_e32 v168, v168
	v_exp_f32_e32 v169, v169
	v_exp_f32_e32 v178, v178
	v_exp_f32_e32 v179, v179
	v_exp_f32_e32 v180, v180
	v_exp_f32_e32 v181, v181
	v_exp_f32_e32 v244, v244
	v_exp_f32_e32 v245, v245
	s_nop 0
	v_add_f32_e32 v168, 1.0, v168
	v_add_f32_e32 v169, 1.0, v169
	v_add_f32_e32 v178, 1.0, v178
	v_add_f32_e32 v179, 1.0, v179
	v_add_f32_e32 v180, 1.0, v180
	v_add_f32_e32 v181, 1.0, v181
	v_add_f32_e32 v244, 1.0, v244
	v_add_f32_e32 v245, 1.0, v245
	v_rcp_f32_e32 v168, v168
	v_rcp_f32_e32 v169, v169
	v_rcp_f32_e32 v180, v180
	v_rcp_f32_e32 v181, v181
	s_nop 0
	v_pk_mul_f32 v[168:169], v[168:169], v[178:179]
	v_pk_mul_f32 v[180:181], v[180:181], v[244:245]
	v_pk_mul_f32 v[106:107], v[106:107], v[168:169]
	v_pk_mul_f32 v[108:109], v[108:109], v[180:181]
	v_lshlrev_b32_e32 v168, 16, v204
	v_and_b32_e32 v169, 0xffff0000, v204
	v_lshlrev_b32_e32 v178, 16, v212
	v_and_b32_e32 v179, 0xffff0000, v212
	v_lshlrev_b32_e32 v180, 16, v205
	v_and_b32_e32 v181, 0xffff0000, v205
	v_lshlrev_b32_e32 v244, 16, v213
	v_and_b32_e32 v245, 0xffff0000, v213
	v_pk_mul_f32 v[168:169], v[168:169], v[240:241] op_sel_hi:[1,0]
	v_pk_mul_f32 v[178:179], v[178:179], v[240:241] op_sel_hi:[1,0]
	v_pk_mul_f32 v[180:181], v[180:181], v[240:241] op_sel_hi:[1,0]
	v_pk_mul_f32 v[244:245], v[244:245], v[240:241] op_sel_hi:[1,0]
	v_min_f32_e32 v168, 0x42b80000, v168
	v_min_f32_e32 v169, 0x42b80000, v169
	v_min_f32_e32 v178, 0x42b80000, v178
	v_min_f32_e32 v179, 0x42b80000, v179
	v_min_f32_e32 v180, 0x42b80000, v180
	v_min_f32_e32 v181, 0x42b80000, v181
	v_min_f32_e32 v244, 0x42b80000, v244
	v_min_f32_e32 v245, 0x42b80000, v245
	v_exp_f32_e32 v168, v168
	v_exp_f32_e32 v169, v169
	v_exp_f32_e32 v178, v178
	v_exp_f32_e32 v179, v179
	v_exp_f32_e32 v180, v180
	v_exp_f32_e32 v181, v181
	v_exp_f32_e32 v244, v244
	v_exp_f32_e32 v245, v245
	s_nop 0
	v_add_f32_e32 v168, 1.0, v168
	v_add_f32_e32 v169, 1.0, v169
	v_add_f32_e32 v178, 1.0, v178
	v_add_f32_e32 v179, 1.0, v179
	v_add_f32_e32 v180, 1.0, v180
	v_add_f32_e32 v181, 1.0, v181
	v_add_f32_e32 v244, 1.0, v244
	v_add_f32_e32 v245, 1.0, v245
	v_rcp_f32_e32 v168, v168
	v_rcp_f32_e32 v169, v169
	v_rcp_f32_e32 v180, v180
	v_rcp_f32_e32 v181, v181
	s_nop 0
	v_pk_mul_f32 v[168:169], v[168:169], v[178:179]
	v_pk_mul_f32 v[180:181], v[180:181], v[244:245]
	v_pk_mul_f32 v[98:99], v[98:99], v[168:169]
	v_pk_mul_f32 v[100:101], v[100:101], v[180:181]
	v_lshlrev_b32_e32 v146, 16, v206
	v_and_b32_e32 v147, 0xffff0000, v206
	v_lshlrev_b32_e32 v148, 16, v214
	v_and_b32_e32 v149, 0xffff0000, v214
	v_lshlrev_b32_e32 v150, 16, v207
	v_and_b32_e32 v151, 0xffff0000, v207
	v_lshlrev_b32_e32 v152, 16, v215
	v_and_b32_e32 v153, 0xffff0000, v215
	v_pk_mul_f32 v[146:147], v[146:147], v[240:241] op_sel_hi:[1,0]
	v_pk_mul_f32 v[148:149], v[148:149], v[240:241] op_sel_hi:[1,0]
	v_pk_mul_f32 v[150:151], v[150:151], v[240:241] op_sel_hi:[1,0]
	v_pk_mul_f32 v[152:153], v[152:153], v[240:241] op_sel_hi:[1,0]
	v_min_f32_e32 v146, 0x42b80000, v146
	v_min_f32_e32 v147, 0x42b80000, v147
	v_min_f32_e32 v148, 0x42b80000, v148
	v_min_f32_e32 v149, 0x42b80000, v149
	v_min_f32_e32 v150, 0x42b80000, v150
	v_min_f32_e32 v151, 0x42b80000, v151
	v_min_f32_e32 v152, 0x42b80000, v152
	v_min_f32_e32 v153, 0x42b80000, v153
	v_exp_f32_e32 v146, v146
	v_exp_f32_e32 v147, v147
	v_exp_f32_e32 v148, v148
	v_exp_f32_e32 v149, v149
	v_exp_f32_e32 v150, v150
	v_exp_f32_e32 v151, v151
	v_exp_f32_e32 v152, v152
	v_exp_f32_e32 v153, v153
	s_nop 0
	v_add_f32_e32 v146, 1.0, v146
	v_add_f32_e32 v147, 1.0, v147
	v_add_f32_e32 v148, 1.0, v148
	v_add_f32_e32 v149, 1.0, v149
	v_add_f32_e32 v150, 1.0, v150
	v_add_f32_e32 v151, 1.0, v151
	v_add_f32_e32 v152, 1.0, v152
	v_add_f32_e32 v153, 1.0, v153
	v_rcp_f32_e32 v146, v146
	v_rcp_f32_e32 v147, v147
	v_rcp_f32_e32 v150, v150
	v_rcp_f32_e32 v151, v151
	s_nop 0
	v_pk_mul_f32 v[146:147], v[146:147], v[148:149]
	v_pk_mul_f32 v[150:151], v[150:151], v[152:153]
	v_pk_mul_f32 v[90:91], v[90:91], v[146:147]
	v_pk_mul_f32 v[92:93], v[92:93], v[150:151]
	s_add_u32 s100, s98, 0x190000
	s_addc_u32 s101, s99, 0
	global_load_dwordx4 v[200:203], v243, s[100:101]
	s_add_u32 s100, s98, 0x1a9000
	s_addc_u32 s101, s99, 0
	global_load_dwordx4 v[204:207], v243, s[100:101]
	s_add_u32 s100, s98, 0x190000
	s_addc_u32 s101, s99, 0
	global_load_dwordx4 v[208:211], v243, s[100:101] offset:2048
	s_add_u32 s100, s98, 0x1a9000
	s_addc_u32 s101, s99, 0
	global_load_dwordx4 v[212:215], v243, s[100:101] offset:2048
	s_waitcnt vmcnt(8)
; DI float bflo(unsigned w) { return __uint_as_float(w << 16); }
; DI float bfhi(unsigned w) { return __uint_as_float(w & 0xffff0000u); }
;     DI void operator()(Acc& acc, const Unit& u, int wr, int wc, int fr, int fq) const {
;     ...
;             for (int ai = 0; ai < 2; ++ai)
; #pragma unroll
;                 for (int m = 0; m < 4; ++m)
; #pragma unroll
;                     for (int bj = 0; bj < 2; ++bj) g[ai][m][bj] = *(const u32x4*)(base + (size_t)(ai * 128 + m * 16) * NPJ + u.k * 1024 + bj * 128);
; #pragma unroll
;             for (int ai = 0; ai < 2; ++ai)
; #pragma unroll
;                 for (int m = 0; m < 4; ++m)
; #pragma unroll
;                     for (int bj = 0; bj < 2; ++bj) { const u32x4 q = g[ai][m][bj]; f32x4& v0 = acc[ai][bj][m][0]; f32x4& v1 = acc[ai][bj][m][1];
;                         v0[0] *= bflo(q.x); v0[1] *= bfhi(q.x); v0[2] *= bflo(q.y); v0[3] *= bfhi(q.y); v1[0] *= bflo(q.z); v1[1] *= bfhi(q.z); v1[2] *= bflo(q.w); v1[3] *= bfhi(q.w); }
	v_lshlrev_b32_e32 v146, 16, v216
	v_and_b32_e32 v147, 0xffff0000, v216
	v_lshlrev_b32_e32 v148, 16, v224
	v_and_b32_e32 v149, 0xffff0000, v224
	v_lshlrev_b32_e32 v150, 16, v217
	v_and_b32_e32 v151, 0xffff0000, v217
	v_lshlrev_b32_e32 v152, 16, v225
	v_and_b32_e32 v153, 0xffff0000, v225
	v_pk_mul_f32 v[146:147], v[146:147], v[240:241] op_sel_hi:[1,0]
	v_pk_mul_f32 v[148:149], v[148:149], v[240:241] op_sel_hi:[1,0]
	v_pk_mul_f32 v[150:151], v[150:151], v[240:241] op_sel_hi:[1,0]
	v_pk_mul_f32 v[152:153], v[152:153], v[240:241] op_sel_hi:[1,0]
	v_min_f32_e32 v146, 0x42b80000, v146
	v_min_f32_e32 v147, 0x42b80000, v147
	v_min_f32_e32 v148, 0x42b80000, v148
	v_min_f32_e32 v149, 0x42b80000, v149
	v_min_f32_e32 v150, 0x42b80000, v150
	v_min_f32_e32 v151, 0x42b80000, v151
	v_min_f32_e32 v152, 0x42b80000, v152
	v_min_f32_e32 v153, 0x42b80000, v153
	v_exp_f32_e32 v146, v146
	v_exp_f32_e32 v147, v147
	v_exp_f32_e32 v148, v148
	v_exp_f32_e32 v149, v149
	v_exp_f32_e32 v150, v150
	v_exp_f32_e32 v151, v151
	v_exp_f32_e32 v152, v152
	v_exp_f32_e32 v153, v153
	s_nop 0
	v_add_f32_e32 v146, 1.0, v146
	v_add_f32_e32 v147, 1.0, v147
	v_add_f32_e32 v148, 1.0, v148
	v_add_f32_e32 v149, 1.0, v149
	v_add_f32_e32 v150, 1.0, v150
	v_add_f32_e32 v151, 1.0, v151
	v_add_f32_e32 v152, 1.0, v152
	v_add_f32_e32 v153, 1.0, v153
	v_rcp_f32_e32 v146, v146
	v_rcp_f32_e32 v147, v147
	v_rcp_f32_e32 v150, v150
	v_rcp_f32_e32 v151, v151
	s_nop 0
	v_pk_mul_f32 v[146:147], v[146:147], v[148:149]
	v_pk_mul_f32 v[150:151], v[150:151], v[152:153]
	v_pk_mul_f32 v[102:103], v[102:103], v[146:147]
	v_pk_mul_f32 v[104:105], v[104:105], v[150:151]
	v_lshlrev_b32_e32 v168, 16, v218
	v_and_b32_e32 v169, 0xffff0000, v218
	v_lshlrev_b32_e32 v178, 16, v226
	v_and_b32_e32 v179, 0xffff0000, v226
	v_lshlrev_b32_e32 v180, 16, v219
	v_and_b32_e32 v181, 0xffff0000, v219
	v_lshlrev_b32_e32 v244, 16, v227
	v_and_b32_e32 v245, 0xffff0000, v227
	v_pk_mul_f32 v[168:169], v[168:169], v[240:241] op_sel_hi:[1,0]
	v_pk_mul_f32 v[178:179], v[178:179], v[240:241] op_sel_hi:[1,0]
	v_pk_mul_f32 v[180:181], v[180:181], v[240:241] op_sel_hi:[1,0]
	v_pk_mul_f32 v[244:245], v[244:245], v[240:241] op_sel_hi:[1,0]
	v_min_f32_e32 v168, 0x42b80000, v168
	v_min_f32_e32 v169, 0x42b80000, v169
	v_min_f32_e32 v178, 0x42b80000, v178
	v_min_f32_e32 v179, 0x42b80000, v179
	v_min_f32_e32 v180, 0x42b80000, v180
	v_min_f32_e32 v181, 0x42b80000, v181
	v_min_f32_e32 v244, 0x42b80000, v244
	v_min_f32_e32 v245, 0x42b80000, v245
	v_exp_f32_e32 v168, v168
	v_exp_f32_e32 v169, v169
	v_exp_f32_e32 v178, v178
	v_exp_f32_e32 v179, v179
	v_exp_f32_e32 v180, v180
	v_exp_f32_e32 v181, v181
	v_exp_f32_e32 v244, v244
	v_exp_f32_e32 v245, v245
	s_nop 0
	v_add_f32_e32 v168, 1.0, v168
	v_add_f32_e32 v169, 1.0, v169
	v_add_f32_e32 v178, 1.0, v178
	v_add_f32_e32 v179, 1.0, v179
	v_add_f32_e32 v180, 1.0, v180
	v_add_f32_e32 v181, 1.0, v181
	v_add_f32_e32 v244, 1.0, v244
	v_add_f32_e32 v245, 1.0, v245
	v_rcp_f32_e32 v168, v168
	v_rcp_f32_e32 v169, v169
	v_rcp_f32_e32 v180, v180
	v_rcp_f32_e32 v181, v181
	s_nop 0
	v_pk_mul_f32 v[168:169], v[168:169], v[178:179]
	v_pk_mul_f32 v[180:181], v[180:181], v[244:245]
	v_pk_mul_f32 v[94:95], v[94:95], v[168:169]
	v_pk_mul_f32 v[96:97], v[96:97], v[180:181]
	v_lshlrev_b32_e32 v168, 16, v220
	v_and_b32_e32 v169, 0xffff0000, v220
	v_lshlrev_b32_e32 v178, 16, v228
	v_and_b32_e32 v179, 0xffff0000, v228
	v_lshlrev_b32_e32 v180, 16, v221
	v_and_b32_e32 v181, 0xffff0000, v221
	v_lshlrev_b32_e32 v244, 16, v229
	v_and_b32_e32 v245, 0xffff0000, v229
	v_pk_mul_f32 v[168:169], v[168:169], v[240:241] op_sel_hi:[1,0]
	v_pk_mul_f32 v[178:179], v[178:179], v[240:241] op_sel_hi:[1,0]
	v_pk_mul_f32 v[180:181], v[180:181], v[240:241] op_sel_hi:[1,0]
	v_pk_mul_f32 v[244:245], v[244:245], v[240:241] op_sel_hi:[1,0]
	v_min_f32_e32 v168, 0x42b80000, v168
	v_min_f32_e32 v169, 0x42b80000, v169
	v_min_f32_e32 v178, 0x42b80000, v178
	v_min_f32_e32 v179, 0x42b80000, v179
	v_min_f32_e32 v180, 0x42b80000, v180
	v_min_f32_e32 v181, 0x42b80000, v181
	v_min_f32_e32 v244, 0x42b80000, v244
	v_min_f32_e32 v245, 0x42b80000, v245
	v_exp_f32_e32 v168, v168
	v_exp_f32_e32 v169, v169
	v_exp_f32_e32 v178, v178
	v_exp_f32_e32 v179, v179
	v_exp_f32_e32 v180, v180
	v_exp_f32_e32 v181, v181
	v_exp_f32_e32 v244, v244
	v_exp_f32_e32 v245, v245
	s_nop 0
	v_add_f32_e32 v168, 1.0, v168
	v_add_f32_e32 v169, 1.0, v169
	v_add_f32_e32 v178, 1.0, v178
	v_add_f32_e32 v179, 1.0, v179
	v_add_f32_e32 v180, 1.0, v180
	v_add_f32_e32 v181, 1.0, v181
	v_add_f32_e32 v244, 1.0, v244
	v_add_f32_e32 v245, 1.0, v245
	v_rcp_f32_e32 v168, v168
	v_rcp_f32_e32 v169, v169
	v_rcp_f32_e32 v180, v180
	v_rcp_f32_e32 v181, v181
	s_nop 0
	v_pk_mul_f32 v[168:169], v[168:169], v[178:179]
	v_pk_mul_f32 v[180:181], v[180:181], v[244:245]
	v_pk_mul_f32 v[82:83], v[82:83], v[168:169]
	v_pk_mul_f32 v[84:85], v[84:85], v[180:181]
	v_lshlrev_b32_e32 v146, 16, v222
	v_and_b32_e32 v147, 0xffff0000, v222
	v_lshlrev_b32_e32 v148, 16, v230
	v_and_b32_e32 v149, 0xffff0000, v230
	v_lshlrev_b32_e32 v150, 16, v223
	v_and_b32_e32 v151, 0xffff0000, v223
	v_lshlrev_b32_e32 v152, 16, v231
	v_and_b32_e32 v153, 0xffff0000, v231
	v_pk_mul_f32 v[146:147], v[146:147], v[240:241] op_sel_hi:[1,0]
	v_pk_mul_f32 v[148:149], v[148:149], v[240:241] op_sel_hi:[1,0]
	v_pk_mul_f32 v[150:151], v[150:151], v[240:241] op_sel_hi:[1,0]
	v_pk_mul_f32 v[152:153], v[152:153], v[240:241] op_sel_hi:[1,0]
	v_min_f32_e32 v146, 0x42b80000, v146
	v_min_f32_e32 v147, 0x42b80000, v147
	v_min_f32_e32 v148, 0x42b80000, v148
	v_min_f32_e32 v149, 0x42b80000, v149
	v_min_f32_e32 v150, 0x42b80000, v150
	v_min_f32_e32 v151, 0x42b80000, v151
	v_min_f32_e32 v152, 0x42b80000, v152
	v_min_f32_e32 v153, 0x42b80000, v153
	v_exp_f32_e32 v146, v146
	v_exp_f32_e32 v147, v147
	v_exp_f32_e32 v148, v148
	v_exp_f32_e32 v149, v149
	v_exp_f32_e32 v150, v150
	v_exp_f32_e32 v151, v151
	v_exp_f32_e32 v152, v152
	v_exp_f32_e32 v153, v153
	s_nop 0
	v_add_f32_e32 v146, 1.0, v146
	v_add_f32_e32 v147, 1.0, v147
	v_add_f32_e32 v148, 1.0, v148
	v_add_f32_e32 v149, 1.0, v149
	v_add_f32_e32 v150, 1.0, v150
	v_add_f32_e32 v151, 1.0, v151
	v_add_f32_e32 v152, 1.0, v152
	v_add_f32_e32 v153, 1.0, v153
	v_rcp_f32_e32 v146, v146
	v_rcp_f32_e32 v147, v147
	v_rcp_f32_e32 v150, v150
	v_rcp_f32_e32 v151, v151
	s_nop 0
	v_pk_mul_f32 v[146:147], v[146:147], v[148:149]
	v_pk_mul_f32 v[150:151], v[150:151], v[152:153]
	v_pk_mul_f32 v[74:75], v[74:75], v[146:147]
	v_pk_mul_f32 v[76:77], v[76:77], v[150:151]
	s_add_u32 s100, s98, 0x1c2000
	s_addc_u32 s101, s99, 0
	global_load_dwordx4 v[216:219], v243, s[100:101]
	s_add_u32 s100, s98, 0x1db000
	s_addc_u32 s101, s99, 0
	global_load_dwordx4 v[220:223], v243, s[100:101]
	s_add_u32 s100, s98, 0x1c2000
	s_addc_u32 s101, s99, 0
	global_load_dwordx4 v[224:227], v243, s[100:101] offset:2048
	s_add_u32 s100, s98, 0x1db000
	s_addc_u32 s101, s99, 0
	global_load_dwordx4 v[228:231], v243, s[100:101] offset:2048
	s_waitcnt vmcnt(8)
; DI float bflo(unsigned w) { return __uint_as_float(w << 16); }
; DI float bfhi(unsigned w) { return __uint_as_float(w & 0xffff0000u); }
;     DI void operator()(Acc& acc, const Unit& u, int wr, int wc, int fr, int fq) const {
;     ...
;             for (int ai = 0; ai < 2; ++ai)
; #pragma unroll
;                 for (int m = 0; m < 4; ++m)
; #pragma unroll
;                     for (int bj = 0; bj < 2; ++bj) g[ai][m][bj] = *(const u32x4*)(base + (size_t)(ai * 128 + m * 16) * NPJ + u.k * 1024 + bj * 128);
; #pragma unroll
;             for (int ai = 0; ai < 2; ++ai)
; #pragma unroll
;                 for (int m = 0; m < 4; ++m)
; #pragma unroll
;                     for (int bj = 0; bj < 2; ++bj) { const u32x4 q = g[ai][m][bj]; f32x4& v0 = acc[ai][bj][m][0]; f32x4& v1 = acc[ai][bj][m][1];
;                         v0[0] *= bflo(q.x); v0[1] *= bfhi(q.x); v0[2] *= bflo(q.y); v0[3] *= bfhi(q.y); v1[0] *= bflo(q.z); v1[1] *= bfhi(q.z); v1[2] *= bflo(q.w); v1[3] *= bfhi(q.w); }
	v_lshlrev_b32_e32 v146, 16, v184
	v_and_b32_e32 v147, 0xffff0000, v184
	v_lshlrev_b32_e32 v148, 16, v192
	v_and_b32_e32 v149, 0xffff0000, v192
	v_lshlrev_b32_e32 v150, 16, v185
	v_and_b32_e32 v151, 0xffff0000, v185
	v_lshlrev_b32_e32 v152, 16, v193
	v_and_b32_e32 v153, 0xffff0000, v193
	v_pk_mul_f32 v[146:147], v[146:147], v[240:241] op_sel_hi:[1,0]
	v_pk_mul_f32 v[148:149], v[148:149], v[240:241] op_sel_hi:[1,0]
	v_pk_mul_f32 v[150:151], v[150:151], v[240:241] op_sel_hi:[1,0]
	v_pk_mul_f32 v[152:153], v[152:153], v[240:241] op_sel_hi:[1,0]
	v_min_f32_e32 v146, 0x42b80000, v146
	v_min_f32_e32 v147, 0x42b80000, v147
	v_min_f32_e32 v148, 0x42b80000, v148
	v_min_f32_e32 v149, 0x42b80000, v149
	v_min_f32_e32 v150, 0x42b80000, v150
	v_min_f32_e32 v151, 0x42b80000, v151
	v_min_f32_e32 v152, 0x42b80000, v152
	v_min_f32_e32 v153, 0x42b80000, v153
	v_exp_f32_e32 v146, v146
	v_exp_f32_e32 v147, v147
	v_exp_f32_e32 v148, v148
	v_exp_f32_e32 v149, v149
	v_exp_f32_e32 v150, v150
	v_exp_f32_e32 v151, v151
	v_exp_f32_e32 v152, v152
	v_exp_f32_e32 v153, v153
	s_nop 0
	v_add_f32_e32 v146, 1.0, v146
	v_add_f32_e32 v147, 1.0, v147
	v_add_f32_e32 v148, 1.0, v148
	v_add_f32_e32 v149, 1.0, v149
	v_add_f32_e32 v150, 1.0, v150
	v_add_f32_e32 v151, 1.0, v151
	v_add_f32_e32 v152, 1.0, v152
	v_add_f32_e32 v153, 1.0, v153
	v_rcp_f32_e32 v146, v146
	v_rcp_f32_e32 v147, v147
	v_rcp_f32_e32 v150, v150
	v_rcp_f32_e32 v151, v151
	s_nop 0
	v_pk_mul_f32 v[146:147], v[146:147], v[148:149]
	v_pk_mul_f32 v[150:151], v[150:151], v[152:153]
	v_pk_mul_f32 v[86:87], v[86:87], v[146:147]
	v_pk_mul_f32 v[88:89], v[88:89], v[150:151]
	v_lshlrev_b32_e32 v168, 16, v186
	v_and_b32_e32 v169, 0xffff0000, v186
	v_lshlrev_b32_e32 v178, 16, v194
	v_and_b32_e32 v179, 0xffff0000, v194
	v_lshlrev_b32_e32 v180, 16, v187
	v_and_b32_e32 v181, 0xffff0000, v187
	v_lshlrev_b32_e32 v244, 16, v195
	v_and_b32_e32 v245, 0xffff0000, v195
	v_pk_mul_f32 v[168:169], v[168:169], v[240:241] op_sel_hi:[1,0]
	v_pk_mul_f32 v[178:179], v[178:179], v[240:241] op_sel_hi:[1,0]
	v_pk_mul_f32 v[180:181], v[180:181], v[240:241] op_sel_hi:[1,0]
	v_pk_mul_f32 v[244:245], v[244:245], v[240:241] op_sel_hi:[1,0]
	v_min_f32_e32 v168, 0x42b80000, v168
	v_min_f32_e32 v169, 0x42b80000, v169
	v_min_f32_e32 v178, 0x42b80000, v178
	v_min_f32_e32 v179, 0x42b80000, v179
	v_min_f32_e32 v180, 0x42b80000, v180
	v_min_f32_e32 v181, 0x42b80000, v181
	v_min_f32_e32 v244, 0x42b80000, v244
	v_min_f32_e32 v245, 0x42b80000, v245
	v_exp_f32_e32 v168, v168
	v_exp_f32_e32 v169, v169
	v_exp_f32_e32 v178, v178
	v_exp_f32_e32 v179, v179
	v_exp_f32_e32 v180, v180
	v_exp_f32_e32 v181, v181
	v_exp_f32_e32 v244, v244
	v_exp_f32_e32 v245, v245
	s_nop 0
	v_add_f32_e32 v168, 1.0, v168
	v_add_f32_e32 v169, 1.0, v169
	v_add_f32_e32 v178, 1.0, v178
	v_add_f32_e32 v179, 1.0, v179
	v_add_f32_e32 v180, 1.0, v180
	v_add_f32_e32 v181, 1.0, v181
	v_add_f32_e32 v244, 1.0, v244
	v_add_f32_e32 v245, 1.0, v245
	v_rcp_f32_e32 v168, v168
	v_rcp_f32_e32 v169, v169
	v_rcp_f32_e32 v180, v180
	v_rcp_f32_e32 v181, v181
	s_nop 0
	v_pk_mul_f32 v[168:169], v[168:169], v[178:179]
	v_pk_mul_f32 v[180:181], v[180:181], v[244:245]
	v_pk_mul_f32 v[78:79], v[78:79], v[168:169]
	v_pk_mul_f32 v[80:81], v[80:81], v[180:181]
	v_lshlrev_b32_e32 v168, 16, v188
	v_and_b32_e32 v169, 0xffff0000, v188
	v_lshlrev_b32_e32 v178, 16, v196
	v_and_b32_e32 v179, 0xffff0000, v196
	v_lshlrev_b32_e32 v180, 16, v189
	v_and_b32_e32 v181, 0xffff0000, v189
	v_lshlrev_b32_e32 v244, 16, v197
	v_and_b32_e32 v245, 0xffff0000, v197
	v_pk_mul_f32 v[168:169], v[168:169], v[240:241] op_sel_hi:[1,0]
	v_pk_mul_f32 v[178:179], v[178:179], v[240:241] op_sel_hi:[1,0]
	v_pk_mul_f32 v[180:181], v[180:181], v[240:241] op_sel_hi:[1,0]
	v_pk_mul_f32 v[244:245], v[244:245], v[240:241] op_sel_hi:[1,0]
	v_min_f32_e32 v168, 0x42b80000, v168
	v_min_f32_e32 v169, 0x42b80000, v169
	v_min_f32_e32 v178, 0x42b80000, v178
	v_min_f32_e32 v179, 0x42b80000, v179
	v_min_f32_e32 v180, 0x42b80000, v180
	v_min_f32_e32 v181, 0x42b80000, v181
	v_min_f32_e32 v244, 0x42b80000, v244
	v_min_f32_e32 v245, 0x42b80000, v245
	v_exp_f32_e32 v168, v168
	v_exp_f32_e32 v169, v169
	v_exp_f32_e32 v178, v178
	v_exp_f32_e32 v179, v179
	v_exp_f32_e32 v180, v180
	v_exp_f32_e32 v181, v181
	v_exp_f32_e32 v244, v244
	v_exp_f32_e32 v245, v245
	s_nop 0
	v_add_f32_e32 v168, 1.0, v168
	v_add_f32_e32 v169, 1.0, v169
	v_add_f32_e32 v178, 1.0, v178
	v_add_f32_e32 v179, 1.0, v179
	v_add_f32_e32 v180, 1.0, v180
	v_add_f32_e32 v181, 1.0, v181
	v_add_f32_e32 v244, 1.0, v244
	v_add_f32_e32 v245, 1.0, v245
	v_rcp_f32_e32 v168, v168
	v_rcp_f32_e32 v169, v169
	v_rcp_f32_e32 v180, v180
	v_rcp_f32_e32 v181, v181
	s_nop 0
	v_pk_mul_f32 v[168:169], v[168:169], v[178:179]
	v_pk_mul_f32 v[180:181], v[180:181], v[244:245]
	v_pk_mul_f32 v[70:71], v[70:71], v[168:169]
	v_pk_mul_f32 v[72:73], v[72:73], v[180:181]
	v_lshlrev_b32_e32 v146, 16, v190
	v_and_b32_e32 v147, 0xffff0000, v190
	v_lshlrev_b32_e32 v148, 16, v198
	v_and_b32_e32 v149, 0xffff0000, v198
	v_lshlrev_b32_e32 v150, 16, v191
	v_and_b32_e32 v151, 0xffff0000, v191
	v_lshlrev_b32_e32 v152, 16, v199
	v_and_b32_e32 v153, 0xffff0000, v199
	v_pk_mul_f32 v[146:147], v[146:147], v[240:241] op_sel_hi:[1,0]
	v_pk_mul_f32 v[148:149], v[148:149], v[240:241] op_sel_hi:[1,0]
	v_pk_mul_f32 v[150:151], v[150:151], v[240:241] op_sel_hi:[1,0]
	v_pk_mul_f32 v[152:153], v[152:153], v[240:241] op_sel_hi:[1,0]
	v_min_f32_e32 v146, 0x42b80000, v146
	v_min_f32_e32 v147, 0x42b80000, v147
	v_min_f32_e32 v148, 0x42b80000, v148
	v_min_f32_e32 v149, 0x42b80000, v149
	v_min_f32_e32 v150, 0x42b80000, v150
	v_min_f32_e32 v151, 0x42b80000, v151
	v_min_f32_e32 v152, 0x42b80000, v152
	v_min_f32_e32 v153, 0x42b80000, v153
	v_exp_f32_e32 v146, v146
	v_exp_f32_e32 v147, v147
	v_exp_f32_e32 v148, v148
	v_exp_f32_e32 v149, v149
	v_exp_f32_e32 v150, v150
	v_exp_f32_e32 v151, v151
	v_exp_f32_e32 v152, v152
	v_exp_f32_e32 v153, v153
	s_nop 0
	v_add_f32_e32 v146, 1.0, v146
	v_add_f32_e32 v147, 1.0, v147
	v_add_f32_e32 v148, 1.0, v148
	v_add_f32_e32 v149, 1.0, v149
	v_add_f32_e32 v150, 1.0, v150
	v_add_f32_e32 v151, 1.0, v151
	v_add_f32_e32 v152, 1.0, v152
	v_add_f32_e32 v153, 1.0, v153
	v_rcp_f32_e32 v146, v146
	v_rcp_f32_e32 v147, v147
	v_rcp_f32_e32 v150, v150
	v_rcp_f32_e32 v151, v151
	s_nop 0
	v_pk_mul_f32 v[146:147], v[146:147], v[148:149]
	v_pk_mul_f32 v[150:151], v[150:151], v[152:153]
	v_pk_mul_f32 v[66:67], v[66:67], v[146:147]
	v_pk_mul_f32 v[68:69], v[68:69], v[150:151]
	s_add_u32 s100, s98, 0x1f4000
	s_addc_u32 s101, s99, 0
	global_load_dwordx4 v[184:187], v243, s[100:101]
	s_add_u32 s100, s98, 0x20d000
	s_addc_u32 s101, s99, 0
	global_load_dwordx4 v[188:191], v243, s[100:101]
	s_add_u32 s100, s98, 0x1f4000
	s_addc_u32 s101, s99, 0
	global_load_dwordx4 v[192:195], v243, s[100:101] offset:2048
	s_add_u32 s100, s98, 0x20d000
	s_addc_u32 s101, s99, 0
	global_load_dwordx4 v[196:199], v243, s[100:101] offset:2048
	s_waitcnt vmcnt(8)
; DI float bflo(unsigned w) { return __uint_as_float(w << 16); }
; DI float bfhi(unsigned w) { return __uint_as_float(w & 0xffff0000u); }
;     DI void operator()(Acc& acc, const Unit& u, int wr, int wc, int fr, int fq) const {
;     ...
;             for (int ai = 0; ai < 2; ++ai)
; #pragma unroll
;                 for (int m = 0; m < 4; ++m)
; #pragma unroll
;                     for (int bj = 0; bj < 2; ++bj) g[ai][m][bj] = *(const u32x4*)(base + (size_t)(ai * 128 + m * 16) * NPJ + u.k * 1024 + bj * 128);
; #pragma unroll
;             for (int ai = 0; ai < 2; ++ai)
; #pragma unroll
;                 for (int m = 0; m < 4; ++m)
; #pragma unroll
;                     for (int bj = 0; bj < 2; ++bj) { const u32x4 q = g[ai][m][bj]; f32x4& v0 = acc[ai][bj][m][0]; f32x4& v1 = acc[ai][bj][m][1];
;                         v0[0] *= bflo(q.x); v0[1] *= bfhi(q.x); v0[2] *= bflo(q.y); v0[3] *= bfhi(q.y); v1[0] *= bflo(q.z); v1[1] *= bfhi(q.z); v1[2] *= bflo(q.w); v1[3] *= bfhi(q.w); }
	v_lshlrev_b32_e32 v146, 16, v200
	v_and_b32_e32 v147, 0xffff0000, v200
	v_lshlrev_b32_e32 v148, 16, v208
	v_and_b32_e32 v149, 0xffff0000, v208
	v_lshlrev_b32_e32 v150, 16, v201
	v_and_b32_e32 v151, 0xffff0000, v201
	v_lshlrev_b32_e32 v152, 16, v209
	v_and_b32_e32 v153, 0xffff0000, v209
	v_pk_mul_f32 v[146:147], v[146:147], v[240:241] op_sel_hi:[1,0]
	v_pk_mul_f32 v[148:149], v[148:149], v[240:241] op_sel_hi:[1,0]
	v_pk_mul_f32 v[150:151], v[150:151], v[240:241] op_sel_hi:[1,0]
	v_pk_mul_f32 v[152:153], v[152:153], v[240:241] op_sel_hi:[1,0]
	v_min_f32_e32 v146, 0x42b80000, v146
	v_min_f32_e32 v147, 0x42b80000, v147
	v_min_f32_e32 v148, 0x42b80000, v148
	v_min_f32_e32 v149, 0x42b80000, v149
	v_min_f32_e32 v150, 0x42b80000, v150
	v_min_f32_e32 v151, 0x42b80000, v151
	v_min_f32_e32 v152, 0x42b80000, v152
	v_min_f32_e32 v153, 0x42b80000, v153
	v_exp_f32_e32 v146, v146
	v_exp_f32_e32 v147, v147
	v_exp_f32_e32 v148, v148
	v_exp_f32_e32 v149, v149
	v_exp_f32_e32 v150, v150
	v_exp_f32_e32 v151, v151
	v_exp_f32_e32 v152, v152
	v_exp_f32_e32 v153, v153
	s_nop 0
	v_add_f32_e32 v146, 1.0, v146
	v_add_f32_e32 v147, 1.0, v147
	v_add_f32_e32 v148, 1.0, v148
	v_add_f32_e32 v149, 1.0, v149
	v_add_f32_e32 v150, 1.0, v150
	v_add_f32_e32 v151, 1.0, v151
	v_add_f32_e32 v152, 1.0, v152
	v_add_f32_e32 v153, 1.0, v153
	v_rcp_f32_e32 v146, v146
	v_rcp_f32_e32 v147, v147
	v_rcp_f32_e32 v150, v150
	v_rcp_f32_e32 v151, v151
	s_nop 0
	v_pk_mul_f32 v[146:147], v[146:147], v[148:149]
	v_pk_mul_f32 v[150:151], v[150:151], v[152:153]
	v_pk_mul_f32 v[62:63], v[62:63], v[146:147]
	v_pk_mul_f32 v[64:65], v[64:65], v[150:151]
	v_lshlrev_b32_e32 v168, 16, v202
	v_and_b32_e32 v169, 0xffff0000, v202
	v_lshlrev_b32_e32 v178, 16, v210
	v_and_b32_e32 v179, 0xffff0000, v210
	v_lshlrev_b32_e32 v180, 16, v203
	v_and_b32_e32 v181, 0xffff0000, v203
	v_lshlrev_b32_e32 v244, 16, v211
	v_and_b32_e32 v245, 0xffff0000, v211
	v_pk_mul_f32 v[168:169], v[168:169], v[240:241] op_sel_hi:[1,0]
	v_pk_mul_f32 v[178:179], v[178:179], v[240:241] op_sel_hi:[1,0]
	v_pk_mul_f32 v[180:181], v[180:181], v[240:241] op_sel_hi:[1,0]
	v_pk_mul_f32 v[244:245], v[244:245], v[240:241] op_sel_hi:[1,0]
	v_min_f32_e32 v168, 0x42b80000, v168
	v_min_f32_e32 v169, 0x42b80000, v169
	v_min_f32_e32 v178, 0x42b80000, v178
	v_min_f32_e32 v179, 0x42b80000, v179
	v_min_f32_e32 v180, 0x42b80000, v180
	v_min_f32_e32 v181, 0x42b80000, v181
	v_min_f32_e32 v244, 0x42b80000, v244
	v_min_f32_e32 v245, 0x42b80000, v245
	v_exp_f32_e32 v168, v168
	v_exp_f32_e32 v169, v169
	v_exp_f32_e32 v178, v178
	v_exp_f32_e32 v179, v179
	v_exp_f32_e32 v180, v180
	v_exp_f32_e32 v181, v181
	v_exp_f32_e32 v244, v244
	v_exp_f32_e32 v245, v245
	s_nop 0
	v_add_f32_e32 v168, 1.0, v168
	v_add_f32_e32 v169, 1.0, v169
	v_add_f32_e32 v178, 1.0, v178
	v_add_f32_e32 v179, 1.0, v179
	v_add_f32_e32 v180, 1.0, v180
	v_add_f32_e32 v181, 1.0, v181
	v_add_f32_e32 v244, 1.0, v244
	v_add_f32_e32 v245, 1.0, v245
	v_rcp_f32_e32 v168, v168
	v_rcp_f32_e32 v169, v169
	v_rcp_f32_e32 v180, v180
	v_rcp_f32_e32 v181, v181
	s_nop 0
	v_pk_mul_f32 v[168:169], v[168:169], v[178:179]
	v_pk_mul_f32 v[180:181], v[180:181], v[244:245]
	v_pk_mul_f32 v[58:59], v[58:59], v[168:169]
	v_pk_mul_f32 v[60:61], v[60:61], v[180:181]
	v_lshlrev_b32_e32 v168, 16, v204
	v_and_b32_e32 v169, 0xffff0000, v204
	v_lshlrev_b32_e32 v178, 16, v212
	v_and_b32_e32 v179, 0xffff0000, v212
	v_lshlrev_b32_e32 v180, 16, v205
	v_and_b32_e32 v181, 0xffff0000, v205
	v_lshlrev_b32_e32 v244, 16, v213
	v_and_b32_e32 v245, 0xffff0000, v213
	v_pk_mul_f32 v[168:169], v[168:169], v[240:241] op_sel_hi:[1,0]
	v_pk_mul_f32 v[178:179], v[178:179], v[240:241] op_sel_hi:[1,0]
	v_pk_mul_f32 v[180:181], v[180:181], v[240:241] op_sel_hi:[1,0]
	v_pk_mul_f32 v[244:245], v[244:245], v[240:241] op_sel_hi:[1,0]
	v_min_f32_e32 v168, 0x42b80000, v168
	v_min_f32_e32 v169, 0x42b80000, v169
	v_min_f32_e32 v178, 0x42b80000, v178
	v_min_f32_e32 v179, 0x42b80000, v179
	v_min_f32_e32 v180, 0x42b80000, v180
	v_min_f32_e32 v181, 0x42b80000, v181
	v_min_f32_e32 v244, 0x42b80000, v244
	v_min_f32_e32 v245, 0x42b80000, v245
	v_exp_f32_e32 v168, v168
	v_exp_f32_e32 v169, v169
	v_exp_f32_e32 v178, v178
	v_exp_f32_e32 v179, v179
	v_exp_f32_e32 v180, v180
	v_exp_f32_e32 v181, v181
	v_exp_f32_e32 v244, v244
	v_exp_f32_e32 v245, v245
	s_nop 0
	v_add_f32_e32 v168, 1.0, v168
	v_add_f32_e32 v169, 1.0, v169
	v_add_f32_e32 v178, 1.0, v178
	v_add_f32_e32 v179, 1.0, v179
	v_add_f32_e32 v180, 1.0, v180
	v_add_f32_e32 v181, 1.0, v181
	v_add_f32_e32 v244, 1.0, v244
	v_add_f32_e32 v245, 1.0, v245
	v_rcp_f32_e32 v168, v168
	v_rcp_f32_e32 v169, v169
	v_rcp_f32_e32 v180, v180
	v_rcp_f32_e32 v181, v181
	s_nop 0
	v_pk_mul_f32 v[168:169], v[168:169], v[178:179]
	v_pk_mul_f32 v[180:181], v[180:181], v[244:245]
	v_pk_mul_f32 v[50:51], v[50:51], v[168:169]
	v_pk_mul_f32 v[52:53], v[52:53], v[180:181]
	v_lshlrev_b32_e32 v146, 16, v206
	v_and_b32_e32 v147, 0xffff0000, v206
	v_lshlrev_b32_e32 v148, 16, v214
	v_and_b32_e32 v149, 0xffff0000, v214
	v_lshlrev_b32_e32 v150, 16, v207
	v_and_b32_e32 v151, 0xffff0000, v207
	v_lshlrev_b32_e32 v152, 16, v215
	v_and_b32_e32 v153, 0xffff0000, v215
	v_pk_mul_f32 v[146:147], v[146:147], v[240:241] op_sel_hi:[1,0]
	v_pk_mul_f32 v[148:149], v[148:149], v[240:241] op_sel_hi:[1,0]
	v_pk_mul_f32 v[150:151], v[150:151], v[240:241] op_sel_hi:[1,0]
	v_pk_mul_f32 v[152:153], v[152:153], v[240:241] op_sel_hi:[1,0]
	v_min_f32_e32 v146, 0x42b80000, v146
	v_min_f32_e32 v147, 0x42b80000, v147
	v_min_f32_e32 v148, 0x42b80000, v148
	v_min_f32_e32 v149, 0x42b80000, v149
	v_min_f32_e32 v150, 0x42b80000, v150
	v_min_f32_e32 v151, 0x42b80000, v151
	v_min_f32_e32 v152, 0x42b80000, v152
	v_min_f32_e32 v153, 0x42b80000, v153
	v_exp_f32_e32 v146, v146
	v_exp_f32_e32 v147, v147
	v_exp_f32_e32 v148, v148
	v_exp_f32_e32 v149, v149
	v_exp_f32_e32 v150, v150
	v_exp_f32_e32 v151, v151
	v_exp_f32_e32 v152, v152
	v_exp_f32_e32 v153, v153
	s_nop 0
	v_add_f32_e32 v146, 1.0, v146
	v_add_f32_e32 v147, 1.0, v147
	v_add_f32_e32 v148, 1.0, v148
	v_add_f32_e32 v149, 1.0, v149
	v_add_f32_e32 v150, 1.0, v150
	v_add_f32_e32 v151, 1.0, v151
	v_add_f32_e32 v152, 1.0, v152
	v_add_f32_e32 v153, 1.0, v153
	v_rcp_f32_e32 v146, v146
	v_rcp_f32_e32 v147, v147
	v_rcp_f32_e32 v150, v150
	v_rcp_f32_e32 v151, v151
	s_nop 0
	v_pk_mul_f32 v[146:147], v[146:147], v[148:149]
	v_pk_mul_f32 v[150:151], v[150:151], v[152:153]
	v_pk_mul_f32 v[42:43], v[42:43], v[146:147]
	v_pk_mul_f32 v[44:45], v[44:45], v[150:151]
	s_add_u32 s100, s98, 0x226000
	s_addc_u32 s101, s99, 0
	global_load_dwordx4 v[200:203], v243, s[100:101]
	s_add_u32 s100, s98, 0x23f000
	s_addc_u32 s101, s99, 0
	global_load_dwordx4 v[204:207], v243, s[100:101]
	s_add_u32 s100, s98, 0x226000
	s_addc_u32 s101, s99, 0
	global_load_dwordx4 v[208:211], v243, s[100:101] offset:2048
	s_add_u32 s100, s98, 0x23f000
	s_addc_u32 s101, s99, 0
	global_load_dwordx4 v[212:215], v243, s[100:101] offset:2048
	s_waitcnt vmcnt(8)
; DI float bflo(unsigned w) { return __uint_as_float(w << 16); }
; DI float bfhi(unsigned w) { return __uint_as_float(w & 0xffff0000u); }
;     DI void operator()(Acc& acc, const Unit& u, int wr, int wc, int fr, int fq) const {
;     ...
;             for (int ai = 0; ai < 2; ++ai)
; #pragma unroll
;                 for (int m = 0; m < 4; ++m)
; #pragma unroll
;                     for (int bj = 0; bj < 2; ++bj) g[ai][m][bj] = *(const u32x4*)(base + (size_t)(ai * 128 + m * 16) * NPJ + u.k * 1024 + bj * 128);
; #pragma unroll
;             for (int ai = 0; ai < 2; ++ai)
; #pragma unroll
;                 for (int m = 0; m < 4; ++m)
; #pragma unroll
;                     for (int bj = 0; bj < 2; ++bj) { const u32x4 q = g[ai][m][bj]; f32x4& v0 = acc[ai][bj][m][0]; f32x4& v1 = acc[ai][bj][m][1];
;                         v0[0] *= bflo(q.x); v0[1] *= bfhi(q.x); v0[2] *= bflo(q.y); v0[3] *= bfhi(q.y); v1[0] *= bflo(q.z); v1[1] *= bfhi(q.z); v1[2] *= bflo(q.w); v1[3] *= bfhi(q.w); }
	v_lshlrev_b32_e32 v146, 16, v216
	v_and_b32_e32 v147, 0xffff0000, v216
	v_lshlrev_b32_e32 v148, 16, v224
	v_and_b32_e32 v149, 0xffff0000, v224
	v_lshlrev_b32_e32 v150, 16, v217
	v_and_b32_e32 v151, 0xffff0000, v217
	v_lshlrev_b32_e32 v152, 16, v225
	v_and_b32_e32 v153, 0xffff0000, v225
	v_pk_mul_f32 v[146:147], v[146:147], v[240:241] op_sel_hi:[1,0]
	v_pk_mul_f32 v[148:149], v[148:149], v[240:241] op_sel_hi:[1,0]
	v_pk_mul_f32 v[150:151], v[150:151], v[240:241] op_sel_hi:[1,0]
	v_pk_mul_f32 v[152:153], v[152:153], v[240:241] op_sel_hi:[1,0]
	v_min_f32_e32 v146, 0x42b80000, v146
	v_min_f32_e32 v147, 0x42b80000, v147
	v_min_f32_e32 v148, 0x42b80000, v148
	v_min_f32_e32 v149, 0x42b80000, v149
	v_min_f32_e32 v150, 0x42b80000, v150
	v_min_f32_e32 v151, 0x42b80000, v151
	v_min_f32_e32 v152, 0x42b80000, v152
	v_min_f32_e32 v153, 0x42b80000, v153
	v_exp_f32_e32 v146, v146
	v_exp_f32_e32 v147, v147
	v_exp_f32_e32 v148, v148
	v_exp_f32_e32 v149, v149
	v_exp_f32_e32 v150, v150
	v_exp_f32_e32 v151, v151
	v_exp_f32_e32 v152, v152
	v_exp_f32_e32 v153, v153
	s_nop 0
	v_add_f32_e32 v146, 1.0, v146
	v_add_f32_e32 v147, 1.0, v147
	v_add_f32_e32 v148, 1.0, v148
	v_add_f32_e32 v149, 1.0, v149
	v_add_f32_e32 v150, 1.0, v150
	v_add_f32_e32 v151, 1.0, v151
	v_add_f32_e32 v152, 1.0, v152
	v_add_f32_e32 v153, 1.0, v153
	v_rcp_f32_e32 v146, v146
	v_rcp_f32_e32 v147, v147
	v_rcp_f32_e32 v150, v150
	v_rcp_f32_e32 v151, v151
	s_nop 0
	v_pk_mul_f32 v[146:147], v[146:147], v[148:149]
	v_pk_mul_f32 v[150:151], v[150:151], v[152:153]
	v_pk_mul_f32 v[54:55], v[54:55], v[146:147]
	v_pk_mul_f32 v[56:57], v[56:57], v[150:151]
	v_lshlrev_b32_e32 v168, 16, v218
	v_and_b32_e32 v169, 0xffff0000, v218
	v_lshlrev_b32_e32 v178, 16, v226
	v_and_b32_e32 v179, 0xffff0000, v226
	v_lshlrev_b32_e32 v180, 16, v219
	v_and_b32_e32 v181, 0xffff0000, v219
	v_lshlrev_b32_e32 v244, 16, v227
	v_and_b32_e32 v245, 0xffff0000, v227
	v_pk_mul_f32 v[168:169], v[168:169], v[240:241] op_sel_hi:[1,0]
	v_pk_mul_f32 v[178:179], v[178:179], v[240:241] op_sel_hi:[1,0]
	v_pk_mul_f32 v[180:181], v[180:181], v[240:241] op_sel_hi:[1,0]
	v_pk_mul_f32 v[244:245], v[244:245], v[240:241] op_sel_hi:[1,0]
	v_min_f32_e32 v168, 0x42b80000, v168
	v_min_f32_e32 v169, 0x42b80000, v169
	v_min_f32_e32 v178, 0x42b80000, v178
	v_min_f32_e32 v179, 0x42b80000, v179
	v_min_f32_e32 v180, 0x42b80000, v180
	v_min_f32_e32 v181, 0x42b80000, v181
	v_min_f32_e32 v244, 0x42b80000, v244
	v_min_f32_e32 v245, 0x42b80000, v245
	v_exp_f32_e32 v168, v168
	v_exp_f32_e32 v169, v169
	v_exp_f32_e32 v178, v178
	v_exp_f32_e32 v179, v179
	v_exp_f32_e32 v180, v180
	v_exp_f32_e32 v181, v181
	v_exp_f32_e32 v244, v244
	v_exp_f32_e32 v245, v245
	s_nop 0
	v_add_f32_e32 v168, 1.0, v168
	v_add_f32_e32 v169, 1.0, v169
	v_add_f32_e32 v178, 1.0, v178
	v_add_f32_e32 v179, 1.0, v179
	v_add_f32_e32 v180, 1.0, v180
	v_add_f32_e32 v181, 1.0, v181
	v_add_f32_e32 v244, 1.0, v244
	v_add_f32_e32 v245, 1.0, v245
	v_rcp_f32_e32 v168, v168
	v_rcp_f32_e32 v169, v169
	v_rcp_f32_e32 v180, v180
	v_rcp_f32_e32 v181, v181
	s_nop 0
	v_pk_mul_f32 v[168:169], v[168:169], v[178:179]
	v_pk_mul_f32 v[180:181], v[180:181], v[244:245]
	v_pk_mul_f32 v[46:47], v[46:47], v[168:169]
	v_pk_mul_f32 v[48:49], v[48:49], v[180:181]
	v_lshlrev_b32_e32 v168, 16, v220
	v_and_b32_e32 v169, 0xffff0000, v220
	v_lshlrev_b32_e32 v178, 16, v228
	v_and_b32_e32 v179, 0xffff0000, v228
	v_lshlrev_b32_e32 v180, 16, v221
	v_and_b32_e32 v181, 0xffff0000, v221
	v_lshlrev_b32_e32 v244, 16, v229
	v_and_b32_e32 v245, 0xffff0000, v229
	v_pk_mul_f32 v[168:169], v[168:169], v[240:241] op_sel_hi:[1,0]
	v_pk_mul_f32 v[178:179], v[178:179], v[240:241] op_sel_hi:[1,0]
	v_pk_mul_f32 v[180:181], v[180:181], v[240:241] op_sel_hi:[1,0]
	v_pk_mul_f32 v[244:245], v[244:245], v[240:241] op_sel_hi:[1,0]
	v_min_f32_e32 v168, 0x42b80000, v168
	v_min_f32_e32 v169, 0x42b80000, v169
	v_min_f32_e32 v178, 0x42b80000, v178
	v_min_f32_e32 v179, 0x42b80000, v179
	v_min_f32_e32 v180, 0x42b80000, v180
	v_min_f32_e32 v181, 0x42b80000, v181
	v_min_f32_e32 v244, 0x42b80000, v244
	v_min_f32_e32 v245, 0x42b80000, v245
	v_exp_f32_e32 v168, v168
	v_exp_f32_e32 v169, v169
	v_exp_f32_e32 v178, v178
	v_exp_f32_e32 v179, v179
	v_exp_f32_e32 v180, v180
	v_exp_f32_e32 v181, v181
	v_exp_f32_e32 v244, v244
	v_exp_f32_e32 v245, v245
	s_nop 0
	v_add_f32_e32 v168, 1.0, v168
	v_add_f32_e32 v169, 1.0, v169
	v_add_f32_e32 v178, 1.0, v178
	v_add_f32_e32 v179, 1.0, v179
	v_add_f32_e32 v180, 1.0, v180
	v_add_f32_e32 v181, 1.0, v181
	v_add_f32_e32 v244, 1.0, v244
	v_add_f32_e32 v245, 1.0, v245
	v_rcp_f32_e32 v168, v168
	v_rcp_f32_e32 v169, v169
	v_rcp_f32_e32 v180, v180
	v_rcp_f32_e32 v181, v181
	s_nop 0
	v_pk_mul_f32 v[168:169], v[168:169], v[178:179]
	v_pk_mul_f32 v[180:181], v[180:181], v[244:245]
	v_pk_mul_f32 v[34:35], v[34:35], v[168:169]
	v_pk_mul_f32 v[36:37], v[36:37], v[180:181]
	v_lshlrev_b32_e32 v146, 16, v222
	v_and_b32_e32 v147, 0xffff0000, v222
	v_lshlrev_b32_e32 v148, 16, v230
	v_and_b32_e32 v149, 0xffff0000, v230
	v_lshlrev_b32_e32 v150, 16, v223
	v_and_b32_e32 v151, 0xffff0000, v223
	v_lshlrev_b32_e32 v152, 16, v231
	v_and_b32_e32 v153, 0xffff0000, v231
	v_pk_mul_f32 v[146:147], v[146:147], v[240:241] op_sel_hi:[1,0]
	v_pk_mul_f32 v[148:149], v[148:149], v[240:241] op_sel_hi:[1,0]
	v_pk_mul_f32 v[150:151], v[150:151], v[240:241] op_sel_hi:[1,0]
	v_pk_mul_f32 v[152:153], v[152:153], v[240:241] op_sel_hi:[1,0]
	v_min_f32_e32 v146, 0x42b80000, v146
	v_min_f32_e32 v147, 0x42b80000, v147
	v_min_f32_e32 v148, 0x42b80000, v148
	v_min_f32_e32 v149, 0x42b80000, v149
	v_min_f32_e32 v150, 0x42b80000, v150
	v_min_f32_e32 v151, 0x42b80000, v151
	v_min_f32_e32 v152, 0x42b80000, v152
	v_min_f32_e32 v153, 0x42b80000, v153
	v_exp_f32_e32 v146, v146
	v_exp_f32_e32 v147, v147
	v_exp_f32_e32 v148, v148
	v_exp_f32_e32 v149, v149
	v_exp_f32_e32 v150, v150
	v_exp_f32_e32 v151, v151
	v_exp_f32_e32 v152, v152
	v_exp_f32_e32 v153, v153
	s_nop 0
	v_add_f32_e32 v146, 1.0, v146
	v_add_f32_e32 v147, 1.0, v147
	v_add_f32_e32 v148, 1.0, v148
	v_add_f32_e32 v149, 1.0, v149
	v_add_f32_e32 v150, 1.0, v150
	v_add_f32_e32 v151, 1.0, v151
	v_add_f32_e32 v152, 1.0, v152
	v_add_f32_e32 v153, 1.0, v153
	v_rcp_f32_e32 v146, v146
	v_rcp_f32_e32 v147, v147
	v_rcp_f32_e32 v150, v150
	v_rcp_f32_e32 v151, v151
	s_nop 0
	v_pk_mul_f32 v[146:147], v[146:147], v[148:149]
	v_pk_mul_f32 v[150:151], v[150:151], v[152:153]
	v_pk_mul_f32 v[26:27], v[26:27], v[146:147]
	v_pk_mul_f32 v[28:29], v[28:29], v[150:151]
	s_waitcnt vmcnt(4)
; DI float bflo(unsigned w) { return __uint_as_float(w << 16); }
; DI float bfhi(unsigned w) { return __uint_as_float(w & 0xffff0000u); }
;     DI void operator()(Acc& acc, const Unit& u, int wr, int wc, int fr, int fq) const {
;     ...
;             for (int ai = 0; ai < 2; ++ai)
; #pragma unroll
;                 for (int m = 0; m < 4; ++m)
; #pragma unroll
;                     for (int bj = 0; bj < 2; ++bj) g[ai][m][bj] = *(const u32x4*)(base + (size_t)(ai * 128 + m * 16) * NPJ + u.k * 1024 + bj * 128);
; #pragma unroll
;             for (int ai = 0; ai < 2; ++ai)
; #pragma unroll
;                 for (int m = 0; m < 4; ++m)
; #pragma unroll
;                     for (int bj = 0; bj < 2; ++bj) { const u32x4 q = g[ai][m][bj]; f32x4& v0 = acc[ai][bj][m][0]; f32x4& v1 = acc[ai][bj][m][1];
;                         v0[0] *= bflo(q.x); v0[1] *= bfhi(q.x); v0[2] *= bflo(q.y); v0[3] *= bfhi(q.y); v1[0] *= bflo(q.z); v1[1] *= bfhi(q.z); v1[2] *= bflo(q.w); v1[3] *= bfhi(q.w); }
	v_lshlrev_b32_e32 v146, 16, v184
	v_and_b32_e32 v147, 0xffff0000, v184
	v_lshlrev_b32_e32 v148, 16, v192
	v_and_b32_e32 v149, 0xffff0000, v192
	v_lshlrev_b32_e32 v150, 16, v185
	v_and_b32_e32 v151, 0xffff0000, v185
	v_lshlrev_b32_e32 v152, 16, v193
	v_and_b32_e32 v153, 0xffff0000, v193
	v_pk_mul_f32 v[146:147], v[146:147], v[240:241] op_sel_hi:[1,0]
	v_pk_mul_f32 v[148:149], v[148:149], v[240:241] op_sel_hi:[1,0]
	v_pk_mul_f32 v[150:151], v[150:151], v[240:241] op_sel_hi:[1,0]
	v_pk_mul_f32 v[152:153], v[152:153], v[240:241] op_sel_hi:[1,0]
	v_min_f32_e32 v146, 0x42b80000, v146
	v_min_f32_e32 v147, 0x42b80000, v147
	v_min_f32_e32 v148, 0x42b80000, v148
	v_min_f32_e32 v149, 0x42b80000, v149
	v_min_f32_e32 v150, 0x42b80000, v150
	v_min_f32_e32 v151, 0x42b80000, v151
	v_min_f32_e32 v152, 0x42b80000, v152
	v_min_f32_e32 v153, 0x42b80000, v153
	v_exp_f32_e32 v146, v146
	v_exp_f32_e32 v147, v147
	v_exp_f32_e32 v148, v148
	v_exp_f32_e32 v149, v149
	v_exp_f32_e32 v150, v150
	v_exp_f32_e32 v151, v151
	v_exp_f32_e32 v152, v152
	v_exp_f32_e32 v153, v153
	s_nop 0
	v_add_f32_e32 v146, 1.0, v146
	v_add_f32_e32 v147, 1.0, v147
	v_add_f32_e32 v148, 1.0, v148
	v_add_f32_e32 v149, 1.0, v149
	v_add_f32_e32 v150, 1.0, v150
	v_add_f32_e32 v151, 1.0, v151
	v_add_f32_e32 v152, 1.0, v152
	v_add_f32_e32 v153, 1.0, v153
	v_rcp_f32_e32 v146, v146
	v_rcp_f32_e32 v147, v147
	v_rcp_f32_e32 v150, v150
	v_rcp_f32_e32 v151, v151
	s_nop 0
	v_pk_mul_f32 v[146:147], v[146:147], v[148:149]
	v_pk_mul_f32 v[150:151], v[150:151], v[152:153]
	v_pk_mul_f32 v[38:39], v[38:39], v[146:147]
	v_pk_mul_f32 v[40:41], v[40:41], v[150:151]
	v_lshlrev_b32_e32 v168, 16, v186
	v_and_b32_e32 v169, 0xffff0000, v186
	v_lshlrev_b32_e32 v178, 16, v194
	v_and_b32_e32 v179, 0xffff0000, v194
	v_lshlrev_b32_e32 v180, 16, v187
	v_and_b32_e32 v181, 0xffff0000, v187
	v_lshlrev_b32_e32 v244, 16, v195
	v_and_b32_e32 v245, 0xffff0000, v195
	v_pk_mul_f32 v[168:169], v[168:169], v[240:241] op_sel_hi:[1,0]
	v_pk_mul_f32 v[178:179], v[178:179], v[240:241] op_sel_hi:[1,0]
	v_pk_mul_f32 v[180:181], v[180:181], v[240:241] op_sel_hi:[1,0]
	v_pk_mul_f32 v[244:245], v[244:245], v[240:241] op_sel_hi:[1,0]
	v_min_f32_e32 v168, 0x42b80000, v168
	v_min_f32_e32 v169, 0x42b80000, v169
	v_min_f32_e32 v178, 0x42b80000, v178
	v_min_f32_e32 v179, 0x42b80000, v179
	v_min_f32_e32 v180, 0x42b80000, v180
	v_min_f32_e32 v181, 0x42b80000, v181
	v_min_f32_e32 v244, 0x42b80000, v244
	v_min_f32_e32 v245, 0x42b80000, v245
	v_exp_f32_e32 v168, v168
	v_exp_f32_e32 v169, v169
	v_exp_f32_e32 v178, v178
	v_exp_f32_e32 v179, v179
	v_exp_f32_e32 v180, v180
	v_exp_f32_e32 v181, v181
	v_exp_f32_e32 v244, v244
	v_exp_f32_e32 v245, v245
	s_nop 0
	v_add_f32_e32 v168, 1.0, v168
	v_add_f32_e32 v169, 1.0, v169
	v_add_f32_e32 v178, 1.0, v178
	v_add_f32_e32 v179, 1.0, v179
	v_add_f32_e32 v180, 1.0, v180
	v_add_f32_e32 v181, 1.0, v181
	v_add_f32_e32 v244, 1.0, v244
	v_add_f32_e32 v245, 1.0, v245
	v_rcp_f32_e32 v168, v168
	v_rcp_f32_e32 v169, v169
	v_rcp_f32_e32 v180, v180
	v_rcp_f32_e32 v181, v181
	s_nop 0
	v_pk_mul_f32 v[168:169], v[168:169], v[178:179]
	v_pk_mul_f32 v[180:181], v[180:181], v[244:245]
	v_pk_mul_f32 v[30:31], v[30:31], v[168:169]
	v_pk_mul_f32 v[32:33], v[32:33], v[180:181]
	v_lshlrev_b32_e32 v168, 16, v188
	v_and_b32_e32 v169, 0xffff0000, v188
	v_lshlrev_b32_e32 v178, 16, v196
	v_and_b32_e32 v179, 0xffff0000, v196
	v_lshlrev_b32_e32 v180, 16, v189
	v_and_b32_e32 v181, 0xffff0000, v189
	v_lshlrev_b32_e32 v244, 16, v197
	v_and_b32_e32 v245, 0xffff0000, v197
	v_pk_mul_f32 v[168:169], v[168:169], v[240:241] op_sel_hi:[1,0]
	v_pk_mul_f32 v[178:179], v[178:179], v[240:241] op_sel_hi:[1,0]
	v_pk_mul_f32 v[180:181], v[180:181], v[240:241] op_sel_hi:[1,0]
	v_pk_mul_f32 v[244:245], v[244:245], v[240:241] op_sel_hi:[1,0]
	v_min_f32_e32 v168, 0x42b80000, v168
	v_min_f32_e32 v169, 0x42b80000, v169
	v_min_f32_e32 v178, 0x42b80000, v178
	v_min_f32_e32 v179, 0x42b80000, v179
	v_min_f32_e32 v180, 0x42b80000, v180
	v_min_f32_e32 v181, 0x42b80000, v181
	v_min_f32_e32 v244, 0x42b80000, v244
	v_min_f32_e32 v245, 0x42b80000, v245
	v_exp_f32_e32 v168, v168
	v_exp_f32_e32 v169, v169
	v_exp_f32_e32 v178, v178
	v_exp_f32_e32 v179, v179
	v_exp_f32_e32 v180, v180
	v_exp_f32_e32 v181, v181
	v_exp_f32_e32 v244, v244
	v_exp_f32_e32 v245, v245
	s_nop 0
	v_add_f32_e32 v168, 1.0, v168
	v_add_f32_e32 v169, 1.0, v169
	v_add_f32_e32 v178, 1.0, v178
	v_add_f32_e32 v179, 1.0, v179
	v_add_f32_e32 v180, 1.0, v180
	v_add_f32_e32 v181, 1.0, v181
	v_add_f32_e32 v244, 1.0, v244
	v_add_f32_e32 v245, 1.0, v245
	v_rcp_f32_e32 v168, v168
	v_rcp_f32_e32 v169, v169
	v_rcp_f32_e32 v180, v180
	v_rcp_f32_e32 v181, v181
	s_nop 0
	v_pk_mul_f32 v[168:169], v[168:169], v[178:179]
	v_pk_mul_f32 v[180:181], v[180:181], v[244:245]
	v_pk_mul_f32 v[18:19], v[18:19], v[168:169]
	v_pk_mul_f32 v[20:21], v[20:21], v[180:181]
	v_lshlrev_b32_e32 v146, 16, v190
	v_and_b32_e32 v147, 0xffff0000, v190
	v_lshlrev_b32_e32 v148, 16, v198
	v_and_b32_e32 v149, 0xffff0000, v198
	v_lshlrev_b32_e32 v150, 16, v191
	v_and_b32_e32 v151, 0xffff0000, v191
	v_lshlrev_b32_e32 v152, 16, v199
	v_and_b32_e32 v153, 0xffff0000, v199
	v_pk_mul_f32 v[146:147], v[146:147], v[240:241] op_sel_hi:[1,0]
	v_pk_mul_f32 v[148:149], v[148:149], v[240:241] op_sel_hi:[1,0]
	v_pk_mul_f32 v[150:151], v[150:151], v[240:241] op_sel_hi:[1,0]
	v_pk_mul_f32 v[152:153], v[152:153], v[240:241] op_sel_hi:[1,0]
	v_min_f32_e32 v146, 0x42b80000, v146
	v_min_f32_e32 v147, 0x42b80000, v147
	v_min_f32_e32 v148, 0x42b80000, v148
	v_min_f32_e32 v149, 0x42b80000, v149
	v_min_f32_e32 v150, 0x42b80000, v150
	v_min_f32_e32 v151, 0x42b80000, v151
	v_min_f32_e32 v152, 0x42b80000, v152
	v_min_f32_e32 v153, 0x42b80000, v153
	v_exp_f32_e32 v146, v146
	v_exp_f32_e32 v147, v147
	v_exp_f32_e32 v148, v148
	v_exp_f32_e32 v149, v149
	v_exp_f32_e32 v150, v150
	v_exp_f32_e32 v151, v151
	v_exp_f32_e32 v152, v152
	v_exp_f32_e32 v153, v153
	s_nop 0
	v_add_f32_e32 v146, 1.0, v146
	v_add_f32_e32 v147, 1.0, v147
	v_add_f32_e32 v148, 1.0, v148
	v_add_f32_e32 v149, 1.0, v149
	v_add_f32_e32 v150, 1.0, v150
	v_add_f32_e32 v151, 1.0, v151
	v_add_f32_e32 v152, 1.0, v152
	v_add_f32_e32 v153, 1.0, v153
	v_rcp_f32_e32 v146, v146
	v_rcp_f32_e32 v147, v147
	v_rcp_f32_e32 v150, v150
	v_rcp_f32_e32 v151, v151
	s_nop 0
	v_pk_mul_f32 v[146:147], v[146:147], v[148:149]
	v_pk_mul_f32 v[150:151], v[150:151], v[152:153]
	v_pk_mul_f32 v[10:11], v[10:11], v[146:147]
	v_pk_mul_f32 v[12:13], v[12:13], v[150:151]
	s_waitcnt vmcnt(0)
; DI float bflo(unsigned w) { return __uint_as_float(w << 16); }
; DI float bfhi(unsigned w) { return __uint_as_float(w & 0xffff0000u); }
;     DI void operator()(Acc& acc, const Unit& u, int wr, int wc, int fr, int fq) const {
;     ...
;             for (int ai = 0; ai < 2; ++ai)
; #pragma unroll
;                 for (int m = 0; m < 4; ++m)
; #pragma unroll
;                     for (int bj = 0; bj < 2; ++bj) g[ai][m][bj] = *(const u32x4*)(base + (size_t)(ai * 128 + m * 16) * NPJ + u.k * 1024 + bj * 128);
; #pragma unroll
;             for (int ai = 0; ai < 2; ++ai)
; #pragma unroll
;                 for (int m = 0; m < 4; ++m)
; #pragma unroll
;                     for (int bj = 0; bj < 2; ++bj) { const u32x4 q = g[ai][m][bj]; f32x4& v0 = acc[ai][bj][m][0]; f32x4& v1 = acc[ai][bj][m][1];
;                         v0[0] *= bflo(q.x); v0[1] *= bfhi(q.x); v0[2] *= bflo(q.y); v0[3] *= bfhi(q.y); v1[0] *= bflo(q.z); v1[1] *= bfhi(q.z); v1[2] *= bflo(q.w); v1[3] *= bfhi(q.w); }
	v_lshlrev_b32_e32 v146, 16, v200
	v_and_b32_e32 v147, 0xffff0000, v200
	v_lshlrev_b32_e32 v148, 16, v208
	v_and_b32_e32 v149, 0xffff0000, v208
	v_lshlrev_b32_e32 v150, 16, v201
	v_and_b32_e32 v151, 0xffff0000, v201
	v_lshlrev_b32_e32 v152, 16, v209
	v_and_b32_e32 v153, 0xffff0000, v209
	v_pk_mul_f32 v[146:147], v[146:147], v[240:241] op_sel_hi:[1,0]
	v_pk_mul_f32 v[148:149], v[148:149], v[240:241] op_sel_hi:[1,0]
	v_pk_mul_f32 v[150:151], v[150:151], v[240:241] op_sel_hi:[1,0]
	v_pk_mul_f32 v[152:153], v[152:153], v[240:241] op_sel_hi:[1,0]
	v_min_f32_e32 v146, 0x42b80000, v146
	v_min_f32_e32 v147, 0x42b80000, v147
	v_min_f32_e32 v148, 0x42b80000, v148
	v_min_f32_e32 v149, 0x42b80000, v149
	v_min_f32_e32 v150, 0x42b80000, v150
	v_min_f32_e32 v151, 0x42b80000, v151
	v_min_f32_e32 v152, 0x42b80000, v152
	v_min_f32_e32 v153, 0x42b80000, v153
	v_exp_f32_e32 v146, v146
	v_exp_f32_e32 v147, v147
	v_exp_f32_e32 v148, v148
	v_exp_f32_e32 v149, v149
	v_exp_f32_e32 v150, v150
	v_exp_f32_e32 v151, v151
	v_exp_f32_e32 v152, v152
	v_exp_f32_e32 v153, v153
	s_nop 0
	v_add_f32_e32 v146, 1.0, v146
	v_add_f32_e32 v147, 1.0, v147
	v_add_f32_e32 v148, 1.0, v148
	v_add_f32_e32 v149, 1.0, v149
	v_add_f32_e32 v150, 1.0, v150
	v_add_f32_e32 v151, 1.0, v151
	v_add_f32_e32 v152, 1.0, v152
	v_add_f32_e32 v153, 1.0, v153
	v_rcp_f32_e32 v146, v146
	v_rcp_f32_e32 v147, v147
	v_rcp_f32_e32 v150, v150
	v_rcp_f32_e32 v151, v151
	s_nop 0
	v_pk_mul_f32 v[146:147], v[146:147], v[148:149]
	v_pk_mul_f32 v[150:151], v[150:151], v[152:153]
	v_pk_mul_f32 v[22:23], v[22:23], v[146:147]
	v_pk_mul_f32 v[24:25], v[24:25], v[150:151]
	v_lshlrev_b32_e32 v168, 16, v202
	v_and_b32_e32 v169, 0xffff0000, v202
	v_lshlrev_b32_e32 v178, 16, v210
	v_and_b32_e32 v179, 0xffff0000, v210
	v_lshlrev_b32_e32 v180, 16, v203
	v_and_b32_e32 v181, 0xffff0000, v203
	v_lshlrev_b32_e32 v244, 16, v211
	v_and_b32_e32 v245, 0xffff0000, v211
	v_pk_mul_f32 v[168:169], v[168:169], v[240:241] op_sel_hi:[1,0]
	v_pk_mul_f32 v[178:179], v[178:179], v[240:241] op_sel_hi:[1,0]
	v_pk_mul_f32 v[180:181], v[180:181], v[240:241] op_sel_hi:[1,0]
	v_pk_mul_f32 v[244:245], v[244:245], v[240:241] op_sel_hi:[1,0]
	v_min_f32_e32 v168, 0x42b80000, v168
	v_min_f32_e32 v169, 0x42b80000, v169
	v_min_f32_e32 v178, 0x42b80000, v178
	v_min_f32_e32 v179, 0x42b80000, v179
	v_min_f32_e32 v180, 0x42b80000, v180
	v_min_f32_e32 v181, 0x42b80000, v181
	v_min_f32_e32 v244, 0x42b80000, v244
	v_min_f32_e32 v245, 0x42b80000, v245
	v_exp_f32_e32 v168, v168
	v_exp_f32_e32 v169, v169
	v_exp_f32_e32 v178, v178
	v_exp_f32_e32 v179, v179
	v_exp_f32_e32 v180, v180
	v_exp_f32_e32 v181, v181
	v_exp_f32_e32 v244, v244
	v_exp_f32_e32 v245, v245
	s_nop 0
	v_add_f32_e32 v168, 1.0, v168
	v_add_f32_e32 v169, 1.0, v169
	v_add_f32_e32 v178, 1.0, v178
	v_add_f32_e32 v179, 1.0, v179
	v_add_f32_e32 v180, 1.0, v180
	v_add_f32_e32 v181, 1.0, v181
	v_add_f32_e32 v244, 1.0, v244
	v_add_f32_e32 v245, 1.0, v245
	v_rcp_f32_e32 v168, v168
	v_rcp_f32_e32 v169, v169
	v_rcp_f32_e32 v180, v180
	v_rcp_f32_e32 v181, v181
	s_nop 0
	v_pk_mul_f32 v[168:169], v[168:169], v[178:179]
	v_pk_mul_f32 v[180:181], v[180:181], v[244:245]
	v_pk_mul_f32 v[14:15], v[14:15], v[168:169]
	v_pk_mul_f32 v[16:17], v[16:17], v[180:181]
	v_lshlrev_b32_e32 v168, 16, v204
	v_and_b32_e32 v169, 0xffff0000, v204
	v_lshlrev_b32_e32 v178, 16, v212
	v_and_b32_e32 v179, 0xffff0000, v212
	v_lshlrev_b32_e32 v180, 16, v205
	v_and_b32_e32 v181, 0xffff0000, v205
	v_lshlrev_b32_e32 v244, 16, v213
	v_and_b32_e32 v245, 0xffff0000, v213
	v_pk_mul_f32 v[168:169], v[168:169], v[240:241] op_sel_hi:[1,0]
	v_pk_mul_f32 v[178:179], v[178:179], v[240:241] op_sel_hi:[1,0]
	v_pk_mul_f32 v[180:181], v[180:181], v[240:241] op_sel_hi:[1,0]
	v_pk_mul_f32 v[244:245], v[244:245], v[240:241] op_sel_hi:[1,0]
	v_min_f32_e32 v168, 0x42b80000, v168
	v_min_f32_e32 v169, 0x42b80000, v169
	v_min_f32_e32 v178, 0x42b80000, v178
	v_min_f32_e32 v179, 0x42b80000, v179
	v_min_f32_e32 v180, 0x42b80000, v180
	v_min_f32_e32 v181, 0x42b80000, v181
	v_min_f32_e32 v244, 0x42b80000, v244
	v_min_f32_e32 v245, 0x42b80000, v245
	v_exp_f32_e32 v168, v168
	v_exp_f32_e32 v169, v169
	v_exp_f32_e32 v178, v178
	v_exp_f32_e32 v179, v179
	v_exp_f32_e32 v180, v180
	v_exp_f32_e32 v181, v181
	v_exp_f32_e32 v244, v244
	v_exp_f32_e32 v245, v245
	s_nop 0
	v_add_f32_e32 v168, 1.0, v168
	v_add_f32_e32 v169, 1.0, v169
	v_add_f32_e32 v178, 1.0, v178
	v_add_f32_e32 v179, 1.0, v179
	v_add_f32_e32 v180, 1.0, v180
	v_add_f32_e32 v181, 1.0, v181
	v_add_f32_e32 v244, 1.0, v244
	v_add_f32_e32 v245, 1.0, v245
	v_rcp_f32_e32 v168, v168
	v_rcp_f32_e32 v169, v169
	v_rcp_f32_e32 v180, v180
	v_rcp_f32_e32 v181, v181
	s_nop 0
	v_pk_mul_f32 v[168:169], v[168:169], v[178:179]
	v_pk_mul_f32 v[180:181], v[180:181], v[244:245]
	v_pk_mul_f32 v[6:7], v[6:7], v[168:169]
	v_pk_mul_f32 v[8:9], v[8:9], v[180:181]
	v_lshlrev_b32_e32 v146, 16, v206
	v_and_b32_e32 v147, 0xffff0000, v206
	v_lshlrev_b32_e32 v148, 16, v214
	v_and_b32_e32 v149, 0xffff0000, v214
	v_lshlrev_b32_e32 v150, 16, v207
	v_and_b32_e32 v151, 0xffff0000, v207
	v_lshlrev_b32_e32 v152, 16, v215
	v_and_b32_e32 v153, 0xffff0000, v215
	v_pk_mul_f32 v[146:147], v[146:147], v[240:241] op_sel_hi:[1,0]
	v_pk_mul_f32 v[148:149], v[148:149], v[240:241] op_sel_hi:[1,0]
	v_pk_mul_f32 v[150:151], v[150:151], v[240:241] op_sel_hi:[1,0]
	v_pk_mul_f32 v[152:153], v[152:153], v[240:241] op_sel_hi:[1,0]
	v_min_f32_e32 v146, 0x42b80000, v146
	v_min_f32_e32 v147, 0x42b80000, v147
	v_min_f32_e32 v148, 0x42b80000, v148
	v_min_f32_e32 v149, 0x42b80000, v149
	v_min_f32_e32 v150, 0x42b80000, v150
	v_min_f32_e32 v151, 0x42b80000, v151
	v_min_f32_e32 v152, 0x42b80000, v152
	v_min_f32_e32 v153, 0x42b80000, v153
	v_exp_f32_e32 v146, v146
	v_exp_f32_e32 v147, v147
	v_exp_f32_e32 v148, v148
	v_exp_f32_e32 v149, v149
	v_exp_f32_e32 v150, v150
	v_exp_f32_e32 v151, v151
	v_exp_f32_e32 v152, v152
	v_exp_f32_e32 v153, v153
	s_nop 0
	v_add_f32_e32 v146, 1.0, v146
	v_add_f32_e32 v147, 1.0, v147
	v_add_f32_e32 v148, 1.0, v148
	v_add_f32_e32 v149, 1.0, v149
	v_add_f32_e32 v150, 1.0, v150
	v_add_f32_e32 v151, 1.0, v151
	v_add_f32_e32 v152, 1.0, v152
	v_add_f32_e32 v153, 1.0, v153
	v_rcp_f32_e32 v146, v146
	v_rcp_f32_e32 v147, v147
	v_rcp_f32_e32 v150, v150
	v_rcp_f32_e32 v151, v151
	s_nop 0
	v_pk_mul_f32 v[146:147], v[146:147], v[148:149]
	v_pk_mul_f32 v[150:151], v[150:151], v[152:153]
	v_pk_mul_f32 v[2:3], v[2:3], v[146:147]
	v_pk_mul_f32 v[4:5], v[4:5], v[150:151]
	s_branch .Lup3_tail
; DI float bflo(unsigned w) { return __uint_as_float(w << 16); }
; DI float bfhi(unsigned w) { return __uint_as_float(w & 0xffff0000u); }
; DI u32x4 pack8(f32x4 a, f32x4 b) { u32x4 w; w.x = pk2(a[0], a[1]); w.y = pk2(a[2], a[3]); w.z = pk2(b[0], b[1]); w.w = pk2(b[2], b[3]); return w; }
;     DI void operator()(Acc& acc, const Unit& u, int wr, int wc, int fr, int fq) const {
;     ...
;         bf16_t* base = proj + (size_t)(u.pm * 256 + wr * 64 + fr) * NPJ + C_GL + u.pn * 256 + wc * 32 + fq * 8;
;         {
;             u32x4 g[2][4][2];
; #pragma unroll
;             for (int ai = 0; ai < 2; ++ai)
; #pragma unroll
;                 for (int m = 0; m < 4; ++m)
; #pragma unroll
;                     for (int bj = 0; bj < 2; ++bj) g[ai][m][bj] = *(const u32x4*)(base + (size_t)(ai * 128 + m * 16) * NPJ + u.k * 1024 + bj * 128);
; #pragma unroll
;             for (int ai = 0; ai < 2; ++ai)
; #pragma unroll
;                 for (int m = 0; m < 4; ++m)
; #pragma unroll
;                     for (int bj = 0; bj < 2; ++bj) { const u32x4 q = g[ai][m][bj]; f32x4& v0 = acc[ai][bj][m][0]; f32x4& v1 = acc[ai][bj][m][1];
;                         v0[0] *= bflo(q.x); v0[1] *= bfhi(q.x); v0[2] *= bflo(q.y); v0[3] *= bfhi(q.y); v1[0] *= bflo(q.z); v1[1] *= bfhi(q.z); v1[2] *= bflo(q.w); v1[3] *= bfhi(q.w); }
;     ...
;                     for (int bj = 0; bj < 2; ++bj) *(u32x4*)(base + (size_t)(ai * 128 + m * 16) * NPJ + bj * 128) = pack8(acc[ai][bj][m][0], acc[ai][bj][m][1]);
.Lup3_final:
	s_mov_b32 s101, 0
	s_mov_b32 s100, 0x32000
	v_lshl_add_u64 v[132:133], v[166:167], 0, s[100:101]
	s_mov_b32 s100, 0x64000
	v_lshl_add_u64 v[134:135], v[166:167], 0, s[100:101]
	s_mov_b32 s100, 0x96000
	v_lshl_add_u64 v[136:137], v[166:167], 0, s[100:101]
	s_mov_b32 s100, 0x190000
	v_lshl_add_u64 v[138:139], v[166:167], 0, s[100:101]
	s_mov_b32 s100, 0x1c2000
	v_lshl_add_u64 v[140:141], v[166:167], 0, s[100:101]
	s_mov_b32 s100, 0x1f4000
	v_lshl_add_u64 v[142:143], v[166:167], 0, s[100:101]
	s_mov_b32 s100, 0x226000
	v_lshl_add_u64 v[144:145], v[166:167], 0, s[100:101]
	s_add_u32 s100, s98, 0x0
	s_addc_u32 s101, s99, 0
	global_load_dwordx4 v[184:187], v243, s[100:101]
	s_add_u32 s100, s98, 0x19000
	s_addc_u32 s101, s99, 0
	global_load_dwordx4 v[188:191], v243, s[100:101]
	s_add_u32 s100, s98, 0x32000
	s_addc_u32 s101, s99, 0
	global_load_dwordx4 v[192:195], v243, s[100:101]
	s_add_u32 s100, s98, 0x4b000
	s_addc_u32 s101, s99, 0
	global_load_dwordx4 v[196:199], v243, s[100:101]
	s_add_u32 s100, s98, 0x64000
	s_addc_u32 s101, s99, 0
	global_load_dwordx4 v[200:203], v243, s[100:101]
	s_add_u32 s100, s98, 0x7d000
	s_addc_u32 s101, s99, 0
	global_load_dwordx4 v[204:207], v243, s[100:101]
	s_add_u32 s100, s98, 0x96000
	s_addc_u32 s101, s99, 0
	global_load_dwordx4 v[208:211], v243, s[100:101]
	s_add_u32 s100, s98, 0xaf000
	s_addc_u32 s101, s99, 0
	global_load_dwordx4 v[212:215], v243, s[100:101]
	s_add_u32 s100, s98, 0x190000
	s_addc_u32 s101, s99, 0
	global_load_dwordx4 v[216:219], v243, s[100:101]
	s_add_u32 s100, s98, 0x1a9000
	s_addc_u32 s101, s99, 0
	global_load_dwordx4 v[220:223], v243, s[100:101]
	s_add_u32 s100, s98, 0x1c2000
	s_addc_u32 s101, s99, 0
	global_load_dwordx4 v[224:227], v243, s[100:101]
	s_add_u32 s100, s98, 0x1db000
	s_addc_u32 s101, s99, 0
	global_load_dwordx4 v[228:231], v243, s[100:101]
	s_waitcnt vmcnt(10)
	v_lshlrev_b32_e32 v146, 16, v184
	v_and_b32_e32 v147, 0xffff0000, v184
	v_lshlrev_b32_e32 v148, 16, v185
	v_and_b32_e32 v149, 0xffff0000, v185
	v_lshlrev_b32_e32 v150, 16, v186
	v_and_b32_e32 v151, 0xffff0000, v186
	v_lshlrev_b32_e32 v152, 16, v187
	v_and_b32_e32 v153, 0xffff0000, v187
	v_pk_mul_f32 v[146:147], v[146:147], v[240:241] op_sel_hi:[1,0]
	v_pk_mul_f32 v[148:149], v[148:149], v[240:241] op_sel_hi:[1,0]
	v_pk_mul_f32 v[150:151], v[150:151], v[240:241] op_sel_hi:[1,0]
	v_pk_mul_f32 v[152:153], v[152:153], v[240:241] op_sel_hi:[1,0]
	v_min_f32_e32 v146, 0x42b80000, v146
	v_min_f32_e32 v147, 0x42b80000, v147
	v_min_f32_e32 v148, 0x42b80000, v148
	v_min_f32_e32 v149, 0x42b80000, v149
	v_min_f32_e32 v150, 0x42b80000, v150
	v_min_f32_e32 v151, 0x42b80000, v151
	v_min_f32_e32 v152, 0x42b80000, v152
	v_min_f32_e32 v153, 0x42b80000, v153
	v_exp_f32_e32 v146, v146
	v_exp_f32_e32 v147, v147
	v_exp_f32_e32 v148, v148
	v_exp_f32_e32 v149, v149
	v_exp_f32_e32 v150, v150
	v_exp_f32_e32 v151, v151
	v_exp_f32_e32 v152, v152
	v_exp_f32_e32 v153, v153
	s_nop 0
	v_add_f32_e32 v146, 1.0, v146
	v_add_f32_e32 v147, 1.0, v147
	v_add_f32_e32 v148, 1.0, v148
	v_add_f32_e32 v149, 1.0, v149
	v_add_f32_e32 v150, 1.0, v150
	v_add_f32_e32 v151, 1.0, v151
	v_add_f32_e32 v152, 1.0, v152
	v_add_f32_e32 v153, 1.0, v153
	v_rcp_f32_e32 v146, v146
	v_rcp_f32_e32 v147, v147
	v_rcp_f32_e32 v148, v148
	v_rcp_f32_e32 v149, v149
	v_rcp_f32_e32 v150, v150
	v_rcp_f32_e32 v151, v151
	v_rcp_f32_e32 v152, v152
	v_rcp_f32_e32 v153, v153
	s_nop 0
	v_pk_mul_f32 v[126:127], v[126:127], v[146:147]
	v_pk_mul_f32 v[128:129], v[128:129], v[148:149]
	v_pk_mul_f32 v[122:123], v[122:123], v[150:151]
	v_pk_mul_f32 v[124:125], v[124:125], v[152:153]
	v_cvt_pk_bf16_f32 v184, v126, v127
	v_cvt_pk_bf16_f32 v185, v128, v129
	v_cvt_pk_bf16_f32 v186, v122, v123
	v_cvt_pk_bf16_f32 v187, v124, v125
	v_lshlrev_b32_e32 v168, 16, v188
	v_and_b32_e32 v169, 0xffff0000, v188
	v_lshlrev_b32_e32 v178, 16, v189
	v_and_b32_e32 v179, 0xffff0000, v189
	v_lshlrev_b32_e32 v180, 16, v190
	v_and_b32_e32 v181, 0xffff0000, v190
	v_lshlrev_b32_e32 v244, 16, v191
	v_and_b32_e32 v245, 0xffff0000, v191
	v_pk_mul_f32 v[168:169], v[168:169], v[240:241] op_sel_hi:[1,0]
	v_pk_mul_f32 v[178:179], v[178:179], v[240:241] op_sel_hi:[1,0]
	v_pk_mul_f32 v[180:181], v[180:181], v[240:241] op_sel_hi:[1,0]
	v_pk_mul_f32 v[244:245], v[244:245], v[240:241] op_sel_hi:[1,0]
	v_min_f32_e32 v168, 0x42b80000, v168
	v_min_f32_e32 v169, 0x42b80000, v169
	v_min_f32_e32 v178, 0x42b80000, v178
	v_min_f32_e32 v179, 0x42b80000, v179
	v_min_f32_e32 v180, 0x42b80000, v180
	v_min_f32_e32 v181, 0x42b80000, v181
	v_min_f32_e32 v244, 0x42b80000, v244
	v_min_f32_e32 v245, 0x42b80000, v245
	v_exp_f32_e32 v168, v168
	v_exp_f32_e32 v169, v169
	v_exp_f32_e32 v178, v178
	v_exp_f32_e32 v179, v179
	v_exp_f32_e32 v180, v180
	v_exp_f32_e32 v181, v181
	v_exp_f32_e32 v244, v244
	v_exp_f32_e32 v245, v245
	s_nop 0
	v_add_f32_e32 v168, 1.0, v168
	v_add_f32_e32 v169, 1.0, v169
	v_add_f32_e32 v178, 1.0, v178
	v_add_f32_e32 v179, 1.0, v179
	v_add_f32_e32 v180, 1.0, v180
	v_add_f32_e32 v181, 1.0, v181
	v_add_f32_e32 v244, 1.0, v244
	v_add_f32_e32 v245, 1.0, v245
	v_rcp_f32_e32 v168, v168
	v_rcp_f32_e32 v169, v169
	v_rcp_f32_e32 v178, v178
	v_rcp_f32_e32 v179, v179
	v_rcp_f32_e32 v180, v180
	v_rcp_f32_e32 v181, v181
	v_rcp_f32_e32 v244, v244
	v_rcp_f32_e32 v245, v245
	s_nop 0
	v_pk_mul_f32 v[114:115], v[114:115], v[168:169]
	v_pk_mul_f32 v[116:117], v[116:117], v[178:179]
	v_pk_mul_f32 v[110:111], v[110:111], v[180:181]
	v_pk_mul_f32 v[112:113], v[112:113], v[244:245]
	v_cvt_pk_bf16_f32 v188, v114, v115
	v_cvt_pk_bf16_f32 v189, v116, v117
	v_cvt_pk_bf16_f32 v190, v110, v111
	v_cvt_pk_bf16_f32 v191, v112, v113
	global_store_dwordx4 v[166:167], v[184:187], off
	global_store_dwordx4 v[166:167], v[188:191], off offset:256
	s_nop 1
	s_add_u32 s100, s98, 0x1f4000
	s_addc_u32 s101, s99, 0
	global_load_dwordx4 v[184:187], v243, s[100:101]
	s_add_u32 s100, s98, 0x20d000
	s_addc_u32 s101, s99, 0
	global_load_dwordx4 v[188:191], v243, s[100:101]
	s_waitcnt vmcnt(12)
; DI float bflo(unsigned w) { return __uint_as_float(w << 16); }
; DI float bfhi(unsigned w) { return __uint_as_float(w & 0xffff0000u); }
; DI u32x4 pack8(f32x4 a, f32x4 b) { u32x4 w; w.x = pk2(a[0], a[1]); w.y = pk2(a[2], a[3]); w.z = pk2(b[0], b[1]); w.w = pk2(b[2], b[3]); return w; }
;     DI void operator()(Acc& acc, const Unit& u, int wr, int wc, int fr, int fq) const {
;     ...
;             for (int ai = 0; ai < 2; ++ai)
; #pragma unroll
;                 for (int m = 0; m < 4; ++m)
; #pragma unroll
;                     for (int bj = 0; bj < 2; ++bj) g[ai][m][bj] = *(const u32x4*)(base + (size_t)(ai * 128 + m * 16) * NPJ + u.k * 1024 + bj * 128);
; #pragma unroll
;             for (int ai = 0; ai < 2; ++ai)
; #pragma unroll
;                 for (int m = 0; m < 4; ++m)
; #pragma unroll
;                     for (int bj = 0; bj < 2; ++bj) { const u32x4 q = g[ai][m][bj]; f32x4& v0 = acc[ai][bj][m][0]; f32x4& v1 = acc[ai][bj][m][1];
;                         v0[0] *= bflo(q.x); v0[1] *= bfhi(q.x); v0[2] *= bflo(q.y); v0[3] *= bfhi(q.y); v1[0] *= bflo(q.z); v1[1] *= bfhi(q.z); v1[2] *= bflo(q.w); v1[3] *= bfhi(q.w); }
;     ...
;                     for (int bj = 0; bj < 2; ++bj) *(u32x4*)(base + (size_t)(ai * 128 + m * 16) * NPJ + bj * 128) = pack8(acc[ai][bj][m][0], acc[ai][bj][m][1]);
	v_lshlrev_b32_e32 v146, 16, v192
	v_and_b32_e32 v147, 0xffff0000, v192
	v_lshlrev_b32_e32 v148, 16, v193
	v_and_b32_e32 v149, 0xffff0000, v193
	v_lshlrev_b32_e32 v150, 16, v194
	v_and_b32_e32 v151, 0xffff0000, v194
	v_lshlrev_b32_e32 v152, 16, v195
	v_and_b32_e32 v153, 0xffff0000, v195
	v_pk_mul_f32 v[146:147], v[146:147], v[240:241] op_sel_hi:[1,0]
	v_pk_mul_f32 v[148:149], v[148:149], v[240:241] op_sel_hi:[1,0]
	v_pk_mul_f32 v[150:151], v[150:151], v[240:241] op_sel_hi:[1,0]
	v_pk_mul_f32 v[152:153], v[152:153], v[240:241] op_sel_hi:[1,0]
	v_min_f32_e32 v146, 0x42b80000, v146
	v_min_f32_e32 v147, 0x42b80000, v147
	v_min_f32_e32 v148, 0x42b80000, v148
	v_min_f32_e32 v149, 0x42b80000, v149
	v_min_f32_e32 v150, 0x42b80000, v150
	v_min_f32_e32 v151, 0x42b80000, v151
	v_min_f32_e32 v152, 0x42b80000, v152
	v_min_f32_e32 v153, 0x42b80000, v153
	v_exp_f32_e32 v146, v146
	v_exp_f32_e32 v147, v147
	v_exp_f32_e32 v148, v148
	v_exp_f32_e32 v149, v149
	v_exp_f32_e32 v150, v150
	v_exp_f32_e32 v151, v151
	v_exp_f32_e32 v152, v152
	v_exp_f32_e32 v153, v153
	s_nop 0
	v_add_f32_e32 v146, 1.0, v146
	v_add_f32_e32 v147, 1.0, v147
	v_add_f32_e32 v148, 1.0, v148
	v_add_f32_e32 v149, 1.0, v149
	v_add_f32_e32 v150, 1.0, v150
	v_add_f32_e32 v151, 1.0, v151
	v_add_f32_e32 v152, 1.0, v152
	v_add_f32_e32 v153, 1.0, v153
	v_rcp_f32_e32 v146, v146
	v_rcp_f32_e32 v147, v147
	v_rcp_f32_e32 v148, v148
	v_rcp_f32_e32 v149, v149
	v_rcp_f32_e32 v150, v150
	v_rcp_f32_e32 v151, v151
	v_rcp_f32_e32 v152, v152
	v_rcp_f32_e32 v153, v153
	s_nop 0
	v_pk_mul_f32 v[118:119], v[118:119], v[146:147]
	v_pk_mul_f32 v[120:121], v[120:121], v[148:149]
	v_pk_mul_f32 v[106:107], v[106:107], v[150:151]
	v_pk_mul_f32 v[108:109], v[108:109], v[152:153]
	v_cvt_pk_bf16_f32 v192, v118, v119
	v_cvt_pk_bf16_f32 v193, v120, v121
	v_cvt_pk_bf16_f32 v194, v106, v107
	v_cvt_pk_bf16_f32 v195, v108, v109
	v_lshlrev_b32_e32 v168, 16, v196
	v_and_b32_e32 v169, 0xffff0000, v196
	v_lshlrev_b32_e32 v178, 16, v197
	v_and_b32_e32 v179, 0xffff0000, v197
	v_lshlrev_b32_e32 v180, 16, v198
	v_and_b32_e32 v181, 0xffff0000, v198
	v_lshlrev_b32_e32 v244, 16, v199
	v_and_b32_e32 v245, 0xffff0000, v199
	v_pk_mul_f32 v[168:169], v[168:169], v[240:241] op_sel_hi:[1,0]
	v_pk_mul_f32 v[178:179], v[178:179], v[240:241] op_sel_hi:[1,0]
	v_pk_mul_f32 v[180:181], v[180:181], v[240:241] op_sel_hi:[1,0]
	v_pk_mul_f32 v[244:245], v[244:245], v[240:241] op_sel_hi:[1,0]
	v_min_f32_e32 v168, 0x42b80000, v168
	v_min_f32_e32 v169, 0x42b80000, v169
	v_min_f32_e32 v178, 0x42b80000, v178
	v_min_f32_e32 v179, 0x42b80000, v179
	v_min_f32_e32 v180, 0x42b80000, v180
	v_min_f32_e32 v181, 0x42b80000, v181
	v_min_f32_e32 v244, 0x42b80000, v244
	v_min_f32_e32 v245, 0x42b80000, v245
	v_exp_f32_e32 v168, v168
	v_exp_f32_e32 v169, v169
	v_exp_f32_e32 v178, v178
	v_exp_f32_e32 v179, v179
	v_exp_f32_e32 v180, v180
	v_exp_f32_e32 v181, v181
	v_exp_f32_e32 v244, v244
	v_exp_f32_e32 v245, v245
	s_nop 0
	v_add_f32_e32 v168, 1.0, v168
	v_add_f32_e32 v169, 1.0, v169
	v_add_f32_e32 v178, 1.0, v178
	v_add_f32_e32 v179, 1.0, v179
	v_add_f32_e32 v180, 1.0, v180
	v_add_f32_e32 v181, 1.0, v181
	v_add_f32_e32 v244, 1.0, v244
	v_add_f32_e32 v245, 1.0, v245
	v_rcp_f32_e32 v168, v168
	v_rcp_f32_e32 v169, v169
	v_rcp_f32_e32 v178, v178
	v_rcp_f32_e32 v179, v179
	v_rcp_f32_e32 v180, v180
	v_rcp_f32_e32 v181, v181
	v_rcp_f32_e32 v244, v244
	v_rcp_f32_e32 v245, v245
	s_nop 0
	v_pk_mul_f32 v[98:99], v[98:99], v[168:169]
	v_pk_mul_f32 v[100:101], v[100:101], v[178:179]
	v_pk_mul_f32 v[90:91], v[90:91], v[180:181]
	v_pk_mul_f32 v[92:93], v[92:93], v[244:245]
	v_cvt_pk_bf16_f32 v196, v98, v99
	v_cvt_pk_bf16_f32 v197, v100, v101
	v_cvt_pk_bf16_f32 v198, v90, v91
	v_cvt_pk_bf16_f32 v199, v92, v93
	global_store_dwordx4 v[132:133], v[192:195], off
	global_store_dwordx4 v[132:133], v[196:199], off offset:256
	s_nop 1
	s_add_u32 s100, s98, 0x226000
	s_addc_u32 s101, s99, 0
	global_load_dwordx4 v[192:195], v243, s[100:101]
	s_add_u32 s100, s98, 0x23f000
	s_addc_u32 s101, s99, 0
	global_load_dwordx4 v[196:199], v243, s[100:101]
	s_waitcnt vmcnt(14)
	v_lshlrev_b32_e32 v146, 16, v200
	v_and_b32_e32 v147, 0xffff0000, v200
	v_lshlrev_b32_e32 v148, 16, v201
	v_and_b32_e32 v149, 0xffff0000, v201
	v_lshlrev_b32_e32 v150, 16, v202
	v_and_b32_e32 v151, 0xffff0000, v202
	v_lshlrev_b32_e32 v152, 16, v203
	v_and_b32_e32 v153, 0xffff0000, v203
	v_pk_mul_f32 v[146:147], v[146:147], v[240:241] op_sel_hi:[1,0]
	v_pk_mul_f32 v[148:149], v[148:149], v[240:241] op_sel_hi:[1,0]
	v_pk_mul_f32 v[150:151], v[150:151], v[240:241] op_sel_hi:[1,0]
	v_pk_mul_f32 v[152:153], v[152:153], v[240:241] op_sel_hi:[1,0]
	v_min_f32_e32 v146, 0x42b80000, v146
	v_min_f32_e32 v147, 0x42b80000, v147
	v_min_f32_e32 v148, 0x42b80000, v148
	v_min_f32_e32 v149, 0x42b80000, v149
	v_min_f32_e32 v150, 0x42b80000, v150
	v_min_f32_e32 v151, 0x42b80000, v151
	v_min_f32_e32 v152, 0x42b80000, v152
	v_min_f32_e32 v153, 0x42b80000, v153
	v_exp_f32_e32 v146, v146
	v_exp_f32_e32 v147, v147
	v_exp_f32_e32 v148, v148
	v_exp_f32_e32 v149, v149
	v_exp_f32_e32 v150, v150
	v_exp_f32_e32 v151, v151
	v_exp_f32_e32 v152, v152
	v_exp_f32_e32 v153, v153
	s_nop 0
	v_add_f32_e32 v146, 1.0, v146
	v_add_f32_e32 v147, 1.0, v147
	v_add_f32_e32 v148, 1.0, v148
	v_add_f32_e32 v149, 1.0, v149
	v_add_f32_e32 v150, 1.0, v150
	v_add_f32_e32 v151, 1.0, v151
	v_add_f32_e32 v152, 1.0, v152
	v_add_f32_e32 v153, 1.0, v153
	v_rcp_f32_e32 v146, v146
	v_rcp_f32_e32 v147, v147
	v_rcp_f32_e32 v148, v148
	v_rcp_f32_e32 v149, v149
	v_rcp_f32_e32 v150, v150
	v_rcp_f32_e32 v151, v151
	v_rcp_f32_e32 v152, v152
	v_rcp_f32_e32 v153, v153
	s_nop 0
; DI float bflo(unsigned w) { return __uint_as_float(w << 16); }
; DI float bfhi(unsigned w) { return __uint_as_float(w & 0xffff0000u); }
; DI u32x4 pack8(f32x4 a, f32x4 b) { u32x4 w; w.x = pk2(a[0], a[1]); w.y = pk2(a[2], a[3]); w.z = pk2(b[0], b[1]); w.w = pk2(b[2], b[3]); return w; }
;     DI void operator()(Acc& acc, const Unit& u, int wr, int wc, int fr, int fq) const {
;     ...
;             for (int ai = 0; ai < 2; ++ai)
; #pragma unroll
;                 for (int m = 0; m < 4; ++m)
; #pragma unroll
;                     for (int bj = 0; bj < 2; ++bj) g[ai][m][bj] = *(const u32x4*)(base + (size_t)(ai * 128 + m * 16) * NPJ + u.k * 1024 + bj * 128);
; #pragma unroll
;             for (int ai = 0; ai < 2; ++ai)
; #pragma unroll
;                 for (int m = 0; m < 4; ++m)
; #pragma unroll
;                     for (int bj = 0; bj < 2; ++bj) { const u32x4 q = g[ai][m][bj]; f32x4& v0 = acc[ai][bj][m][0]; f32x4& v1 = acc[ai][bj][m][1];
;                         v0[0] *= bflo(q.x); v0[1] *= bfhi(q.x); v0[2] *= bflo(q.y); v0[3] *= bfhi(q.y); v1[0] *= bflo(q.z); v1[1] *= bfhi(q.z); v1[2] *= bflo(q.w); v1[3] *= bfhi(q.w); }
;     ...
;                     for (int bj = 0; bj < 2; ++bj) *(u32x4*)(base + (size_t)(ai * 128 + m * 16) * NPJ + bj * 128) = pack8(acc[ai][bj][m][0], acc[ai][bj][m][1]);
	v_pk_mul_f32 v[102:103], v[102:103], v[146:147]
	v_pk_mul_f32 v[104:105], v[104:105], v[148:149]
	v_pk_mul_f32 v[94:95], v[94:95], v[150:151]
	v_pk_mul_f32 v[96:97], v[96:97], v[152:153]
	v_cvt_pk_bf16_f32 v200, v102, v103
	v_cvt_pk_bf16_f32 v201, v104, v105
	v_cvt_pk_bf16_f32 v202, v94, v95
	v_cvt_pk_bf16_f32 v203, v96, v97
	v_lshlrev_b32_e32 v168, 16, v204
	v_and_b32_e32 v169, 0xffff0000, v204
	v_lshlrev_b32_e32 v178, 16, v205
	v_and_b32_e32 v179, 0xffff0000, v205
	v_lshlrev_b32_e32 v180, 16, v206
	v_and_b32_e32 v181, 0xffff0000, v206
	v_lshlrev_b32_e32 v244, 16, v207
	v_and_b32_e32 v245, 0xffff0000, v207
	v_pk_mul_f32 v[168:169], v[168:169], v[240:241] op_sel_hi:[1,0]
	v_pk_mul_f32 v[178:179], v[178:179], v[240:241] op_sel_hi:[1,0]
	v_pk_mul_f32 v[180:181], v[180:181], v[240:241] op_sel_hi:[1,0]
	v_pk_mul_f32 v[244:245], v[244:245], v[240:241] op_sel_hi:[1,0]
	v_min_f32_e32 v168, 0x42b80000, v168
	v_min_f32_e32 v169, 0x42b80000, v169
	v_min_f32_e32 v178, 0x42b80000, v178
	v_min_f32_e32 v179, 0x42b80000, v179
	v_min_f32_e32 v180, 0x42b80000, v180
	v_min_f32_e32 v181, 0x42b80000, v181
	v_min_f32_e32 v244, 0x42b80000, v244
	v_min_f32_e32 v245, 0x42b80000, v245
	v_exp_f32_e32 v168, v168
	v_exp_f32_e32 v169, v169
	v_exp_f32_e32 v178, v178
	v_exp_f32_e32 v179, v179
	v_exp_f32_e32 v180, v180
	v_exp_f32_e32 v181, v181
	v_exp_f32_e32 v244, v244
	v_exp_f32_e32 v245, v245
	s_nop 0
	v_add_f32_e32 v168, 1.0, v168
	v_add_f32_e32 v169, 1.0, v169
	v_add_f32_e32 v178, 1.0, v178
	v_add_f32_e32 v179, 1.0, v179
	v_add_f32_e32 v180, 1.0, v180
	v_add_f32_e32 v181, 1.0, v181
	v_add_f32_e32 v244, 1.0, v244
	v_add_f32_e32 v245, 1.0, v245
	v_rcp_f32_e32 v168, v168
	v_rcp_f32_e32 v169, v169
	v_rcp_f32_e32 v178, v178
	v_rcp_f32_e32 v179, v179
	v_rcp_f32_e32 v180, v180
	v_rcp_f32_e32 v181, v181
	v_rcp_f32_e32 v244, v244
	v_rcp_f32_e32 v245, v245
	s_nop 0
	v_pk_mul_f32 v[82:83], v[82:83], v[168:169]
	v_pk_mul_f32 v[84:85], v[84:85], v[178:179]
	v_pk_mul_f32 v[74:75], v[74:75], v[180:181]
	v_pk_mul_f32 v[76:77], v[76:77], v[244:245]
	v_cvt_pk_bf16_f32 v204, v82, v83
	v_cvt_pk_bf16_f32 v205, v84, v85
	v_cvt_pk_bf16_f32 v206, v74, v75
	v_cvt_pk_bf16_f32 v207, v76, v77
	global_store_dwordx4 v[134:135], v[200:203], off
	global_store_dwordx4 v[134:135], v[204:207], off offset:256
	s_waitcnt vmcnt(14)
	v_lshlrev_b32_e32 v146, 16, v208
	v_and_b32_e32 v147, 0xffff0000, v208
	v_lshlrev_b32_e32 v148, 16, v209
	v_and_b32_e32 v149, 0xffff0000, v209
	v_lshlrev_b32_e32 v150, 16, v210
	v_and_b32_e32 v151, 0xffff0000, v210
	v_lshlrev_b32_e32 v152, 16, v211
	v_and_b32_e32 v153, 0xffff0000, v211
	v_pk_mul_f32 v[146:147], v[146:147], v[240:241] op_sel_hi:[1,0]
	v_pk_mul_f32 v[148:149], v[148:149], v[240:241] op_sel_hi:[1,0]
	v_pk_mul_f32 v[150:151], v[150:151], v[240:241] op_sel_hi:[1,0]
	v_pk_mul_f32 v[152:153], v[152:153], v[240:241] op_sel_hi:[1,0]
	v_min_f32_e32 v146, 0x42b80000, v146
	v_min_f32_e32 v147, 0x42b80000, v147
	v_min_f32_e32 v148, 0x42b80000, v148
	v_min_f32_e32 v149, 0x42b80000, v149
	v_min_f32_e32 v150, 0x42b80000, v150
	v_min_f32_e32 v151, 0x42b80000, v151
	v_min_f32_e32 v152, 0x42b80000, v152
	v_min_f32_e32 v153, 0x42b80000, v153
	v_exp_f32_e32 v146, v146
	v_exp_f32_e32 v147, v147
	v_exp_f32_e32 v148, v148
	v_exp_f32_e32 v149, v149
	v_exp_f32_e32 v150, v150
	v_exp_f32_e32 v151, v151
	v_exp_f32_e32 v152, v152
	v_exp_f32_e32 v153, v153
	s_nop 0
	v_add_f32_e32 v146, 1.0, v146
	v_add_f32_e32 v147, 1.0, v147
	v_add_f32_e32 v148, 1.0, v148
	v_add_f32_e32 v149, 1.0, v149
	v_add_f32_e32 v150, 1.0, v150
	v_add_f32_e32 v151, 1.0, v151
	v_add_f32_e32 v152, 1.0, v152
	v_add_f32_e32 v153, 1.0, v153
	v_rcp_f32_e32 v146, v146
	v_rcp_f32_e32 v147, v147
	v_rcp_f32_e32 v148, v148
	v_rcp_f32_e32 v149, v149
	v_rcp_f32_e32 v150, v150
	v_rcp_f32_e32 v151, v151
	v_rcp_f32_e32 v152, v152
	v_rcp_f32_e32 v153, v153
	s_nop 0
	v_pk_mul_f32 v[86:87], v[86:87], v[146:147]
	v_pk_mul_f32 v[88:89], v[88:89], v[148:149]
	v_pk_mul_f32 v[78:79], v[78:79], v[150:151]
	v_pk_mul_f32 v[80:81], v[80:81], v[152:153]
	v_cvt_pk_bf16_f32 v208, v86, v87
	v_cvt_pk_bf16_f32 v209, v88, v89
	v_cvt_pk_bf16_f32 v210, v78, v79
	v_cvt_pk_bf16_f32 v211, v80, v81
	v_lshlrev_b32_e32 v168, 16, v212
	v_and_b32_e32 v169, 0xffff0000, v212
	v_lshlrev_b32_e32 v178, 16, v213
	v_and_b32_e32 v179, 0xffff0000, v213
	v_lshlrev_b32_e32 v180, 16, v214
	v_and_b32_e32 v181, 0xffff0000, v214
	v_lshlrev_b32_e32 v244, 16, v215
	v_and_b32_e32 v245, 0xffff0000, v215
	v_pk_mul_f32 v[168:169], v[168:169], v[240:241] op_sel_hi:[1,0]
	v_pk_mul_f32 v[178:179], v[178:179], v[240:241] op_sel_hi:[1,0]
	v_pk_mul_f32 v[180:181], v[180:181], v[240:241] op_sel_hi:[1,0]
	v_pk_mul_f32 v[244:245], v[244:245], v[240:241] op_sel_hi:[1,0]
	v_min_f32_e32 v168, 0x42b80000, v168
	v_min_f32_e32 v169, 0x42b80000, v169
	v_min_f32_e32 v178, 0x42b80000, v178
	v_min_f32_e32 v179, 0x42b80000, v179
	v_min_f32_e32 v180, 0x42b80000, v180
	v_min_f32_e32 v181, 0x42b80000, v181
	v_min_f32_e32 v244, 0x42b80000, v244
	v_min_f32_e32 v245, 0x42b80000, v245
	v_exp_f32_e32 v168, v168
	v_exp_f32_e32 v169, v169
	v_exp_f32_e32 v178, v178
	v_exp_f32_e32 v179, v179
	v_exp_f32_e32 v180, v180
	v_exp_f32_e32 v181, v181
	v_exp_f32_e32 v244, v244
	v_exp_f32_e32 v245, v245
	s_nop 0
	v_add_f32_e32 v168, 1.0, v168
	v_add_f32_e32 v169, 1.0, v169
	v_add_f32_e32 v178, 1.0, v178
	v_add_f32_e32 v179, 1.0, v179
	v_add_f32_e32 v180, 1.0, v180
	v_add_f32_e32 v181, 1.0, v181
	v_add_f32_e32 v244, 1.0, v244
	v_add_f32_e32 v245, 1.0, v245
	v_rcp_f32_e32 v168, v168
	v_rcp_f32_e32 v169, v169
	v_rcp_f32_e32 v178, v178
	v_rcp_f32_e32 v179, v179
	v_rcp_f32_e32 v180, v180
	v_rcp_f32_e32 v181, v181
	v_rcp_f32_e32 v244, v244
	v_rcp_f32_e32 v245, v245
	s_nop 0
	v_pk_mul_f32 v[70:71], v[70:71], v[168:169]
	v_pk_mul_f32 v[72:73], v[72:73], v[178:179]
	v_pk_mul_f32 v[66:67], v[66:67], v[180:181]
	v_pk_mul_f32 v[68:69], v[68:69], v[244:245]
	v_cvt_pk_bf16_f32 v212, v70, v71
	v_cvt_pk_bf16_f32 v213, v72, v73
	v_cvt_pk_bf16_f32 v214, v66, v67
	v_cvt_pk_bf16_f32 v215, v68, v69
	global_store_dwordx4 v[136:137], v[208:211], off
	global_store_dwordx4 v[136:137], v[212:215], off offset:256
	s_waitcnt vmcnt(14)
; DI float bflo(unsigned w) { return __uint_as_float(w << 16); }
; DI float bfhi(unsigned w) { return __uint_as_float(w & 0xffff0000u); }
;     DI void operator()(Acc& acc, const Unit& u, int wr, int wc, int fr, int fq) const {
;     ...
;         bf16_t* base = proj + (size_t)(u.pm * 256 + wr * 64 + fr) * NPJ + C_GL + u.pn * 256 + wc * 32 + fq * 8;
;         {
;             u32x4 g[2][4][2];
; #pragma unroll
;             for (int ai = 0; ai < 2; ++ai)
; #pragma unroll
;                 for (int m = 0; m < 4; ++m)
; #pragma unroll
;                     for (int bj = 0; bj < 2; ++bj) g[ai][m][bj] = *(const u32x4*)(base + (size_t)(ai * 128 + m * 16) * NPJ + u.k * 1024 + bj * 128);
; #pragma unroll
;             for (int ai = 0; ai < 2; ++ai)
; #pragma unroll
;                 for (int m = 0; m < 4; ++m)
; #pragma unroll
;                     for (int bj = 0; bj < 2; ++bj) { const u32x4 q = g[ai][m][bj]; f32x4& v0 = acc[ai][bj][m][0]; f32x4& v1 = acc[ai][bj][m][1];
;                         v0[0] *= bflo(q.x); v0[1] *= bfhi(q.x); v0[2] *= bflo(q.y); v0[3] *= bfhi(q.y); v1[0] *= bflo(q.z); v1[1] *= bfhi(q.z); v1[2] *= bflo(q.w); v1[3] *= bfhi(q.w); }
;         }
;         if (u.k > 0) {
;             u32x4 g[2][4][2];
; #pragma unroll
;             for (int ai = 0; ai < 2; ++ai)
; #pragma unroll
;                 for (int m = 0; m < 4; ++m)
; #pragma unroll
;                     for (int bj = 0; bj < 2; ++bj) g[ai][m][bj] = *(const u32x4*)(base + (size_t)(ai * 128 + m * 16) * NPJ + bj * 128);
; #pragma unroll
;             for (int ai = 0; ai < 2; ++ai)
; #pragma unroll
;                 for (int m = 0; m < 4; ++m)
; #pragma unroll
;                     for (int bj = 0; bj < 2; ++bj) { const u32x4 q = g[ai][m][bj]; f32x4& v0 = acc[ai][bj][m][0]; f32x4& v1 = acc[ai][bj][m][1];
;                         v0[0] += bflo(q.x); v0[1] += bfhi(q.x); v0[2] += bflo(q.y); v0[3] += bfhi(q.y); v1[0] += bflo(q.z); v1[1] += bfhi(q.z); v1[2] += bflo(q.w); v1[3] += bfhi(q.w); }
;         }
;         if (!dry) {
; #pragma unroll
;             for (int ai = 0; ai < 2; ++ai)
; #pragma unroll
;                 for (int m = 0; m < 4; ++m)
; #pragma unroll
;                     for (int bj = 0; bj < 2; ++bj) *(u32x4*)(base + (size_t)(ai * 128 + m * 16) * NPJ + bj * 128) = pack8(acc[ai][bj][m][0], acc[ai][bj][m][1]);
	v_lshlrev_b32_e32 v146, 16, v216
	v_and_b32_e32 v147, 0xffff0000, v216
	v_lshlrev_b32_e32 v148, 16, v217
	v_and_b32_e32 v149, 0xffff0000, v217
	v_lshlrev_b32_e32 v150, 16, v218
	v_and_b32_e32 v151, 0xffff0000, v218
	v_lshlrev_b32_e32 v152, 16, v219
	v_and_b32_e32 v153, 0xffff0000, v219
	v_pk_mul_f32 v[146:147], v[146:147], v[240:241] op_sel_hi:[1,0]
	v_pk_mul_f32 v[148:149], v[148:149], v[240:241] op_sel_hi:[1,0]
	v_pk_mul_f32 v[150:151], v[150:151], v[240:241] op_sel_hi:[1,0]
	v_pk_mul_f32 v[152:153], v[152:153], v[240:241] op_sel_hi:[1,0]
	v_min_f32_e32 v146, 0x42b80000, v146
	v_min_f32_e32 v147, 0x42b80000, v147
	v_min_f32_e32 v148, 0x42b80000, v148
	v_min_f32_e32 v149, 0x42b80000, v149
	v_min_f32_e32 v150, 0x42b80000, v150
	v_min_f32_e32 v151, 0x42b80000, v151
	v_min_f32_e32 v152, 0x42b80000, v152
	v_min_f32_e32 v153, 0x42b80000, v153
	v_exp_f32_e32 v146, v146
	v_exp_f32_e32 v147, v147
	v_exp_f32_e32 v148, v148
	v_exp_f32_e32 v149, v149
	v_exp_f32_e32 v150, v150
	v_exp_f32_e32 v151, v151
	v_exp_f32_e32 v152, v152
	v_exp_f32_e32 v153, v153
	s_nop 0
	v_add_f32_e32 v146, 1.0, v146
	v_add_f32_e32 v147, 1.0, v147
	v_add_f32_e32 v148, 1.0, v148
	v_add_f32_e32 v149, 1.0, v149
	v_add_f32_e32 v150, 1.0, v150
	v_add_f32_e32 v151, 1.0, v151
	v_add_f32_e32 v152, 1.0, v152
	v_add_f32_e32 v153, 1.0, v153
	v_rcp_f32_e32 v146, v146
	v_rcp_f32_e32 v147, v147
	v_rcp_f32_e32 v148, v148
	v_rcp_f32_e32 v149, v149
	v_rcp_f32_e32 v150, v150
	v_rcp_f32_e32 v151, v151
	v_rcp_f32_e32 v152, v152
	v_rcp_f32_e32 v153, v153
	s_nop 0
	v_pk_mul_f32 v[62:63], v[62:63], v[146:147]
	v_pk_mul_f32 v[64:65], v[64:65], v[148:149]
	v_pk_mul_f32 v[58:59], v[58:59], v[150:151]
	v_pk_mul_f32 v[60:61], v[60:61], v[152:153]
	v_cvt_pk_bf16_f32 v216, v62, v63
	v_cvt_pk_bf16_f32 v217, v64, v65
	v_cvt_pk_bf16_f32 v218, v58, v59
	v_cvt_pk_bf16_f32 v219, v60, v61
	v_lshlrev_b32_e32 v168, 16, v220
	v_and_b32_e32 v169, 0xffff0000, v220
	v_lshlrev_b32_e32 v178, 16, v221
	v_and_b32_e32 v179, 0xffff0000, v221
	v_lshlrev_b32_e32 v180, 16, v222
	v_and_b32_e32 v181, 0xffff0000, v222
	v_lshlrev_b32_e32 v244, 16, v223
	v_and_b32_e32 v245, 0xffff0000, v223
	v_pk_mul_f32 v[168:169], v[168:169], v[240:241] op_sel_hi:[1,0]
	v_pk_mul_f32 v[178:179], v[178:179], v[240:241] op_sel_hi:[1,0]
	v_pk_mul_f32 v[180:181], v[180:181], v[240:241] op_sel_hi:[1,0]
	v_pk_mul_f32 v[244:245], v[244:245], v[240:241] op_sel_hi:[1,0]
	v_min_f32_e32 v168, 0x42b80000, v168
	v_min_f32_e32 v169, 0x42b80000, v169
	v_min_f32_e32 v178, 0x42b80000, v178
	v_min_f32_e32 v179, 0x42b80000, v179
	v_min_f32_e32 v180, 0x42b80000, v180
	v_min_f32_e32 v181, 0x42b80000, v181
	v_min_f32_e32 v244, 0x42b80000, v244
	v_min_f32_e32 v245, 0x42b80000, v245
	v_exp_f32_e32 v168, v168
	v_exp_f32_e32 v169, v169
	v_exp_f32_e32 v178, v178
	v_exp_f32_e32 v179, v179
	v_exp_f32_e32 v180, v180
	v_exp_f32_e32 v181, v181
	v_exp_f32_e32 v244, v244
	v_exp_f32_e32 v245, v245
	s_nop 0
	v_add_f32_e32 v168, 1.0, v168
	v_add_f32_e32 v169, 1.0, v169
	v_add_f32_e32 v178, 1.0, v178
	v_add_f32_e32 v179, 1.0, v179
	v_add_f32_e32 v180, 1.0, v180
	v_add_f32_e32 v181, 1.0, v181
	v_add_f32_e32 v244, 1.0, v244
	v_add_f32_e32 v245, 1.0, v245
	v_rcp_f32_e32 v168, v168
	v_rcp_f32_e32 v169, v169
	v_rcp_f32_e32 v178, v178
	v_rcp_f32_e32 v179, v179
	v_rcp_f32_e32 v180, v180
	v_rcp_f32_e32 v181, v181
	v_rcp_f32_e32 v244, v244
	v_rcp_f32_e32 v245, v245
	s_nop 0
	v_pk_mul_f32 v[50:51], v[50:51], v[168:169]
	v_pk_mul_f32 v[52:53], v[52:53], v[178:179]
	v_pk_mul_f32 v[42:43], v[42:43], v[180:181]
	v_pk_mul_f32 v[44:45], v[44:45], v[244:245]
	v_cvt_pk_bf16_f32 v220, v50, v51
	v_cvt_pk_bf16_f32 v221, v52, v53
	v_cvt_pk_bf16_f32 v222, v42, v43
	v_cvt_pk_bf16_f32 v223, v44, v45
	global_store_dwordx4 v[138:139], v[216:219], off
	global_store_dwordx4 v[138:139], v[220:223], off offset:256
	s_waitcnt vmcnt(14)
	v_lshlrev_b32_e32 v146, 16, v224
	v_and_b32_e32 v147, 0xffff0000, v224
	v_lshlrev_b32_e32 v148, 16, v225
	v_and_b32_e32 v149, 0xffff0000, v225
	v_lshlrev_b32_e32 v150, 16, v226
	v_and_b32_e32 v151, 0xffff0000, v226
	v_lshlrev_b32_e32 v152, 16, v227
	v_and_b32_e32 v153, 0xffff0000, v227
	v_pk_mul_f32 v[146:147], v[146:147], v[240:241] op_sel_hi:[1,0]
	v_pk_mul_f32 v[148:149], v[148:149], v[240:241] op_sel_hi:[1,0]
	v_pk_mul_f32 v[150:151], v[150:151], v[240:241] op_sel_hi:[1,0]
	v_pk_mul_f32 v[152:153], v[152:153], v[240:241] op_sel_hi:[1,0]
	v_min_f32_e32 v146, 0x42b80000, v146
	v_min_f32_e32 v147, 0x42b80000, v147
	v_min_f32_e32 v148, 0x42b80000, v148
	v_min_f32_e32 v149, 0x42b80000, v149
	v_min_f32_e32 v150, 0x42b80000, v150
	v_min_f32_e32 v151, 0x42b80000, v151
	v_min_f32_e32 v152, 0x42b80000, v152
	v_min_f32_e32 v153, 0x42b80000, v153
	v_exp_f32_e32 v146, v146
	v_exp_f32_e32 v147, v147
	v_exp_f32_e32 v148, v148
	v_exp_f32_e32 v149, v149
	v_exp_f32_e32 v150, v150
	v_exp_f32_e32 v151, v151
	v_exp_f32_e32 v152, v152
	v_exp_f32_e32 v153, v153
	s_nop 0
	v_add_f32_e32 v146, 1.0, v146
	v_add_f32_e32 v147, 1.0, v147
	v_add_f32_e32 v148, 1.0, v148
	v_add_f32_e32 v149, 1.0, v149
	v_add_f32_e32 v150, 1.0, v150
	v_add_f32_e32 v151, 1.0, v151
	v_add_f32_e32 v152, 1.0, v152
	v_add_f32_e32 v153, 1.0, v153
	v_rcp_f32_e32 v146, v146
	v_rcp_f32_e32 v147, v147
	v_rcp_f32_e32 v148, v148
	v_rcp_f32_e32 v149, v149
	v_rcp_f32_e32 v150, v150
	v_rcp_f32_e32 v151, v151
	v_rcp_f32_e32 v152, v152
	v_rcp_f32_e32 v153, v153
	s_nop 0
	v_pk_mul_f32 v[54:55], v[54:55], v[146:147]
	v_pk_mul_f32 v[56:57], v[56:57], v[148:149]
	v_pk_mul_f32 v[46:47], v[46:47], v[150:151]
	v_pk_mul_f32 v[48:49], v[48:49], v[152:153]
	v_cvt_pk_bf16_f32 v224, v54, v55
	v_cvt_pk_bf16_f32 v225, v56, v57
	v_cvt_pk_bf16_f32 v226, v46, v47
; DI float bflo(unsigned w) { return __uint_as_float(w << 16); }
; DI float bfhi(unsigned w) { return __uint_as_float(w & 0xffff0000u); }
;     DI void operator()(Acc& acc, const Unit& u, int wr, int wc, int fr, int fq) const {
;     ...
;         bf16_t* base = proj + (size_t)(u.pm * 256 + wr * 64 + fr) * NPJ + C_GL + u.pn * 256 + wc * 32 + fq * 8;
;         {
;             u32x4 g[2][4][2];
; #pragma unroll
;             for (int ai = 0; ai < 2; ++ai)
; #pragma unroll
;                 for (int m = 0; m < 4; ++m)
; #pragma unroll
;                     for (int bj = 0; bj < 2; ++bj) g[ai][m][bj] = *(const u32x4*)(base + (size_t)(ai * 128 + m * 16) * NPJ + u.k * 1024 + bj * 128);
; #pragma unroll
;             for (int ai = 0; ai < 2; ++ai)
; #pragma unroll
;                 for (int m = 0; m < 4; ++m)
; #pragma unroll
;                     for (int bj = 0; bj < 2; ++bj) { const u32x4 q = g[ai][m][bj]; f32x4& v0 = acc[ai][bj][m][0]; f32x4& v1 = acc[ai][bj][m][1];
;                         v0[0] *= bflo(q.x); v0[1] *= bfhi(q.x); v0[2] *= bflo(q.y); v0[3] *= bfhi(q.y); v1[0] *= bflo(q.z); v1[1] *= bfhi(q.z); v1[2] *= bflo(q.w); v1[3] *= bfhi(q.w); }
;         }
;         if (u.k > 0) {
;             u32x4 g[2][4][2];
; #pragma unroll
;             for (int ai = 0; ai < 2; ++ai)
; #pragma unroll
;                 for (int m = 0; m < 4; ++m)
; #pragma unroll
;                     for (int bj = 0; bj < 2; ++bj) g[ai][m][bj] = *(const u32x4*)(base + (size_t)(ai * 128 + m * 16) * NPJ + bj * 128);
; #pragma unroll
;             for (int ai = 0; ai < 2; ++ai)
; #pragma unroll
;                 for (int m = 0; m < 4; ++m)
; #pragma unroll
;                     for (int bj = 0; bj < 2; ++bj) { const u32x4 q = g[ai][m][bj]; f32x4& v0 = acc[ai][bj][m][0]; f32x4& v1 = acc[ai][bj][m][1];
;                         v0[0] += bflo(q.x); v0[1] += bfhi(q.x); v0[2] += bflo(q.y); v0[3] += bfhi(q.y); v1[0] += bflo(q.z); v1[1] += bfhi(q.z); v1[2] += bflo(q.w); v1[3] += bfhi(q.w); }
;         }
;         if (!dry) {
; #pragma unroll
;             for (int ai = 0; ai < 2; ++ai)
; #pragma unroll
;                 for (int m = 0; m < 4; ++m)
; #pragma unroll
;                     for (int bj = 0; bj < 2; ++bj) *(u32x4*)(base + (size_t)(ai * 128 + m * 16) * NPJ + bj * 128) = pack8(acc[ai][bj][m][0], acc[ai][bj][m][1]);
	v_cvt_pk_bf16_f32 v227, v48, v49
	v_lshlrev_b32_e32 v168, 16, v228
	v_and_b32_e32 v169, 0xffff0000, v228
	v_lshlrev_b32_e32 v178, 16, v229
	v_and_b32_e32 v179, 0xffff0000, v229
	v_lshlrev_b32_e32 v180, 16, v230
	v_and_b32_e32 v181, 0xffff0000, v230
	v_lshlrev_b32_e32 v244, 16, v231
	v_and_b32_e32 v245, 0xffff0000, v231
	v_pk_mul_f32 v[168:169], v[168:169], v[240:241] op_sel_hi:[1,0]
	v_pk_mul_f32 v[178:179], v[178:179], v[240:241] op_sel_hi:[1,0]
	v_pk_mul_f32 v[180:181], v[180:181], v[240:241] op_sel_hi:[1,0]
	v_pk_mul_f32 v[244:245], v[244:245], v[240:241] op_sel_hi:[1,0]
	v_min_f32_e32 v168, 0x42b80000, v168
	v_min_f32_e32 v169, 0x42b80000, v169
	v_min_f32_e32 v178, 0x42b80000, v178
	v_min_f32_e32 v179, 0x42b80000, v179
	v_min_f32_e32 v180, 0x42b80000, v180
	v_min_f32_e32 v181, 0x42b80000, v181
	v_min_f32_e32 v244, 0x42b80000, v244
	v_min_f32_e32 v245, 0x42b80000, v245
	v_exp_f32_e32 v168, v168
	v_exp_f32_e32 v169, v169
	v_exp_f32_e32 v178, v178
	v_exp_f32_e32 v179, v179
	v_exp_f32_e32 v180, v180
	v_exp_f32_e32 v181, v181
	v_exp_f32_e32 v244, v244
	v_exp_f32_e32 v245, v245
	s_nop 0
	v_add_f32_e32 v168, 1.0, v168
	v_add_f32_e32 v169, 1.0, v169
	v_add_f32_e32 v178, 1.0, v178
	v_add_f32_e32 v179, 1.0, v179
	v_add_f32_e32 v180, 1.0, v180
	v_add_f32_e32 v181, 1.0, v181
	v_add_f32_e32 v244, 1.0, v244
	v_add_f32_e32 v245, 1.0, v245
	v_rcp_f32_e32 v168, v168
	v_rcp_f32_e32 v169, v169
	v_rcp_f32_e32 v178, v178
	v_rcp_f32_e32 v179, v179
	v_rcp_f32_e32 v180, v180
	v_rcp_f32_e32 v181, v181
	v_rcp_f32_e32 v244, v244
	v_rcp_f32_e32 v245, v245
	s_nop 0
	v_pk_mul_f32 v[34:35], v[34:35], v[168:169]
	v_pk_mul_f32 v[36:37], v[36:37], v[178:179]
	v_pk_mul_f32 v[26:27], v[26:27], v[180:181]
	v_pk_mul_f32 v[28:29], v[28:29], v[244:245]
	v_cvt_pk_bf16_f32 v228, v34, v35
	v_cvt_pk_bf16_f32 v229, v36, v37
	v_cvt_pk_bf16_f32 v230, v26, v27
	v_cvt_pk_bf16_f32 v231, v28, v29
	global_store_dwordx4 v[140:141], v[224:227], off
	global_store_dwordx4 v[140:141], v[228:231], off offset:256
	s_waitcnt vmcnt(12)
	v_lshlrev_b32_e32 v146, 16, v184
	v_and_b32_e32 v147, 0xffff0000, v184
	v_lshlrev_b32_e32 v148, 16, v185
	v_and_b32_e32 v149, 0xffff0000, v185
	v_lshlrev_b32_e32 v150, 16, v186
	v_and_b32_e32 v151, 0xffff0000, v186
	v_lshlrev_b32_e32 v152, 16, v187
	v_and_b32_e32 v153, 0xffff0000, v187
	v_pk_mul_f32 v[146:147], v[146:147], v[240:241] op_sel_hi:[1,0]
	v_pk_mul_f32 v[148:149], v[148:149], v[240:241] op_sel_hi:[1,0]
	v_pk_mul_f32 v[150:151], v[150:151], v[240:241] op_sel_hi:[1,0]
	v_pk_mul_f32 v[152:153], v[152:153], v[240:241] op_sel_hi:[1,0]
	v_min_f32_e32 v146, 0x42b80000, v146
	v_min_f32_e32 v147, 0x42b80000, v147
	v_min_f32_e32 v148, 0x42b80000, v148
	v_min_f32_e32 v149, 0x42b80000, v149
	v_min_f32_e32 v150, 0x42b80000, v150
	v_min_f32_e32 v151, 0x42b80000, v151
	v_min_f32_e32 v152, 0x42b80000, v152
	v_min_f32_e32 v153, 0x42b80000, v153
	v_exp_f32_e32 v146, v146
	v_exp_f32_e32 v147, v147
	v_exp_f32_e32 v148, v148
	v_exp_f32_e32 v149, v149
	v_exp_f32_e32 v150, v150
	v_exp_f32_e32 v151, v151
	v_exp_f32_e32 v152, v152
	v_exp_f32_e32 v153, v153
	s_nop 0
	v_add_f32_e32 v146, 1.0, v146
	v_add_f32_e32 v147, 1.0, v147
	v_add_f32_e32 v148, 1.0, v148
	v_add_f32_e32 v149, 1.0, v149
	v_add_f32_e32 v150, 1.0, v150
	v_add_f32_e32 v151, 1.0, v151
	v_add_f32_e32 v152, 1.0, v152
	v_add_f32_e32 v153, 1.0, v153
	v_rcp_f32_e32 v146, v146
	v_rcp_f32_e32 v147, v147
	v_rcp_f32_e32 v148, v148
	v_rcp_f32_e32 v149, v149
	v_rcp_f32_e32 v150, v150
	v_rcp_f32_e32 v151, v151
	v_rcp_f32_e32 v152, v152
	v_rcp_f32_e32 v153, v153
	s_nop 0
	v_pk_mul_f32 v[38:39], v[38:39], v[146:147]
	v_pk_mul_f32 v[40:41], v[40:41], v[148:149]
	v_pk_mul_f32 v[30:31], v[30:31], v[150:151]
	v_pk_mul_f32 v[32:33], v[32:33], v[152:153]
	v_cvt_pk_bf16_f32 v184, v38, v39
	v_cvt_pk_bf16_f32 v185, v40, v41
	v_cvt_pk_bf16_f32 v186, v30, v31
	v_cvt_pk_bf16_f32 v187, v32, v33
	v_lshlrev_b32_e32 v168, 16, v188
	v_and_b32_e32 v169, 0xffff0000, v188
	v_lshlrev_b32_e32 v178, 16, v189
	v_and_b32_e32 v179, 0xffff0000, v189
	v_lshlrev_b32_e32 v180, 16, v190
	v_and_b32_e32 v181, 0xffff0000, v190
	v_lshlrev_b32_e32 v244, 16, v191
	v_and_b32_e32 v245, 0xffff0000, v191
	v_pk_mul_f32 v[168:169], v[168:169], v[240:241] op_sel_hi:[1,0]
	v_pk_mul_f32 v[178:179], v[178:179], v[240:241] op_sel_hi:[1,0]
	v_pk_mul_f32 v[180:181], v[180:181], v[240:241] op_sel_hi:[1,0]
	v_pk_mul_f32 v[244:245], v[244:245], v[240:241] op_sel_hi:[1,0]
	v_min_f32_e32 v168, 0x42b80000, v168
	v_min_f32_e32 v169, 0x42b80000, v169
	v_min_f32_e32 v178, 0x42b80000, v178
	v_min_f32_e32 v179, 0x42b80000, v179
	v_min_f32_e32 v180, 0x42b80000, v180
	v_min_f32_e32 v181, 0x42b80000, v181
	v_min_f32_e32 v244, 0x42b80000, v244
	v_min_f32_e32 v245, 0x42b80000, v245
	v_exp_f32_e32 v168, v168
	v_exp_f32_e32 v169, v169
	v_exp_f32_e32 v178, v178
	v_exp_f32_e32 v179, v179
	v_exp_f32_e32 v180, v180
	v_exp_f32_e32 v181, v181
	v_exp_f32_e32 v244, v244
	v_exp_f32_e32 v245, v245
	s_nop 0
	v_add_f32_e32 v168, 1.0, v168
	v_add_f32_e32 v169, 1.0, v169
	v_add_f32_e32 v178, 1.0, v178
	v_add_f32_e32 v179, 1.0, v179
	v_add_f32_e32 v180, 1.0, v180
	v_add_f32_e32 v181, 1.0, v181
	v_add_f32_e32 v244, 1.0, v244
	v_add_f32_e32 v245, 1.0, v245
	v_rcp_f32_e32 v168, v168
	v_rcp_f32_e32 v169, v169
	v_rcp_f32_e32 v178, v178
	v_rcp_f32_e32 v179, v179
	v_rcp_f32_e32 v180, v180
	v_rcp_f32_e32 v181, v181
	v_rcp_f32_e32 v244, v244
	v_rcp_f32_e32 v245, v245
	s_nop 0
	v_pk_mul_f32 v[18:19], v[18:19], v[168:169]
	v_pk_mul_f32 v[20:21], v[20:21], v[178:179]
	v_pk_mul_f32 v[10:11], v[10:11], v[180:181]
	v_pk_mul_f32 v[12:13], v[12:13], v[244:245]
	v_cvt_pk_bf16_f32 v188, v18, v19
	v_cvt_pk_bf16_f32 v189, v20, v21
	v_cvt_pk_bf16_f32 v190, v10, v11
	v_cvt_pk_bf16_f32 v191, v12, v13
	global_store_dwordx4 v[142:143], v[184:187], off
	global_store_dwordx4 v[142:143], v[188:191], off offset:256
	s_waitcnt vmcnt(10)
; DI float bflo(unsigned w) { return __uint_as_float(w << 16); }
; DI float bfhi(unsigned w) { return __uint_as_float(w & 0xffff0000u); }
;     DI void operator()(Acc& acc, const Unit& u, int wr, int wc, int fr, int fq) const {
;     ...
;         bf16_t* base = proj + (size_t)(u.pm * 256 + wr * 64 + fr) * NPJ + C_GL + u.pn * 256 + wc * 32 + fq * 8;
;         {
;             u32x4 g[2][4][2];
; #pragma unroll
;             for (int ai = 0; ai < 2; ++ai)
; #pragma unroll
;                 for (int m = 0; m < 4; ++m)
; #pragma unroll
;                     for (int bj = 0; bj < 2; ++bj) g[ai][m][bj] = *(const u32x4*)(base + (size_t)(ai * 128 + m * 16) * NPJ + u.k * 1024 + bj * 128);
; #pragma unroll
;             for (int ai = 0; ai < 2; ++ai)
; #pragma unroll
;                 for (int m = 0; m < 4; ++m)
; #pragma unroll
;                     for (int bj = 0; bj < 2; ++bj) { const u32x4 q = g[ai][m][bj]; f32x4& v0 = acc[ai][bj][m][0]; f32x4& v1 = acc[ai][bj][m][1];
;                         v0[0] *= bflo(q.x); v0[1] *= bfhi(q.x); v0[2] *= bflo(q.y); v0[3] *= bfhi(q.y); v1[0] *= bflo(q.z); v1[1] *= bfhi(q.z); v1[2] *= bflo(q.w); v1[3] *= bfhi(q.w); }
;         }
;         if (u.k > 0) {
;             u32x4 g[2][4][2];
; #pragma unroll
;             for (int ai = 0; ai < 2; ++ai)
; #pragma unroll
;                 for (int m = 0; m < 4; ++m)
; #pragma unroll
;                     for (int bj = 0; bj < 2; ++bj) g[ai][m][bj] = *(const u32x4*)(base + (size_t)(ai * 128 + m * 16) * NPJ + bj * 128);
; #pragma unroll
;             for (int ai = 0; ai < 2; ++ai)
; #pragma unroll
;                 for (int m = 0; m < 4; ++m)
; #pragma unroll
;                     for (int bj = 0; bj < 2; ++bj) { const u32x4 q = g[ai][m][bj]; f32x4& v0 = acc[ai][bj][m][0]; f32x4& v1 = acc[ai][bj][m][1];
;                         v0[0] += bflo(q.x); v0[1] += bfhi(q.x); v0[2] += bflo(q.y); v0[3] += bfhi(q.y); v1[0] += bflo(q.z); v1[1] += bfhi(q.z); v1[2] += bflo(q.w); v1[3] += bfhi(q.w); }
;         }
;         if (!dry) {
; #pragma unroll
;             for (int ai = 0; ai < 2; ++ai)
; #pragma unroll
;                 for (int m = 0; m < 4; ++m)
; #pragma unroll
;                     for (int bj = 0; bj < 2; ++bj) *(u32x4*)(base + (size_t)(ai * 128 + m * 16) * NPJ + bj * 128) = pack8(acc[ai][bj][m][0], acc[ai][bj][m][1]);
	v_lshlrev_b32_e32 v146, 16, v192
	v_and_b32_e32 v147, 0xffff0000, v192
	v_lshlrev_b32_e32 v148, 16, v193
	v_and_b32_e32 v149, 0xffff0000, v193
	v_lshlrev_b32_e32 v150, 16, v194
	v_and_b32_e32 v151, 0xffff0000, v194
	v_lshlrev_b32_e32 v152, 16, v195
	v_and_b32_e32 v153, 0xffff0000, v195
	v_pk_mul_f32 v[146:147], v[146:147], v[240:241] op_sel_hi:[1,0]
	v_pk_mul_f32 v[148:149], v[148:149], v[240:241] op_sel_hi:[1,0]
	v_pk_mul_f32 v[150:151], v[150:151], v[240:241] op_sel_hi:[1,0]
	v_pk_mul_f32 v[152:153], v[152:153], v[240:241] op_sel_hi:[1,0]
	v_min_f32_e32 v146, 0x42b80000, v146
	v_min_f32_e32 v147, 0x42b80000, v147
	v_min_f32_e32 v148, 0x42b80000, v148
	v_min_f32_e32 v149, 0x42b80000, v149
	v_min_f32_e32 v150, 0x42b80000, v150
	v_min_f32_e32 v151, 0x42b80000, v151
	v_min_f32_e32 v152, 0x42b80000, v152
	v_min_f32_e32 v153, 0x42b80000, v153
	v_exp_f32_e32 v146, v146
	v_exp_f32_e32 v147, v147
	v_exp_f32_e32 v148, v148
	v_exp_f32_e32 v149, v149
	v_exp_f32_e32 v150, v150
	v_exp_f32_e32 v151, v151
	v_exp_f32_e32 v152, v152
	v_exp_f32_e32 v153, v153
	s_nop 0
	v_add_f32_e32 v146, 1.0, v146
	v_add_f32_e32 v147, 1.0, v147
	v_add_f32_e32 v148, 1.0, v148
	v_add_f32_e32 v149, 1.0, v149
	v_add_f32_e32 v150, 1.0, v150
	v_add_f32_e32 v151, 1.0, v151
	v_add_f32_e32 v152, 1.0, v152
	v_add_f32_e32 v153, 1.0, v153
	v_rcp_f32_e32 v146, v146
	v_rcp_f32_e32 v147, v147
	v_rcp_f32_e32 v148, v148
	v_rcp_f32_e32 v149, v149
	v_rcp_f32_e32 v150, v150
	v_rcp_f32_e32 v151, v151
	v_rcp_f32_e32 v152, v152
	v_rcp_f32_e32 v153, v153
	s_nop 0
	v_pk_mul_f32 v[22:23], v[22:23], v[146:147]
	v_pk_mul_f32 v[24:25], v[24:25], v[148:149]
	v_pk_mul_f32 v[14:15], v[14:15], v[150:151]
	v_pk_mul_f32 v[16:17], v[16:17], v[152:153]
	v_cvt_pk_bf16_f32 v192, v22, v23
	v_cvt_pk_bf16_f32 v193, v24, v25
	v_cvt_pk_bf16_f32 v194, v14, v15
	v_cvt_pk_bf16_f32 v195, v16, v17
	v_lshlrev_b32_e32 v168, 16, v196
	v_and_b32_e32 v169, 0xffff0000, v196
	v_lshlrev_b32_e32 v178, 16, v197
	v_and_b32_e32 v179, 0xffff0000, v197
	v_lshlrev_b32_e32 v180, 16, v198
	v_and_b32_e32 v181, 0xffff0000, v198
	v_lshlrev_b32_e32 v244, 16, v199
	v_and_b32_e32 v245, 0xffff0000, v199
	v_pk_mul_f32 v[168:169], v[168:169], v[240:241] op_sel_hi:[1,0]
	v_pk_mul_f32 v[178:179], v[178:179], v[240:241] op_sel_hi:[1,0]
	v_pk_mul_f32 v[180:181], v[180:181], v[240:241] op_sel_hi:[1,0]
	v_pk_mul_f32 v[244:245], v[244:245], v[240:241] op_sel_hi:[1,0]
	v_min_f32_e32 v168, 0x42b80000, v168
	v_min_f32_e32 v169, 0x42b80000, v169
	v_min_f32_e32 v178, 0x42b80000, v178
	v_min_f32_e32 v179, 0x42b80000, v179
	v_min_f32_e32 v180, 0x42b80000, v180
	v_min_f32_e32 v181, 0x42b80000, v181
	v_min_f32_e32 v244, 0x42b80000, v244
	v_min_f32_e32 v245, 0x42b80000, v245
	v_exp_f32_e32 v168, v168
	v_exp_f32_e32 v169, v169
	v_exp_f32_e32 v178, v178
	v_exp_f32_e32 v179, v179
	v_exp_f32_e32 v180, v180
	v_exp_f32_e32 v181, v181
	v_exp_f32_e32 v244, v244
	v_exp_f32_e32 v245, v245
	s_nop 0
	v_add_f32_e32 v168, 1.0, v168
	v_add_f32_e32 v169, 1.0, v169
	v_add_f32_e32 v178, 1.0, v178
	v_add_f32_e32 v179, 1.0, v179
	v_add_f32_e32 v180, 1.0, v180
	v_add_f32_e32 v181, 1.0, v181
	v_add_f32_e32 v244, 1.0, v244
	v_add_f32_e32 v245, 1.0, v245
	v_rcp_f32_e32 v168, v168
	v_rcp_f32_e32 v169, v169
	v_rcp_f32_e32 v178, v178
	v_rcp_f32_e32 v179, v179
	v_rcp_f32_e32 v180, v180
	v_rcp_f32_e32 v181, v181
	v_rcp_f32_e32 v244, v244
	v_rcp_f32_e32 v245, v245
	s_nop 0
	v_pk_mul_f32 v[6:7], v[6:7], v[168:169]
	v_pk_mul_f32 v[8:9], v[8:9], v[178:179]
	v_pk_mul_f32 v[2:3], v[2:3], v[180:181]
	v_pk_mul_f32 v[4:5], v[4:5], v[244:245]
	v_cvt_pk_bf16_f32 v196, v6, v7
	v_cvt_pk_bf16_f32 v197, v8, v9
	v_cvt_pk_bf16_f32 v198, v2, v3
	v_cvt_pk_bf16_f32 v199, v4, v5
	global_store_dwordx4 v[144:145], v[192:195], off
	global_store_dwordx4 v[144:145], v[196:199], off offset:256

; DI float bflo(unsigned w) { return __uint_as_float(w << 16); }
; DI float bfhi(unsigned w) { return __uint_as_float(w & 0xffff0000u); }
;     DI void operator()(Acc& acc, const Unit& u, int wr, int wc, int fr, int fq) const {
;     ...
;         bf16_t* base = proj + (size_t)(u.pm * 256 + wr * 64 + fr) * NPJ + C_GL + u.pn * 256 + wc * 32 + fq * 8;
;         {
;             u32x4 g[2][4][2];
; #pragma unroll
;             for (int ai = 0; ai < 2; ++ai)
; #pragma unroll
;                 for (int m = 0; m < 4; ++m)
; #pragma unroll
;                     for (int bj = 0; bj < 2; ++bj) g[ai][m][bj] = *(const u32x4*)(base + (size_t)(ai * 128 + m * 16) * NPJ + u.k * 1024 + bj * 128);
; #pragma unroll
;             for (int ai = 0; ai < 2; ++ai)
; #pragma unroll
;                 for (int m = 0; m < 4; ++m)
; #pragma unroll
;                     for (int bj = 0; bj < 2; ++bj) { const u32x4 q = g[ai][m][bj]; f32x4& v0 = acc[ai][bj][m][0]; f32x4& v1 = acc[ai][bj][m][1];
;                         v0[0] *= bflo(q.x); v0[1] *= bfhi(q.x); v0[2] *= bflo(q.y); v0[3] *= bfhi(q.y); v1[0] *= bflo(q.z); v1[1] *= bfhi(q.z); v1[2] *= bflo(q.w); v1[3] *= bfhi(q.w); }
.LBB0_1266:
	v_mov_b32_e32 v130, v1
	v_mov_b32_e32 v132, v170
	s_lshl_b32 s22, s69, 8
	s_add_i32 s22, s22, s34
	v_add_u32_e32 v133, s22, v130
	v_mov_b64_e32 v[130:131], s[48:49]
	v_mad_i64_i32 v[130:131], s[22:23], v133, s40, v[130:131]
	s_lshl_b32 s22, s68, 8
	s_ashr_i32 s23, s22, 31
	v_lshl_add_u64 v[130:131], s[22:23], 1, v[130:131]
	v_lshlrev_b32_e32 v132, 3, v132
	v_lshl_add_u64 v[130:131], v[130:131], 0, s[8:9]
	v_ashrrev_i32_e32 v133, 31, v132
	v_lshl_add_u64 v[130:131], v[132:133], 1, v[130:131]
	s_lshl_b32 s22, s67, 10
	v_lshl_add_u64 v[166:167], v[130:131], 0, s[16:17]
	s_ashr_i32 s23, s22, 31
	v_lshl_add_u64 v[130:131], s[22:23], 1, v[166:167]
	s_nop 0
	v_readfirstlane_b32 s98, v130
	v_readfirstlane_b32 s99, v131
	v_bfe_u32 v148, v183, 5, 3
	v_mul_u32_u24_e32 v148, 0x3200, v148
	v_and_b32_e32 v149, 31, v183
	v_lshl_add_u32 v148, v149, 4, v148
	v_bfe_u32 v149, v183, 6, 2
	v_lshlrev_b32_e32 v149, 6, v149
	v_sub_u32_e32 v243, v148, v149
	v_mov_b32_e32 v240, 0xbfb8aa3b
	s_cmp_eq_u32 s67, 2
	s_cbranch_scc1 .Lup6_final
	s_add_u32 s100, s98, 0x0
	s_addc_u32 s101, s99, 0
	global_load_dwordx4 v[184:187], v243, s[100:101]
	s_add_u32 s100, s98, 0x19000
	s_addc_u32 s101, s99, 0
	global_load_dwordx4 v[188:191], v243, s[100:101]
	s_add_u32 s100, s98, 0x0
	s_addc_u32 s101, s99, 0
	global_load_dwordx4 v[192:195], v243, s[100:101] offset:2048
	s_add_u32 s100, s98, 0x19000
	s_addc_u32 s101, s99, 0
	global_load_dwordx4 v[196:199], v243, s[100:101] offset:2048
	s_add_u32 s100, s98, 0x32000
	s_addc_u32 s101, s99, 0
	global_load_dwordx4 v[200:203], v243, s[100:101]
	s_add_u32 s100, s98, 0x4b000
	s_addc_u32 s101, s99, 0
	global_load_dwordx4 v[204:207], v243, s[100:101]
	s_add_u32 s100, s98, 0x32000
	s_addc_u32 s101, s99, 0
	global_load_dwordx4 v[208:211], v243, s[100:101] offset:2048
	s_add_u32 s100, s98, 0x4b000
	s_addc_u32 s101, s99, 0
	global_load_dwordx4 v[212:215], v243, s[100:101] offset:2048
	s_add_u32 s100, s98, 0x64000
	s_addc_u32 s101, s99, 0
	global_load_dwordx4 v[216:219], v243, s[100:101]
	s_add_u32 s100, s98, 0x7d000
	s_addc_u32 s101, s99, 0
	global_load_dwordx4 v[220:223], v243, s[100:101]
	s_add_u32 s100, s98, 0x64000
	s_addc_u32 s101, s99, 0
	global_load_dwordx4 v[224:227], v243, s[100:101] offset:2048
	s_add_u32 s100, s98, 0x7d000
	s_addc_u32 s101, s99, 0
	global_load_dwordx4 v[228:231], v243, s[100:101] offset:2048
	s_waitcnt vmcnt(8)
	v_lshlrev_b32_e32 v148, 16, v184
	v_and_b32_e32 v149, 0xffff0000, v184
	v_lshlrev_b32_e32 v150, 16, v192
	v_and_b32_e32 v151, 0xffff0000, v192
	v_lshlrev_b32_e32 v152, 16, v185
	v_and_b32_e32 v153, 0xffff0000, v185
	v_lshlrev_b32_e32 v168, 16, v193
	v_and_b32_e32 v169, 0xffff0000, v193
	v_pk_mul_f32 v[148:149], v[148:149], v[240:241] op_sel_hi:[1,0]
	v_pk_mul_f32 v[150:151], v[150:151], v[240:241] op_sel_hi:[1,0]
	v_pk_mul_f32 v[152:153], v[152:153], v[240:241] op_sel_hi:[1,0]
	v_pk_mul_f32 v[168:169], v[168:169], v[240:241] op_sel_hi:[1,0]
	v_min_f32_e32 v148, 0x42b80000, v148
	v_min_f32_e32 v149, 0x42b80000, v149
	v_min_f32_e32 v150, 0x42b80000, v150
	v_min_f32_e32 v151, 0x42b80000, v151
	v_min_f32_e32 v152, 0x42b80000, v152
	v_min_f32_e32 v153, 0x42b80000, v153
	v_min_f32_e32 v168, 0x42b80000, v168
	v_min_f32_e32 v169, 0x42b80000, v169
	v_exp_f32_e32 v148, v148
	v_exp_f32_e32 v149, v149
	v_exp_f32_e32 v150, v150
	v_exp_f32_e32 v151, v151
	v_exp_f32_e32 v152, v152
	v_exp_f32_e32 v153, v153
	v_exp_f32_e32 v168, v168
	v_exp_f32_e32 v169, v169
	s_nop 0
	v_add_f32_e32 v148, 1.0, v148
	v_add_f32_e32 v149, 1.0, v149
	v_add_f32_e32 v150, 1.0, v150
	v_add_f32_e32 v151, 1.0, v151
	v_add_f32_e32 v152, 1.0, v152
	v_add_f32_e32 v153, 1.0, v153
	v_add_f32_e32 v168, 1.0, v168
	v_add_f32_e32 v169, 1.0, v169
	v_rcp_f32_e32 v148, v148
	v_rcp_f32_e32 v149, v149
	v_rcp_f32_e32 v152, v152
	v_rcp_f32_e32 v153, v153
	s_nop 0
	v_pk_mul_f32 v[148:149], v[148:149], v[150:151]
	v_pk_mul_f32 v[152:153], v[152:153], v[168:169]
	v_pk_mul_f32 v[126:127], v[126:127], v[148:149]
	v_pk_mul_f32 v[128:129], v[128:129], v[152:153]
	v_lshlrev_b32_e32 v176, 16, v186
	v_and_b32_e32 v177, 0xffff0000, v186
	v_lshlrev_b32_e32 v178, 16, v194
	v_and_b32_e32 v179, 0xffff0000, v194
	v_lshlrev_b32_e32 v180, 16, v187
	v_and_b32_e32 v181, 0xffff0000, v187
	v_lshlrev_b32_e32 v244, 16, v195
	v_and_b32_e32 v245, 0xffff0000, v195
	v_pk_mul_f32 v[176:177], v[176:177], v[240:241] op_sel_hi:[1,0]
	v_pk_mul_f32 v[178:179], v[178:179], v[240:241] op_sel_hi:[1,0]
	v_pk_mul_f32 v[180:181], v[180:181], v[240:241] op_sel_hi:[1,0]
	v_pk_mul_f32 v[244:245], v[244:245], v[240:241] op_sel_hi:[1,0]
	v_min_f32_e32 v176, 0x42b80000, v176
	v_min_f32_e32 v177, 0x42b80000, v177
	v_min_f32_e32 v178, 0x42b80000, v178
	v_min_f32_e32 v179, 0x42b80000, v179
	v_min_f32_e32 v180, 0x42b80000, v180
	v_min_f32_e32 v181, 0x42b80000, v181
	v_min_f32_e32 v244, 0x42b80000, v244
	v_min_f32_e32 v245, 0x42b80000, v245
	v_exp_f32_e32 v176, v176
	v_exp_f32_e32 v177, v177
	v_exp_f32_e32 v178, v178
	v_exp_f32_e32 v179, v179
	v_exp_f32_e32 v180, v180
	v_exp_f32_e32 v181, v181
	v_exp_f32_e32 v244, v244
	v_exp_f32_e32 v245, v245
	s_nop 0
	v_add_f32_e32 v176, 1.0, v176
	v_add_f32_e32 v177, 1.0, v177
	v_add_f32_e32 v178, 1.0, v178
	v_add_f32_e32 v179, 1.0, v179
	v_add_f32_e32 v180, 1.0, v180
	v_add_f32_e32 v181, 1.0, v181
	v_add_f32_e32 v244, 1.0, v244
	v_add_f32_e32 v245, 1.0, v245
	v_rcp_f32_e32 v176, v176
	v_rcp_f32_e32 v177, v177
	v_rcp_f32_e32 v180, v180
	v_rcp_f32_e32 v181, v181
	s_nop 0
	v_pk_mul_f32 v[176:177], v[176:177], v[178:179]
	v_pk_mul_f32 v[180:181], v[180:181], v[244:245]
	v_pk_mul_f32 v[122:123], v[122:123], v[176:177]
	v_pk_mul_f32 v[124:125], v[124:125], v[180:181]
; DI float bflo(unsigned w) { return __uint_as_float(w << 16); }
; DI float bfhi(unsigned w) { return __uint_as_float(w & 0xffff0000u); }
;     DI void operator()(Acc& acc, const Unit& u, int wr, int wc, int fr, int fq) const {
;     ...
;             for (int ai = 0; ai < 2; ++ai)
; #pragma unroll
;                 for (int m = 0; m < 4; ++m)
; #pragma unroll
;                     for (int bj = 0; bj < 2; ++bj) g[ai][m][bj] = *(const u32x4*)(base + (size_t)(ai * 128 + m * 16) * NPJ + u.k * 1024 + bj * 128);
; #pragma unroll
;             for (int ai = 0; ai < 2; ++ai)
; #pragma unroll
;                 for (int m = 0; m < 4; ++m)
; #pragma unroll
;                     for (int bj = 0; bj < 2; ++bj) { const u32x4 q = g[ai][m][bj]; f32x4& v0 = acc[ai][bj][m][0]; f32x4& v1 = acc[ai][bj][m][1];
;                         v0[0] *= bflo(q.x); v0[1] *= bfhi(q.x); v0[2] *= bflo(q.y); v0[3] *= bfhi(q.y); v1[0] *= bflo(q.z); v1[1] *= bfhi(q.z); v1[2] *= bflo(q.w); v1[3] *= bfhi(q.w); }
	v_lshlrev_b32_e32 v176, 16, v188
	v_and_b32_e32 v177, 0xffff0000, v188
	v_lshlrev_b32_e32 v178, 16, v196
	v_and_b32_e32 v179, 0xffff0000, v196
	v_lshlrev_b32_e32 v180, 16, v189
	v_and_b32_e32 v181, 0xffff0000, v189
	v_lshlrev_b32_e32 v244, 16, v197
	v_and_b32_e32 v245, 0xffff0000, v197
	v_pk_mul_f32 v[176:177], v[176:177], v[240:241] op_sel_hi:[1,0]
	v_pk_mul_f32 v[178:179], v[178:179], v[240:241] op_sel_hi:[1,0]
	v_pk_mul_f32 v[180:181], v[180:181], v[240:241] op_sel_hi:[1,0]
	v_pk_mul_f32 v[244:245], v[244:245], v[240:241] op_sel_hi:[1,0]
	v_min_f32_e32 v176, 0x42b80000, v176
	v_min_f32_e32 v177, 0x42b80000, v177
	v_min_f32_e32 v178, 0x42b80000, v178
	v_min_f32_e32 v179, 0x42b80000, v179
	v_min_f32_e32 v180, 0x42b80000, v180
	v_min_f32_e32 v181, 0x42b80000, v181
	v_min_f32_e32 v244, 0x42b80000, v244
	v_min_f32_e32 v245, 0x42b80000, v245
	v_exp_f32_e32 v176, v176
	v_exp_f32_e32 v177, v177
	v_exp_f32_e32 v178, v178
	v_exp_f32_e32 v179, v179
	v_exp_f32_e32 v180, v180
	v_exp_f32_e32 v181, v181
	v_exp_f32_e32 v244, v244
	v_exp_f32_e32 v245, v245
	s_nop 0
	v_add_f32_e32 v176, 1.0, v176
	v_add_f32_e32 v177, 1.0, v177
	v_add_f32_e32 v178, 1.0, v178
	v_add_f32_e32 v179, 1.0, v179
	v_add_f32_e32 v180, 1.0, v180
	v_add_f32_e32 v181, 1.0, v181
	v_add_f32_e32 v244, 1.0, v244
	v_add_f32_e32 v245, 1.0, v245
	v_rcp_f32_e32 v176, v176
	v_rcp_f32_e32 v177, v177
	v_rcp_f32_e32 v180, v180
	v_rcp_f32_e32 v181, v181
	s_nop 0
	v_pk_mul_f32 v[176:177], v[176:177], v[178:179]
	v_pk_mul_f32 v[180:181], v[180:181], v[244:245]
	v_pk_mul_f32 v[114:115], v[114:115], v[176:177]
	v_pk_mul_f32 v[116:117], v[116:117], v[180:181]
	v_lshlrev_b32_e32 v148, 16, v190
	v_and_b32_e32 v149, 0xffff0000, v190
	v_lshlrev_b32_e32 v150, 16, v198
	v_and_b32_e32 v151, 0xffff0000, v198
	v_lshlrev_b32_e32 v152, 16, v191
	v_and_b32_e32 v153, 0xffff0000, v191
	v_lshlrev_b32_e32 v168, 16, v199
	v_and_b32_e32 v169, 0xffff0000, v199
	v_pk_mul_f32 v[148:149], v[148:149], v[240:241] op_sel_hi:[1,0]
	v_pk_mul_f32 v[150:151], v[150:151], v[240:241] op_sel_hi:[1,0]
	v_pk_mul_f32 v[152:153], v[152:153], v[240:241] op_sel_hi:[1,0]
	v_pk_mul_f32 v[168:169], v[168:169], v[240:241] op_sel_hi:[1,0]
	v_min_f32_e32 v148, 0x42b80000, v148
	v_min_f32_e32 v149, 0x42b80000, v149
	v_min_f32_e32 v150, 0x42b80000, v150
	v_min_f32_e32 v151, 0x42b80000, v151
	v_min_f32_e32 v152, 0x42b80000, v152
	v_min_f32_e32 v153, 0x42b80000, v153
	v_min_f32_e32 v168, 0x42b80000, v168
	v_min_f32_e32 v169, 0x42b80000, v169
	v_exp_f32_e32 v148, v148
	v_exp_f32_e32 v149, v149
	v_exp_f32_e32 v150, v150
	v_exp_f32_e32 v151, v151
	v_exp_f32_e32 v152, v152
	v_exp_f32_e32 v153, v153
	v_exp_f32_e32 v168, v168
	v_exp_f32_e32 v169, v169
	s_nop 0
	v_add_f32_e32 v148, 1.0, v148
	v_add_f32_e32 v149, 1.0, v149
	v_add_f32_e32 v150, 1.0, v150
	v_add_f32_e32 v151, 1.0, v151
	v_add_f32_e32 v152, 1.0, v152
	v_add_f32_e32 v153, 1.0, v153
	v_add_f32_e32 v168, 1.0, v168
	v_add_f32_e32 v169, 1.0, v169
	v_rcp_f32_e32 v148, v148
	v_rcp_f32_e32 v149, v149
	v_rcp_f32_e32 v152, v152
	v_rcp_f32_e32 v153, v153
	s_nop 0
	v_pk_mul_f32 v[148:149], v[148:149], v[150:151]
	v_pk_mul_f32 v[152:153], v[152:153], v[168:169]
	v_pk_mul_f32 v[110:111], v[110:111], v[148:149]
	v_pk_mul_f32 v[112:113], v[112:113], v[152:153]
	s_add_u32 s100, s98, 0x96000
	s_addc_u32 s101, s99, 0
	global_load_dwordx4 v[184:187], v243, s[100:101]
	s_add_u32 s100, s98, 0xaf000
	s_addc_u32 s101, s99, 0
	global_load_dwordx4 v[188:191], v243, s[100:101]
	s_add_u32 s100, s98, 0x96000
	s_addc_u32 s101, s99, 0
	global_load_dwordx4 v[192:195], v243, s[100:101] offset:2048
	s_add_u32 s100, s98, 0xaf000
	s_addc_u32 s101, s99, 0
	global_load_dwordx4 v[196:199], v243, s[100:101] offset:2048
	s_waitcnt vmcnt(8)
	v_lshlrev_b32_e32 v148, 16, v200
	v_and_b32_e32 v149, 0xffff0000, v200
	v_lshlrev_b32_e32 v150, 16, v208
	v_and_b32_e32 v151, 0xffff0000, v208
	v_lshlrev_b32_e32 v152, 16, v201
	v_and_b32_e32 v153, 0xffff0000, v201
	v_lshlrev_b32_e32 v168, 16, v209
	v_and_b32_e32 v169, 0xffff0000, v209
	v_pk_mul_f32 v[148:149], v[148:149], v[240:241] op_sel_hi:[1,0]
	v_pk_mul_f32 v[150:151], v[150:151], v[240:241] op_sel_hi:[1,0]
	v_pk_mul_f32 v[152:153], v[152:153], v[240:241] op_sel_hi:[1,0]
	v_pk_mul_f32 v[168:169], v[168:169], v[240:241] op_sel_hi:[1,0]
	v_min_f32_e32 v148, 0x42b80000, v148
	v_min_f32_e32 v149, 0x42b80000, v149
	v_min_f32_e32 v150, 0x42b80000, v150
	v_min_f32_e32 v151, 0x42b80000, v151
	v_min_f32_e32 v152, 0x42b80000, v152
	v_min_f32_e32 v153, 0x42b80000, v153
	v_min_f32_e32 v168, 0x42b80000, v168
	v_min_f32_e32 v169, 0x42b80000, v169
	v_exp_f32_e32 v148, v148
	v_exp_f32_e32 v149, v149
	v_exp_f32_e32 v150, v150
	v_exp_f32_e32 v151, v151
	v_exp_f32_e32 v152, v152
	v_exp_f32_e32 v153, v153
	v_exp_f32_e32 v168, v168
	v_exp_f32_e32 v169, v169
	s_nop 0
	v_add_f32_e32 v148, 1.0, v148
	v_add_f32_e32 v149, 1.0, v149
	v_add_f32_e32 v150, 1.0, v150
	v_add_f32_e32 v151, 1.0, v151
	v_add_f32_e32 v152, 1.0, v152
	v_add_f32_e32 v153, 1.0, v153
	v_add_f32_e32 v168, 1.0, v168
	v_add_f32_e32 v169, 1.0, v169
	v_rcp_f32_e32 v148, v148
	v_rcp_f32_e32 v149, v149
	v_rcp_f32_e32 v152, v152
	v_rcp_f32_e32 v153, v153
	s_nop 0
	v_pk_mul_f32 v[148:149], v[148:149], v[150:151]
	v_pk_mul_f32 v[152:153], v[152:153], v[168:169]
	v_pk_mul_f32 v[118:119], v[118:119], v[148:149]
	v_pk_mul_f32 v[120:121], v[120:121], v[152:153]
	v_lshlrev_b32_e32 v176, 16, v202
	v_and_b32_e32 v177, 0xffff0000, v202
	v_lshlrev_b32_e32 v178, 16, v210
	v_and_b32_e32 v179, 0xffff0000, v210
	v_lshlrev_b32_e32 v180, 16, v203
	v_and_b32_e32 v181, 0xffff0000, v203
	v_lshlrev_b32_e32 v244, 16, v211
	v_and_b32_e32 v245, 0xffff0000, v211
; DI float bflo(unsigned w) { return __uint_as_float(w << 16); }
; DI float bfhi(unsigned w) { return __uint_as_float(w & 0xffff0000u); }
;     DI void operator()(Acc& acc, const Unit& u, int wr, int wc, int fr, int fq) const {
;     ...
;             for (int ai = 0; ai < 2; ++ai)
; #pragma unroll
;                 for (int m = 0; m < 4; ++m)
; #pragma unroll
;                     for (int bj = 0; bj < 2; ++bj) g[ai][m][bj] = *(const u32x4*)(base + (size_t)(ai * 128 + m * 16) * NPJ + u.k * 1024 + bj * 128);
; #pragma unroll
;             for (int ai = 0; ai < 2; ++ai)
; #pragma unroll
;                 for (int m = 0; m < 4; ++m)
; #pragma unroll
;                     for (int bj = 0; bj < 2; ++bj) { const u32x4 q = g[ai][m][bj]; f32x4& v0 = acc[ai][bj][m][0]; f32x4& v1 = acc[ai][bj][m][1];
;                         v0[0] *= bflo(q.x); v0[1] *= bfhi(q.x); v0[2] *= bflo(q.y); v0[3] *= bfhi(q.y); v1[0] *= bflo(q.z); v1[1] *= bfhi(q.z); v1[2] *= bflo(q.w); v1[3] *= bfhi(q.w); }
	v_pk_mul_f32 v[176:177], v[176:177], v[240:241] op_sel_hi:[1,0]
	v_pk_mul_f32 v[178:179], v[178:179], v[240:241] op_sel_hi:[1,0]
	v_pk_mul_f32 v[180:181], v[180:181], v[240:241] op_sel_hi:[1,0]
	v_pk_mul_f32 v[244:245], v[244:245], v[240:241] op_sel_hi:[1,0]
	v_min_f32_e32 v176, 0x42b80000, v176
	v_min_f32_e32 v177, 0x42b80000, v177
	v_min_f32_e32 v178, 0x42b80000, v178
	v_min_f32_e32 v179, 0x42b80000, v179
	v_min_f32_e32 v180, 0x42b80000, v180
	v_min_f32_e32 v181, 0x42b80000, v181
	v_min_f32_e32 v244, 0x42b80000, v244
	v_min_f32_e32 v245, 0x42b80000, v245
	v_exp_f32_e32 v176, v176
	v_exp_f32_e32 v177, v177
	v_exp_f32_e32 v178, v178
	v_exp_f32_e32 v179, v179
	v_exp_f32_e32 v180, v180
	v_exp_f32_e32 v181, v181
	v_exp_f32_e32 v244, v244
	v_exp_f32_e32 v245, v245
	s_nop 0
	v_add_f32_e32 v176, 1.0, v176
	v_add_f32_e32 v177, 1.0, v177
	v_add_f32_e32 v178, 1.0, v178
	v_add_f32_e32 v179, 1.0, v179
	v_add_f32_e32 v180, 1.0, v180
	v_add_f32_e32 v181, 1.0, v181
	v_add_f32_e32 v244, 1.0, v244
	v_add_f32_e32 v245, 1.0, v245
	v_rcp_f32_e32 v176, v176
	v_rcp_f32_e32 v177, v177
	v_rcp_f32_e32 v180, v180
	v_rcp_f32_e32 v181, v181
	s_nop 0
	v_pk_mul_f32 v[176:177], v[176:177], v[178:179]
	v_pk_mul_f32 v[180:181], v[180:181], v[244:245]
	v_pk_mul_f32 v[106:107], v[106:107], v[176:177]
	v_pk_mul_f32 v[108:109], v[108:109], v[180:181]
	v_lshlrev_b32_e32 v176, 16, v204
	v_and_b32_e32 v177, 0xffff0000, v204
	v_lshlrev_b32_e32 v178, 16, v212
	v_and_b32_e32 v179, 0xffff0000, v212
	v_lshlrev_b32_e32 v180, 16, v205
	v_and_b32_e32 v181, 0xffff0000, v205
	v_lshlrev_b32_e32 v244, 16, v213
	v_and_b32_e32 v245, 0xffff0000, v213
	v_pk_mul_f32 v[176:177], v[176:177], v[240:241] op_sel_hi:[1,0]
	v_pk_mul_f32 v[178:179], v[178:179], v[240:241] op_sel_hi:[1,0]
	v_pk_mul_f32 v[180:181], v[180:181], v[240:241] op_sel_hi:[1,0]
	v_pk_mul_f32 v[244:245], v[244:245], v[240:241] op_sel_hi:[1,0]
	v_min_f32_e32 v176, 0x42b80000, v176
	v_min_f32_e32 v177, 0x42b80000, v177
	v_min_f32_e32 v178, 0x42b80000, v178
	v_min_f32_e32 v179, 0x42b80000, v179
	v_min_f32_e32 v180, 0x42b80000, v180
	v_min_f32_e32 v181, 0x42b80000, v181
	v_min_f32_e32 v244, 0x42b80000, v244
	v_min_f32_e32 v245, 0x42b80000, v245
	v_exp_f32_e32 v176, v176
	v_exp_f32_e32 v177, v177
	v_exp_f32_e32 v178, v178
	v_exp_f32_e32 v179, v179
	v_exp_f32_e32 v180, v180
	v_exp_f32_e32 v181, v181
	v_exp_f32_e32 v244, v244
	v_exp_f32_e32 v245, v245
	s_nop 0
	v_add_f32_e32 v176, 1.0, v176
	v_add_f32_e32 v177, 1.0, v177
	v_add_f32_e32 v178, 1.0, v178
	v_add_f32_e32 v179, 1.0, v179
	v_add_f32_e32 v180, 1.0, v180
	v_add_f32_e32 v181, 1.0, v181
	v_add_f32_e32 v244, 1.0, v244
	v_add_f32_e32 v245, 1.0, v245
	v_rcp_f32_e32 v176, v176
	v_rcp_f32_e32 v177, v177
	v_rcp_f32_e32 v180, v180
	v_rcp_f32_e32 v181, v181
	s_nop 0
	v_pk_mul_f32 v[176:177], v[176:177], v[178:179]
	v_pk_mul_f32 v[180:181], v[180:181], v[244:245]
	v_pk_mul_f32 v[98:99], v[98:99], v[176:177]
	v_pk_mul_f32 v[100:101], v[100:101], v[180:181]
	v_lshlrev_b32_e32 v148, 16, v206
	v_and_b32_e32 v149, 0xffff0000, v206
	v_lshlrev_b32_e32 v150, 16, v214
	v_and_b32_e32 v151, 0xffff0000, v214
	v_lshlrev_b32_e32 v152, 16, v207
	v_and_b32_e32 v153, 0xffff0000, v207
	v_lshlrev_b32_e32 v168, 16, v215
	v_and_b32_e32 v169, 0xffff0000, v215
	v_pk_mul_f32 v[148:149], v[148:149], v[240:241] op_sel_hi:[1,0]
	v_pk_mul_f32 v[150:151], v[150:151], v[240:241] op_sel_hi:[1,0]
	v_pk_mul_f32 v[152:153], v[152:153], v[240:241] op_sel_hi:[1,0]
	v_pk_mul_f32 v[168:169], v[168:169], v[240:241] op_sel_hi:[1,0]
	v_min_f32_e32 v148, 0x42b80000, v148
	v_min_f32_e32 v149, 0x42b80000, v149
	v_min_f32_e32 v150, 0x42b80000, v150
	v_min_f32_e32 v151, 0x42b80000, v151
	v_min_f32_e32 v152, 0x42b80000, v152
	v_min_f32_e32 v153, 0x42b80000, v153
	v_min_f32_e32 v168, 0x42b80000, v168
	v_min_f32_e32 v169, 0x42b80000, v169
	v_exp_f32_e32 v148, v148
	v_exp_f32_e32 v149, v149
	v_exp_f32_e32 v150, v150
	v_exp_f32_e32 v151, v151
	v_exp_f32_e32 v152, v152
	v_exp_f32_e32 v153, v153
	v_exp_f32_e32 v168, v168
	v_exp_f32_e32 v169, v169
	s_nop 0
	v_add_f32_e32 v148, 1.0, v148
	v_add_f32_e32 v149, 1.0, v149
	v_add_f32_e32 v150, 1.0, v150
	v_add_f32_e32 v151, 1.0, v151
	v_add_f32_e32 v152, 1.0, v152
	v_add_f32_e32 v153, 1.0, v153
	v_add_f32_e32 v168, 1.0, v168
	v_add_f32_e32 v169, 1.0, v169
	v_rcp_f32_e32 v148, v148
	v_rcp_f32_e32 v149, v149
	v_rcp_f32_e32 v152, v152
	v_rcp_f32_e32 v153, v153
	s_nop 0
	v_pk_mul_f32 v[148:149], v[148:149], v[150:151]
	v_pk_mul_f32 v[152:153], v[152:153], v[168:169]
	v_pk_mul_f32 v[90:91], v[90:91], v[148:149]
	v_pk_mul_f32 v[92:93], v[92:93], v[152:153]
	s_add_u32 s100, s98, 0x190000
	s_addc_u32 s101, s99, 0
	global_load_dwordx4 v[200:203], v243, s[100:101]
	s_add_u32 s100, s98, 0x1a9000
	s_addc_u32 s101, s99, 0
	global_load_dwordx4 v[204:207], v243, s[100:101]
	s_add_u32 s100, s98, 0x190000
	s_addc_u32 s101, s99, 0
	global_load_dwordx4 v[208:211], v243, s[100:101] offset:2048
	s_add_u32 s100, s98, 0x1a9000
	s_addc_u32 s101, s99, 0
	global_load_dwordx4 v[212:215], v243, s[100:101] offset:2048
	s_waitcnt vmcnt(8)
; DI float bflo(unsigned w) { return __uint_as_float(w << 16); }
; DI float bfhi(unsigned w) { return __uint_as_float(w & 0xffff0000u); }
;     DI void operator()(Acc& acc, const Unit& u, int wr, int wc, int fr, int fq) const {
;     ...
;             for (int ai = 0; ai < 2; ++ai)
; #pragma unroll
;                 for (int m = 0; m < 4; ++m)
; #pragma unroll
;                     for (int bj = 0; bj < 2; ++bj) g[ai][m][bj] = *(const u32x4*)(base + (size_t)(ai * 128 + m * 16) * NPJ + u.k * 1024 + bj * 128);
; #pragma unroll
;             for (int ai = 0; ai < 2; ++ai)
; #pragma unroll
;                 for (int m = 0; m < 4; ++m)
; #pragma unroll
;                     for (int bj = 0; bj < 2; ++bj) { const u32x4 q = g[ai][m][bj]; f32x4& v0 = acc[ai][bj][m][0]; f32x4& v1 = acc[ai][bj][m][1];
;                         v0[0] *= bflo(q.x); v0[1] *= bfhi(q.x); v0[2] *= bflo(q.y); v0[3] *= bfhi(q.y); v1[0] *= bflo(q.z); v1[1] *= bfhi(q.z); v1[2] *= bflo(q.w); v1[3] *= bfhi(q.w); }
	v_lshlrev_b32_e32 v148, 16, v216
	v_and_b32_e32 v149, 0xffff0000, v216
	v_lshlrev_b32_e32 v150, 16, v224
	v_and_b32_e32 v151, 0xffff0000, v224
	v_lshlrev_b32_e32 v152, 16, v217
	v_and_b32_e32 v153, 0xffff0000, v217
	v_lshlrev_b32_e32 v168, 16, v225
	v_and_b32_e32 v169, 0xffff0000, v225
	v_pk_mul_f32 v[148:149], v[148:149], v[240:241] op_sel_hi:[1,0]
	v_pk_mul_f32 v[150:151], v[150:151], v[240:241] op_sel_hi:[1,0]
	v_pk_mul_f32 v[152:153], v[152:153], v[240:241] op_sel_hi:[1,0]
	v_pk_mul_f32 v[168:169], v[168:169], v[240:241] op_sel_hi:[1,0]
	v_min_f32_e32 v148, 0x42b80000, v148
	v_min_f32_e32 v149, 0x42b80000, v149
	v_min_f32_e32 v150, 0x42b80000, v150
	v_min_f32_e32 v151, 0x42b80000, v151
	v_min_f32_e32 v152, 0x42b80000, v152
	v_min_f32_e32 v153, 0x42b80000, v153
	v_min_f32_e32 v168, 0x42b80000, v168
	v_min_f32_e32 v169, 0x42b80000, v169
	v_exp_f32_e32 v148, v148
	v_exp_f32_e32 v149, v149
	v_exp_f32_e32 v150, v150
	v_exp_f32_e32 v151, v151
	v_exp_f32_e32 v152, v152
	v_exp_f32_e32 v153, v153
	v_exp_f32_e32 v168, v168
	v_exp_f32_e32 v169, v169
	s_nop 0
	v_add_f32_e32 v148, 1.0, v148
	v_add_f32_e32 v149, 1.0, v149
	v_add_f32_e32 v150, 1.0, v150
	v_add_f32_e32 v151, 1.0, v151
	v_add_f32_e32 v152, 1.0, v152
	v_add_f32_e32 v153, 1.0, v153
	v_add_f32_e32 v168, 1.0, v168
	v_add_f32_e32 v169, 1.0, v169
	v_rcp_f32_e32 v148, v148
	v_rcp_f32_e32 v149, v149
	v_rcp_f32_e32 v152, v152
	v_rcp_f32_e32 v153, v153
	s_nop 0
	v_pk_mul_f32 v[148:149], v[148:149], v[150:151]
	v_pk_mul_f32 v[152:153], v[152:153], v[168:169]
	v_pk_mul_f32 v[102:103], v[102:103], v[148:149]
	v_pk_mul_f32 v[104:105], v[104:105], v[152:153]
	v_lshlrev_b32_e32 v176, 16, v218
	v_and_b32_e32 v177, 0xffff0000, v218
	v_lshlrev_b32_e32 v178, 16, v226
	v_and_b32_e32 v179, 0xffff0000, v226
	v_lshlrev_b32_e32 v180, 16, v219
	v_and_b32_e32 v181, 0xffff0000, v219
	v_lshlrev_b32_e32 v244, 16, v227
	v_and_b32_e32 v245, 0xffff0000, v227
	v_pk_mul_f32 v[176:177], v[176:177], v[240:241] op_sel_hi:[1,0]
	v_pk_mul_f32 v[178:179], v[178:179], v[240:241] op_sel_hi:[1,0]
	v_pk_mul_f32 v[180:181], v[180:181], v[240:241] op_sel_hi:[1,0]
	v_pk_mul_f32 v[244:245], v[244:245], v[240:241] op_sel_hi:[1,0]
	v_min_f32_e32 v176, 0x42b80000, v176
	v_min_f32_e32 v177, 0x42b80000, v177
	v_min_f32_e32 v178, 0x42b80000, v178
	v_min_f32_e32 v179, 0x42b80000, v179
	v_min_f32_e32 v180, 0x42b80000, v180
	v_min_f32_e32 v181, 0x42b80000, v181
	v_min_f32_e32 v244, 0x42b80000, v244
	v_min_f32_e32 v245, 0x42b80000, v245
	v_exp_f32_e32 v176, v176
	v_exp_f32_e32 v177, v177
	v_exp_f32_e32 v178, v178
	v_exp_f32_e32 v179, v179
	v_exp_f32_e32 v180, v180
	v_exp_f32_e32 v181, v181
	v_exp_f32_e32 v244, v244
	v_exp_f32_e32 v245, v245
	s_nop 0
	v_add_f32_e32 v176, 1.0, v176
	v_add_f32_e32 v177, 1.0, v177
	v_add_f32_e32 v178, 1.0, v178
	v_add_f32_e32 v179, 1.0, v179
	v_add_f32_e32 v180, 1.0, v180
	v_add_f32_e32 v181, 1.0, v181
	v_add_f32_e32 v244, 1.0, v244
	v_add_f32_e32 v245, 1.0, v245
	v_rcp_f32_e32 v176, v176
	v_rcp_f32_e32 v177, v177
	v_rcp_f32_e32 v180, v180
	v_rcp_f32_e32 v181, v181
	s_nop 0
	v_pk_mul_f32 v[176:177], v[176:177], v[178:179]
	v_pk_mul_f32 v[180:181], v[180:181], v[244:245]
	v_pk_mul_f32 v[94:95], v[94:95], v[176:177]
	v_pk_mul_f32 v[96:97], v[96:97], v[180:181]
	v_lshlrev_b32_e32 v176, 16, v220
	v_and_b32_e32 v177, 0xffff0000, v220
	v_lshlrev_b32_e32 v178, 16, v228
	v_and_b32_e32 v179, 0xffff0000, v228
	v_lshlrev_b32_e32 v180, 16, v221
	v_and_b32_e32 v181, 0xffff0000, v221
	v_lshlrev_b32_e32 v244, 16, v229
	v_and_b32_e32 v245, 0xffff0000, v229
	v_pk_mul_f32 v[176:177], v[176:177], v[240:241] op_sel_hi:[1,0]
	v_pk_mul_f32 v[178:179], v[178:179], v[240:241] op_sel_hi:[1,0]
	v_pk_mul_f32 v[180:181], v[180:181], v[240:241] op_sel_hi:[1,0]
	v_pk_mul_f32 v[244:245], v[244:245], v[240:241] op_sel_hi:[1,0]
	v_min_f32_e32 v176, 0x42b80000, v176
	v_min_f32_e32 v177, 0x42b80000, v177
	v_min_f32_e32 v178, 0x42b80000, v178
	v_min_f32_e32 v179, 0x42b80000, v179
	v_min_f32_e32 v180, 0x42b80000, v180
	v_min_f32_e32 v181, 0x42b80000, v181
	v_min_f32_e32 v244, 0x42b80000, v244
	v_min_f32_e32 v245, 0x42b80000, v245
	v_exp_f32_e32 v176, v176
	v_exp_f32_e32 v177, v177
	v_exp_f32_e32 v178, v178
	v_exp_f32_e32 v179, v179
	v_exp_f32_e32 v180, v180
	v_exp_f32_e32 v181, v181
	v_exp_f32_e32 v244, v244
	v_exp_f32_e32 v245, v245
	s_nop 0
	v_add_f32_e32 v176, 1.0, v176
	v_add_f32_e32 v177, 1.0, v177
	v_add_f32_e32 v178, 1.0, v178
	v_add_f32_e32 v179, 1.0, v179
	v_add_f32_e32 v180, 1.0, v180
	v_add_f32_e32 v181, 1.0, v181
	v_add_f32_e32 v244, 1.0, v244
	v_add_f32_e32 v245, 1.0, v245
	v_rcp_f32_e32 v176, v176
	v_rcp_f32_e32 v177, v177
	v_rcp_f32_e32 v180, v180
	v_rcp_f32_e32 v181, v181
	s_nop 0
	v_pk_mul_f32 v[176:177], v[176:177], v[178:179]
	v_pk_mul_f32 v[180:181], v[180:181], v[244:245]
	v_pk_mul_f32 v[82:83], v[82:83], v[176:177]
	v_pk_mul_f32 v[84:85], v[84:85], v[180:181]
	v_lshlrev_b32_e32 v148, 16, v222
	v_and_b32_e32 v149, 0xffff0000, v222
	v_lshlrev_b32_e32 v150, 16, v230
	v_and_b32_e32 v151, 0xffff0000, v230
	v_lshlrev_b32_e32 v152, 16, v223
	v_and_b32_e32 v153, 0xffff0000, v223
	v_lshlrev_b32_e32 v168, 16, v231
	v_and_b32_e32 v169, 0xffff0000, v231
	v_pk_mul_f32 v[148:149], v[148:149], v[240:241] op_sel_hi:[1,0]
	v_pk_mul_f32 v[150:151], v[150:151], v[240:241] op_sel_hi:[1,0]
	v_pk_mul_f32 v[152:153], v[152:153], v[240:241] op_sel_hi:[1,0]
	v_pk_mul_f32 v[168:169], v[168:169], v[240:241] op_sel_hi:[1,0]
	v_min_f32_e32 v148, 0x42b80000, v148
	v_min_f32_e32 v149, 0x42b80000, v149
	v_min_f32_e32 v150, 0x42b80000, v150
	v_min_f32_e32 v151, 0x42b80000, v151
	v_min_f32_e32 v152, 0x42b80000, v152
	v_min_f32_e32 v153, 0x42b80000, v153
	v_min_f32_e32 v168, 0x42b80000, v168
	v_min_f32_e32 v169, 0x42b80000, v169
	v_exp_f32_e32 v148, v148
	v_exp_f32_e32 v149, v149
	v_exp_f32_e32 v150, v150
	v_exp_f32_e32 v151, v151
	v_exp_f32_e32 v152, v152
	v_exp_f32_e32 v153, v153
	v_exp_f32_e32 v168, v168
	v_exp_f32_e32 v169, v169
	s_nop 0
	v_add_f32_e32 v148, 1.0, v148
	v_add_f32_e32 v149, 1.0, v149
	v_add_f32_e32 v150, 1.0, v150
	v_add_f32_e32 v151, 1.0, v151
	v_add_f32_e32 v152, 1.0, v152
	v_add_f32_e32 v153, 1.0, v153
	v_add_f32_e32 v168, 1.0, v168
	v_add_f32_e32 v169, 1.0, v169
	v_rcp_f32_e32 v148, v148
	v_rcp_f32_e32 v149, v149
	v_rcp_f32_e32 v152, v152
	v_rcp_f32_e32 v153, v153
	s_nop 0
	v_pk_mul_f32 v[148:149], v[148:149], v[150:151]
	v_pk_mul_f32 v[152:153], v[152:153], v[168:169]
	v_pk_mul_f32 v[74:75], v[74:75], v[148:149]
	v_pk_mul_f32 v[76:77], v[76:77], v[152:153]
	s_add_u32 s100, s98, 0x1c2000
	s_addc_u32 s101, s99, 0
	global_load_dwordx4 v[216:219], v243, s[100:101]
	s_add_u32 s100, s98, 0x1db000
	s_addc_u32 s101, s99, 0
	global_load_dwordx4 v[220:223], v243, s[100:101]
	s_add_u32 s100, s98, 0x1c2000
	s_addc_u32 s101, s99, 0
	global_load_dwordx4 v[224:227], v243, s[100:101] offset:2048
	s_add_u32 s100, s98, 0x1db000
	s_addc_u32 s101, s99, 0
	global_load_dwordx4 v[228:231], v243, s[100:101] offset:2048
	s_waitcnt vmcnt(8)
; DI float bflo(unsigned w) { return __uint_as_float(w << 16); }
; DI float bfhi(unsigned w) { return __uint_as_float(w & 0xffff0000u); }
;     DI void operator()(Acc& acc, const Unit& u, int wr, int wc, int fr, int fq) const {
;     ...
;             for (int ai = 0; ai < 2; ++ai)
; #pragma unroll
;                 for (int m = 0; m < 4; ++m)
; #pragma unroll
;                     for (int bj = 0; bj < 2; ++bj) g[ai][m][bj] = *(const u32x4*)(base + (size_t)(ai * 128 + m * 16) * NPJ + u.k * 1024 + bj * 128);
; #pragma unroll
;             for (int ai = 0; ai < 2; ++ai)
; #pragma unroll
;                 for (int m = 0; m < 4; ++m)
; #pragma unroll
;                     for (int bj = 0; bj < 2; ++bj) { const u32x4 q = g[ai][m][bj]; f32x4& v0 = acc[ai][bj][m][0]; f32x4& v1 = acc[ai][bj][m][1];
;                         v0[0] *= bflo(q.x); v0[1] *= bfhi(q.x); v0[2] *= bflo(q.y); v0[3] *= bfhi(q.y); v1[0] *= bflo(q.z); v1[1] *= bfhi(q.z); v1[2] *= bflo(q.w); v1[3] *= bfhi(q.w); }
	v_lshlrev_b32_e32 v148, 16, v184
	v_and_b32_e32 v149, 0xffff0000, v184
	v_lshlrev_b32_e32 v150, 16, v192
	v_and_b32_e32 v151, 0xffff0000, v192
	v_lshlrev_b32_e32 v152, 16, v185
	v_and_b32_e32 v153, 0xffff0000, v185
	v_lshlrev_b32_e32 v168, 16, v193
	v_and_b32_e32 v169, 0xffff0000, v193
	v_pk_mul_f32 v[148:149], v[148:149], v[240:241] op_sel_hi:[1,0]
	v_pk_mul_f32 v[150:151], v[150:151], v[240:241] op_sel_hi:[1,0]
	v_pk_mul_f32 v[152:153], v[152:153], v[240:241] op_sel_hi:[1,0]
	v_pk_mul_f32 v[168:169], v[168:169], v[240:241] op_sel_hi:[1,0]
	v_min_f32_e32 v148, 0x42b80000, v148
	v_min_f32_e32 v149, 0x42b80000, v149
	v_min_f32_e32 v150, 0x42b80000, v150
	v_min_f32_e32 v151, 0x42b80000, v151
	v_min_f32_e32 v152, 0x42b80000, v152
	v_min_f32_e32 v153, 0x42b80000, v153
	v_min_f32_e32 v168, 0x42b80000, v168
	v_min_f32_e32 v169, 0x42b80000, v169
	v_exp_f32_e32 v148, v148
	v_exp_f32_e32 v149, v149
	v_exp_f32_e32 v150, v150
	v_exp_f32_e32 v151, v151
	v_exp_f32_e32 v152, v152
	v_exp_f32_e32 v153, v153
	v_exp_f32_e32 v168, v168
	v_exp_f32_e32 v169, v169
	s_nop 0
	v_add_f32_e32 v148, 1.0, v148
	v_add_f32_e32 v149, 1.0, v149
	v_add_f32_e32 v150, 1.0, v150
	v_add_f32_e32 v151, 1.0, v151
	v_add_f32_e32 v152, 1.0, v152
	v_add_f32_e32 v153, 1.0, v153
	v_add_f32_e32 v168, 1.0, v168
	v_add_f32_e32 v169, 1.0, v169
	v_rcp_f32_e32 v148, v148
	v_rcp_f32_e32 v149, v149
	v_rcp_f32_e32 v152, v152
	v_rcp_f32_e32 v153, v153
	s_nop 0
	v_pk_mul_f32 v[148:149], v[148:149], v[150:151]
	v_pk_mul_f32 v[152:153], v[152:153], v[168:169]
	v_pk_mul_f32 v[86:87], v[86:87], v[148:149]
	v_pk_mul_f32 v[88:89], v[88:89], v[152:153]
	v_lshlrev_b32_e32 v176, 16, v186
	v_and_b32_e32 v177, 0xffff0000, v186
	v_lshlrev_b32_e32 v178, 16, v194
	v_and_b32_e32 v179, 0xffff0000, v194
	v_lshlrev_b32_e32 v180, 16, v187
	v_and_b32_e32 v181, 0xffff0000, v187
	v_lshlrev_b32_e32 v244, 16, v195
	v_and_b32_e32 v245, 0xffff0000, v195
	v_pk_mul_f32 v[176:177], v[176:177], v[240:241] op_sel_hi:[1,0]
	v_pk_mul_f32 v[178:179], v[178:179], v[240:241] op_sel_hi:[1,0]
	v_pk_mul_f32 v[180:181], v[180:181], v[240:241] op_sel_hi:[1,0]
	v_pk_mul_f32 v[244:245], v[244:245], v[240:241] op_sel_hi:[1,0]
	v_min_f32_e32 v176, 0x42b80000, v176
	v_min_f32_e32 v177, 0x42b80000, v177
	v_min_f32_e32 v178, 0x42b80000, v178
	v_min_f32_e32 v179, 0x42b80000, v179
	v_min_f32_e32 v180, 0x42b80000, v180
	v_min_f32_e32 v181, 0x42b80000, v181
	v_min_f32_e32 v244, 0x42b80000, v244
	v_min_f32_e32 v245, 0x42b80000, v245
	v_exp_f32_e32 v176, v176
	v_exp_f32_e32 v177, v177
	v_exp_f32_e32 v178, v178
	v_exp_f32_e32 v179, v179
	v_exp_f32_e32 v180, v180
	v_exp_f32_e32 v181, v181
	v_exp_f32_e32 v244, v244
	v_exp_f32_e32 v245, v245
	s_nop 0
	v_add_f32_e32 v176, 1.0, v176
	v_add_f32_e32 v177, 1.0, v177
	v_add_f32_e32 v178, 1.0, v178
	v_add_f32_e32 v179, 1.0, v179
	v_add_f32_e32 v180, 1.0, v180
	v_add_f32_e32 v181, 1.0, v181
	v_add_f32_e32 v244, 1.0, v244
	v_add_f32_e32 v245, 1.0, v245
	v_rcp_f32_e32 v176, v176
	v_rcp_f32_e32 v177, v177
	v_rcp_f32_e32 v180, v180
	v_rcp_f32_e32 v181, v181
	s_nop 0
	v_pk_mul_f32 v[176:177], v[176:177], v[178:179]
	v_pk_mul_f32 v[180:181], v[180:181], v[244:245]
	v_pk_mul_f32 v[78:79], v[78:79], v[176:177]
	v_pk_mul_f32 v[80:81], v[80:81], v[180:181]
	v_lshlrev_b32_e32 v176, 16, v188
	v_and_b32_e32 v177, 0xffff0000, v188
	v_lshlrev_b32_e32 v178, 16, v196
	v_and_b32_e32 v179, 0xffff0000, v196
	v_lshlrev_b32_e32 v180, 16, v189
	v_and_b32_e32 v181, 0xffff0000, v189
	v_lshlrev_b32_e32 v244, 16, v197
	v_and_b32_e32 v245, 0xffff0000, v197
	v_pk_mul_f32 v[176:177], v[176:177], v[240:241] op_sel_hi:[1,0]
	v_pk_mul_f32 v[178:179], v[178:179], v[240:241] op_sel_hi:[1,0]
	v_pk_mul_f32 v[180:181], v[180:181], v[240:241] op_sel_hi:[1,0]
	v_pk_mul_f32 v[244:245], v[244:245], v[240:241] op_sel_hi:[1,0]
	v_min_f32_e32 v176, 0x42b80000, v176
	v_min_f32_e32 v177, 0x42b80000, v177
	v_min_f32_e32 v178, 0x42b80000, v178
	v_min_f32_e32 v179, 0x42b80000, v179
	v_min_f32_e32 v180, 0x42b80000, v180
	v_min_f32_e32 v181, 0x42b80000, v181
	v_min_f32_e32 v244, 0x42b80000, v244
	v_min_f32_e32 v245, 0x42b80000, v245
	v_exp_f32_e32 v176, v176
	v_exp_f32_e32 v177, v177
	v_exp_f32_e32 v178, v178
	v_exp_f32_e32 v179, v179
	v_exp_f32_e32 v180, v180
	v_exp_f32_e32 v181, v181
	v_exp_f32_e32 v244, v244
	v_exp_f32_e32 v245, v245
	s_nop 0
	v_add_f32_e32 v176, 1.0, v176
	v_add_f32_e32 v177, 1.0, v177
	v_add_f32_e32 v178, 1.0, v178
	v_add_f32_e32 v179, 1.0, v179
	v_add_f32_e32 v180, 1.0, v180
	v_add_f32_e32 v181, 1.0, v181
	v_add_f32_e32 v244, 1.0, v244
	v_add_f32_e32 v245, 1.0, v245
	v_rcp_f32_e32 v176, v176
	v_rcp_f32_e32 v177, v177
	v_rcp_f32_e32 v180, v180
	v_rcp_f32_e32 v181, v181
	s_nop 0
	v_pk_mul_f32 v[176:177], v[176:177], v[178:179]
	v_pk_mul_f32 v[180:181], v[180:181], v[244:245]
	v_pk_mul_f32 v[70:71], v[70:71], v[176:177]
	v_pk_mul_f32 v[72:73], v[72:73], v[180:181]
	v_lshlrev_b32_e32 v148, 16, v190
	v_and_b32_e32 v149, 0xffff0000, v190
	v_lshlrev_b32_e32 v150, 16, v198
	v_and_b32_e32 v151, 0xffff0000, v198
	v_lshlrev_b32_e32 v152, 16, v191
	v_and_b32_e32 v153, 0xffff0000, v191
	v_lshlrev_b32_e32 v168, 16, v199
	v_and_b32_e32 v169, 0xffff0000, v199
	v_pk_mul_f32 v[148:149], v[148:149], v[240:241] op_sel_hi:[1,0]
	v_pk_mul_f32 v[150:151], v[150:151], v[240:241] op_sel_hi:[1,0]
	v_pk_mul_f32 v[152:153], v[152:153], v[240:241] op_sel_hi:[1,0]
	v_pk_mul_f32 v[168:169], v[168:169], v[240:241] op_sel_hi:[1,0]
	v_min_f32_e32 v148, 0x42b80000, v148
	v_min_f32_e32 v149, 0x42b80000, v149
	v_min_f32_e32 v150, 0x42b80000, v150
	v_min_f32_e32 v151, 0x42b80000, v151
	v_min_f32_e32 v152, 0x42b80000, v152
	v_min_f32_e32 v153, 0x42b80000, v153
	v_min_f32_e32 v168, 0x42b80000, v168
	v_min_f32_e32 v169, 0x42b80000, v169
	v_exp_f32_e32 v148, v148
	v_exp_f32_e32 v149, v149
	v_exp_f32_e32 v150, v150
	v_exp_f32_e32 v151, v151
	v_exp_f32_e32 v152, v152
	v_exp_f32_e32 v153, v153
	v_exp_f32_e32 v168, v168
	v_exp_f32_e32 v169, v169
	s_nop 0
	v_add_f32_e32 v148, 1.0, v148
	v_add_f32_e32 v149, 1.0, v149
	v_add_f32_e32 v150, 1.0, v150
	v_add_f32_e32 v151, 1.0, v151
	v_add_f32_e32 v152, 1.0, v152
	v_add_f32_e32 v153, 1.0, v153
	v_add_f32_e32 v168, 1.0, v168
	v_add_f32_e32 v169, 1.0, v169
	v_rcp_f32_e32 v148, v148
	v_rcp_f32_e32 v149, v149
	v_rcp_f32_e32 v152, v152
	v_rcp_f32_e32 v153, v153
	s_nop 0
	v_pk_mul_f32 v[148:149], v[148:149], v[150:151]
	v_pk_mul_f32 v[152:153], v[152:153], v[168:169]
	v_pk_mul_f32 v[66:67], v[66:67], v[148:149]
	v_pk_mul_f32 v[68:69], v[68:69], v[152:153]
	s_add_u32 s100, s98, 0x1f4000
	s_addc_u32 s101, s99, 0
	global_load_dwordx4 v[184:187], v243, s[100:101]
	s_add_u32 s100, s98, 0x20d000
	s_addc_u32 s101, s99, 0
	global_load_dwordx4 v[188:191], v243, s[100:101]
	s_add_u32 s100, s98, 0x1f4000
	s_addc_u32 s101, s99, 0
	global_load_dwordx4 v[192:195], v243, s[100:101] offset:2048
	s_add_u32 s100, s98, 0x20d000
	s_addc_u32 s101, s99, 0
	global_load_dwordx4 v[196:199], v243, s[100:101] offset:2048
	s_waitcnt vmcnt(8)
; DI float bflo(unsigned w) { return __uint_as_float(w << 16); }
; DI float bfhi(unsigned w) { return __uint_as_float(w & 0xffff0000u); }
;     DI void operator()(Acc& acc, const Unit& u, int wr, int wc, int fr, int fq) const {
;     ...
;             for (int ai = 0; ai < 2; ++ai)
; #pragma unroll
;                 for (int m = 0; m < 4; ++m)
; #pragma unroll
;                     for (int bj = 0; bj < 2; ++bj) g[ai][m][bj] = *(const u32x4*)(base + (size_t)(ai * 128 + m * 16) * NPJ + u.k * 1024 + bj * 128);
; #pragma unroll
;             for (int ai = 0; ai < 2; ++ai)
; #pragma unroll
;                 for (int m = 0; m < 4; ++m)
; #pragma unroll
;                     for (int bj = 0; bj < 2; ++bj) { const u32x4 q = g[ai][m][bj]; f32x4& v0 = acc[ai][bj][m][0]; f32x4& v1 = acc[ai][bj][m][1];
;                         v0[0] *= bflo(q.x); v0[1] *= bfhi(q.x); v0[2] *= bflo(q.y); v0[3] *= bfhi(q.y); v1[0] *= bflo(q.z); v1[1] *= bfhi(q.z); v1[2] *= bflo(q.w); v1[3] *= bfhi(q.w); }
	v_lshlrev_b32_e32 v148, 16, v200
	v_and_b32_e32 v149, 0xffff0000, v200
	v_lshlrev_b32_e32 v150, 16, v208
	v_and_b32_e32 v151, 0xffff0000, v208
	v_lshlrev_b32_e32 v152, 16, v201
	v_and_b32_e32 v153, 0xffff0000, v201
	v_lshlrev_b32_e32 v168, 16, v209
	v_and_b32_e32 v169, 0xffff0000, v209
	v_pk_mul_f32 v[148:149], v[148:149], v[240:241] op_sel_hi:[1,0]
	v_pk_mul_f32 v[150:151], v[150:151], v[240:241] op_sel_hi:[1,0]
	v_pk_mul_f32 v[152:153], v[152:153], v[240:241] op_sel_hi:[1,0]
	v_pk_mul_f32 v[168:169], v[168:169], v[240:241] op_sel_hi:[1,0]
	v_min_f32_e32 v148, 0x42b80000, v148
	v_min_f32_e32 v149, 0x42b80000, v149
	v_min_f32_e32 v150, 0x42b80000, v150
	v_min_f32_e32 v151, 0x42b80000, v151
	v_min_f32_e32 v152, 0x42b80000, v152
	v_min_f32_e32 v153, 0x42b80000, v153
	v_min_f32_e32 v168, 0x42b80000, v168
	v_min_f32_e32 v169, 0x42b80000, v169
	v_exp_f32_e32 v148, v148
	v_exp_f32_e32 v149, v149
	v_exp_f32_e32 v150, v150
	v_exp_f32_e32 v151, v151
	v_exp_f32_e32 v152, v152
	v_exp_f32_e32 v153, v153
	v_exp_f32_e32 v168, v168
	v_exp_f32_e32 v169, v169
	s_nop 0
	v_add_f32_e32 v148, 1.0, v148
	v_add_f32_e32 v149, 1.0, v149
	v_add_f32_e32 v150, 1.0, v150
	v_add_f32_e32 v151, 1.0, v151
	v_add_f32_e32 v152, 1.0, v152
	v_add_f32_e32 v153, 1.0, v153
	v_add_f32_e32 v168, 1.0, v168
	v_add_f32_e32 v169, 1.0, v169
	v_rcp_f32_e32 v148, v148
	v_rcp_f32_e32 v149, v149
	v_rcp_f32_e32 v152, v152
	v_rcp_f32_e32 v153, v153
	s_nop 0
	v_pk_mul_f32 v[148:149], v[148:149], v[150:151]
	v_pk_mul_f32 v[152:153], v[152:153], v[168:169]
	v_pk_mul_f32 v[62:63], v[62:63], v[148:149]
	v_pk_mul_f32 v[64:65], v[64:65], v[152:153]
	v_lshlrev_b32_e32 v176, 16, v202
	v_and_b32_e32 v177, 0xffff0000, v202
	v_lshlrev_b32_e32 v178, 16, v210
	v_and_b32_e32 v179, 0xffff0000, v210
	v_lshlrev_b32_e32 v180, 16, v203
	v_and_b32_e32 v181, 0xffff0000, v203
	v_lshlrev_b32_e32 v244, 16, v211
	v_and_b32_e32 v245, 0xffff0000, v211
	v_pk_mul_f32 v[176:177], v[176:177], v[240:241] op_sel_hi:[1,0]
	v_pk_mul_f32 v[178:179], v[178:179], v[240:241] op_sel_hi:[1,0]
	v_pk_mul_f32 v[180:181], v[180:181], v[240:241] op_sel_hi:[1,0]
	v_pk_mul_f32 v[244:245], v[244:245], v[240:241] op_sel_hi:[1,0]
	v_min_f32_e32 v176, 0x42b80000, v176
	v_min_f32_e32 v177, 0x42b80000, v177
	v_min_f32_e32 v178, 0x42b80000, v178
	v_min_f32_e32 v179, 0x42b80000, v179
	v_min_f32_e32 v180, 0x42b80000, v180
	v_min_f32_e32 v181, 0x42b80000, v181
	v_min_f32_e32 v244, 0x42b80000, v244
	v_min_f32_e32 v245, 0x42b80000, v245
	v_exp_f32_e32 v176, v176
	v_exp_f32_e32 v177, v177
	v_exp_f32_e32 v178, v178
	v_exp_f32_e32 v179, v179
	v_exp_f32_e32 v180, v180
	v_exp_f32_e32 v181, v181
	v_exp_f32_e32 v244, v244
	v_exp_f32_e32 v245, v245
	s_nop 0
	v_add_f32_e32 v176, 1.0, v176
	v_add_f32_e32 v177, 1.0, v177
	v_add_f32_e32 v178, 1.0, v178
	v_add_f32_e32 v179, 1.0, v179
	v_add_f32_e32 v180, 1.0, v180
	v_add_f32_e32 v181, 1.0, v181
	v_add_f32_e32 v244, 1.0, v244
	v_add_f32_e32 v245, 1.0, v245
	v_rcp_f32_e32 v176, v176
	v_rcp_f32_e32 v177, v177
	v_rcp_f32_e32 v180, v180
	v_rcp_f32_e32 v181, v181
	s_nop 0
	v_pk_mul_f32 v[176:177], v[176:177], v[178:179]
	v_pk_mul_f32 v[180:181], v[180:181], v[244:245]
	v_pk_mul_f32 v[58:59], v[58:59], v[176:177]
	v_pk_mul_f32 v[60:61], v[60:61], v[180:181]
	v_lshlrev_b32_e32 v176, 16, v204
	v_and_b32_e32 v177, 0xffff0000, v204
	v_lshlrev_b32_e32 v178, 16, v212
	v_and_b32_e32 v179, 0xffff0000, v212
	v_lshlrev_b32_e32 v180, 16, v205
	v_and_b32_e32 v181, 0xffff0000, v205
	v_lshlrev_b32_e32 v244, 16, v213
	v_and_b32_e32 v245, 0xffff0000, v213
	v_pk_mul_f32 v[176:177], v[176:177], v[240:241] op_sel_hi:[1,0]
	v_pk_mul_f32 v[178:179], v[178:179], v[240:241] op_sel_hi:[1,0]
	v_pk_mul_f32 v[180:181], v[180:181], v[240:241] op_sel_hi:[1,0]
	v_pk_mul_f32 v[244:245], v[244:245], v[240:241] op_sel_hi:[1,0]
	v_min_f32_e32 v176, 0x42b80000, v176
	v_min_f32_e32 v177, 0x42b80000, v177
	v_min_f32_e32 v178, 0x42b80000, v178
	v_min_f32_e32 v179, 0x42b80000, v179
	v_min_f32_e32 v180, 0x42b80000, v180
	v_min_f32_e32 v181, 0x42b80000, v181
	v_min_f32_e32 v244, 0x42b80000, v244
	v_min_f32_e32 v245, 0x42b80000, v245
	v_exp_f32_e32 v176, v176
	v_exp_f32_e32 v177, v177
	v_exp_f32_e32 v178, v178
	v_exp_f32_e32 v179, v179
	v_exp_f32_e32 v180, v180
	v_exp_f32_e32 v181, v181
	v_exp_f32_e32 v244, v244
	v_exp_f32_e32 v245, v245
	s_nop 0
	v_add_f32_e32 v176, 1.0, v176
	v_add_f32_e32 v177, 1.0, v177
	v_add_f32_e32 v178, 1.0, v178
	v_add_f32_e32 v179, 1.0, v179
	v_add_f32_e32 v180, 1.0, v180
	v_add_f32_e32 v181, 1.0, v181
	v_add_f32_e32 v244, 1.0, v244
	v_add_f32_e32 v245, 1.0, v245
	v_rcp_f32_e32 v176, v176
	v_rcp_f32_e32 v177, v177
	v_rcp_f32_e32 v180, v180
	v_rcp_f32_e32 v181, v181
	s_nop 0
	v_pk_mul_f32 v[176:177], v[176:177], v[178:179]
	v_pk_mul_f32 v[180:181], v[180:181], v[244:245]
	v_pk_mul_f32 v[50:51], v[50:51], v[176:177]
	v_pk_mul_f32 v[52:53], v[52:53], v[180:181]
	v_lshlrev_b32_e32 v148, 16, v206
	v_and_b32_e32 v149, 0xffff0000, v206
	v_lshlrev_b32_e32 v150, 16, v214
	v_and_b32_e32 v151, 0xffff0000, v214
	v_lshlrev_b32_e32 v152, 16, v207
	v_and_b32_e32 v153, 0xffff0000, v207
	v_lshlrev_b32_e32 v168, 16, v215
	v_and_b32_e32 v169, 0xffff0000, v215
	v_pk_mul_f32 v[148:149], v[148:149], v[240:241] op_sel_hi:[1,0]
	v_pk_mul_f32 v[150:151], v[150:151], v[240:241] op_sel_hi:[1,0]
	v_pk_mul_f32 v[152:153], v[152:153], v[240:241] op_sel_hi:[1,0]
	v_pk_mul_f32 v[168:169], v[168:169], v[240:241] op_sel_hi:[1,0]
	v_min_f32_e32 v148, 0x42b80000, v148
	v_min_f32_e32 v149, 0x42b80000, v149
	v_min_f32_e32 v150, 0x42b80000, v150
	v_min_f32_e32 v151, 0x42b80000, v151
	v_min_f32_e32 v152, 0x42b80000, v152
	v_min_f32_e32 v153, 0x42b80000, v153
	v_min_f32_e32 v168, 0x42b80000, v168
	v_min_f32_e32 v169, 0x42b80000, v169
	v_exp_f32_e32 v148, v148
	v_exp_f32_e32 v149, v149
	v_exp_f32_e32 v150, v150
	v_exp_f32_e32 v151, v151
	v_exp_f32_e32 v152, v152
	v_exp_f32_e32 v153, v153
	v_exp_f32_e32 v168, v168
	v_exp_f32_e32 v169, v169
	s_nop 0
	v_add_f32_e32 v148, 1.0, v148
	v_add_f32_e32 v149, 1.0, v149
	v_add_f32_e32 v150, 1.0, v150
	v_add_f32_e32 v151, 1.0, v151
	v_add_f32_e32 v152, 1.0, v152
	v_add_f32_e32 v153, 1.0, v153
	v_add_f32_e32 v168, 1.0, v168
	v_add_f32_e32 v169, 1.0, v169
	v_rcp_f32_e32 v148, v148
	v_rcp_f32_e32 v149, v149
	v_rcp_f32_e32 v152, v152
	v_rcp_f32_e32 v153, v153
	s_nop 0
	v_pk_mul_f32 v[148:149], v[148:149], v[150:151]
	v_pk_mul_f32 v[152:153], v[152:153], v[168:169]
	v_pk_mul_f32 v[42:43], v[42:43], v[148:149]
	v_pk_mul_f32 v[44:45], v[44:45], v[152:153]
	s_add_u32 s100, s98, 0x226000
	s_addc_u32 s101, s99, 0
	global_load_dwordx4 v[200:203], v243, s[100:101]
	s_add_u32 s100, s98, 0x23f000
	s_addc_u32 s101, s99, 0
	global_load_dwordx4 v[204:207], v243, s[100:101]
	s_add_u32 s100, s98, 0x226000
	s_addc_u32 s101, s99, 0
	global_load_dwordx4 v[208:211], v243, s[100:101] offset:2048
	s_add_u32 s100, s98, 0x23f000
	s_addc_u32 s101, s99, 0
	global_load_dwordx4 v[212:215], v243, s[100:101] offset:2048
	s_waitcnt vmcnt(8)
; DI float bflo(unsigned w) { return __uint_as_float(w << 16); }
; DI float bfhi(unsigned w) { return __uint_as_float(w & 0xffff0000u); }
;     DI void operator()(Acc& acc, const Unit& u, int wr, int wc, int fr, int fq) const {
;     ...
;             for (int ai = 0; ai < 2; ++ai)
; #pragma unroll
;                 for (int m = 0; m < 4; ++m)
; #pragma unroll
;                     for (int bj = 0; bj < 2; ++bj) g[ai][m][bj] = *(const u32x4*)(base + (size_t)(ai * 128 + m * 16) * NPJ + u.k * 1024 + bj * 128);
; #pragma unroll
;             for (int ai = 0; ai < 2; ++ai)
; #pragma unroll
;                 for (int m = 0; m < 4; ++m)
; #pragma unroll
;                     for (int bj = 0; bj < 2; ++bj) { const u32x4 q = g[ai][m][bj]; f32x4& v0 = acc[ai][bj][m][0]; f32x4& v1 = acc[ai][bj][m][1];
;                         v0[0] *= bflo(q.x); v0[1] *= bfhi(q.x); v0[2] *= bflo(q.y); v0[3] *= bfhi(q.y); v1[0] *= bflo(q.z); v1[1] *= bfhi(q.z); v1[2] *= bflo(q.w); v1[3] *= bfhi(q.w); }
	v_lshlrev_b32_e32 v148, 16, v216
	v_and_b32_e32 v149, 0xffff0000, v216
	v_lshlrev_b32_e32 v150, 16, v224
	v_and_b32_e32 v151, 0xffff0000, v224
	v_lshlrev_b32_e32 v152, 16, v217
	v_and_b32_e32 v153, 0xffff0000, v217
	v_lshlrev_b32_e32 v168, 16, v225
	v_and_b32_e32 v169, 0xffff0000, v225
	v_pk_mul_f32 v[148:149], v[148:149], v[240:241] op_sel_hi:[1,0]
	v_pk_mul_f32 v[150:151], v[150:151], v[240:241] op_sel_hi:[1,0]
	v_pk_mul_f32 v[152:153], v[152:153], v[240:241] op_sel_hi:[1,0]
	v_pk_mul_f32 v[168:169], v[168:169], v[240:241] op_sel_hi:[1,0]
	v_min_f32_e32 v148, 0x42b80000, v148
	v_min_f32_e32 v149, 0x42b80000, v149
	v_min_f32_e32 v150, 0x42b80000, v150
	v_min_f32_e32 v151, 0x42b80000, v151
	v_min_f32_e32 v152, 0x42b80000, v152
	v_min_f32_e32 v153, 0x42b80000, v153
	v_min_f32_e32 v168, 0x42b80000, v168
	v_min_f32_e32 v169, 0x42b80000, v169
	v_exp_f32_e32 v148, v148
	v_exp_f32_e32 v149, v149
	v_exp_f32_e32 v150, v150
	v_exp_f32_e32 v151, v151
	v_exp_f32_e32 v152, v152
	v_exp_f32_e32 v153, v153
	v_exp_f32_e32 v168, v168
	v_exp_f32_e32 v169, v169
	s_nop 0
	v_add_f32_e32 v148, 1.0, v148
	v_add_f32_e32 v149, 1.0, v149
	v_add_f32_e32 v150, 1.0, v150
	v_add_f32_e32 v151, 1.0, v151
	v_add_f32_e32 v152, 1.0, v152
	v_add_f32_e32 v153, 1.0, v153
	v_add_f32_e32 v168, 1.0, v168
	v_add_f32_e32 v169, 1.0, v169
	v_rcp_f32_e32 v148, v148
	v_rcp_f32_e32 v149, v149
	v_rcp_f32_e32 v152, v152
	v_rcp_f32_e32 v153, v153
	s_nop 0
	v_pk_mul_f32 v[148:149], v[148:149], v[150:151]
	v_pk_mul_f32 v[152:153], v[152:153], v[168:169]
	v_pk_mul_f32 v[54:55], v[54:55], v[148:149]
	v_pk_mul_f32 v[56:57], v[56:57], v[152:153]
	v_lshlrev_b32_e32 v176, 16, v218
	v_and_b32_e32 v177, 0xffff0000, v218
	v_lshlrev_b32_e32 v178, 16, v226
	v_and_b32_e32 v179, 0xffff0000, v226
	v_lshlrev_b32_e32 v180, 16, v219
	v_and_b32_e32 v181, 0xffff0000, v219
	v_lshlrev_b32_e32 v244, 16, v227
	v_and_b32_e32 v245, 0xffff0000, v227
	v_pk_mul_f32 v[176:177], v[176:177], v[240:241] op_sel_hi:[1,0]
	v_pk_mul_f32 v[178:179], v[178:179], v[240:241] op_sel_hi:[1,0]
	v_pk_mul_f32 v[180:181], v[180:181], v[240:241] op_sel_hi:[1,0]
	v_pk_mul_f32 v[244:245], v[244:245], v[240:241] op_sel_hi:[1,0]
	v_min_f32_e32 v176, 0x42b80000, v176
	v_min_f32_e32 v177, 0x42b80000, v177
	v_min_f32_e32 v178, 0x42b80000, v178
	v_min_f32_e32 v179, 0x42b80000, v179
	v_min_f32_e32 v180, 0x42b80000, v180
	v_min_f32_e32 v181, 0x42b80000, v181
	v_min_f32_e32 v244, 0x42b80000, v244
	v_min_f32_e32 v245, 0x42b80000, v245
	v_exp_f32_e32 v176, v176
	v_exp_f32_e32 v177, v177
	v_exp_f32_e32 v178, v178
	v_exp_f32_e32 v179, v179
	v_exp_f32_e32 v180, v180
	v_exp_f32_e32 v181, v181
	v_exp_f32_e32 v244, v244
	v_exp_f32_e32 v245, v245
	s_nop 0
	v_add_f32_e32 v176, 1.0, v176
	v_add_f32_e32 v177, 1.0, v177
	v_add_f32_e32 v178, 1.0, v178
	v_add_f32_e32 v179, 1.0, v179
	v_add_f32_e32 v180, 1.0, v180
	v_add_f32_e32 v181, 1.0, v181
	v_add_f32_e32 v244, 1.0, v244
	v_add_f32_e32 v245, 1.0, v245
	v_rcp_f32_e32 v176, v176
	v_rcp_f32_e32 v177, v177
	v_rcp_f32_e32 v180, v180
	v_rcp_f32_e32 v181, v181
	s_nop 0
	v_pk_mul_f32 v[176:177], v[176:177], v[178:179]
	v_pk_mul_f32 v[180:181], v[180:181], v[244:245]
	v_pk_mul_f32 v[46:47], v[46:47], v[176:177]
	v_pk_mul_f32 v[48:49], v[48:49], v[180:181]
	v_lshlrev_b32_e32 v176, 16, v220
	v_and_b32_e32 v177, 0xffff0000, v220
	v_lshlrev_b32_e32 v178, 16, v228
	v_and_b32_e32 v179, 0xffff0000, v228
	v_lshlrev_b32_e32 v180, 16, v221
	v_and_b32_e32 v181, 0xffff0000, v221
	v_lshlrev_b32_e32 v244, 16, v229
	v_and_b32_e32 v245, 0xffff0000, v229
	v_pk_mul_f32 v[176:177], v[176:177], v[240:241] op_sel_hi:[1,0]
	v_pk_mul_f32 v[178:179], v[178:179], v[240:241] op_sel_hi:[1,0]
	v_pk_mul_f32 v[180:181], v[180:181], v[240:241] op_sel_hi:[1,0]
	v_pk_mul_f32 v[244:245], v[244:245], v[240:241] op_sel_hi:[1,0]
	v_min_f32_e32 v176, 0x42b80000, v176
	v_min_f32_e32 v177, 0x42b80000, v177
	v_min_f32_e32 v178, 0x42b80000, v178
	v_min_f32_e32 v179, 0x42b80000, v179
	v_min_f32_e32 v180, 0x42b80000, v180
	v_min_f32_e32 v181, 0x42b80000, v181
	v_min_f32_e32 v244, 0x42b80000, v244
	v_min_f32_e32 v245, 0x42b80000, v245
	v_exp_f32_e32 v176, v176
	v_exp_f32_e32 v177, v177
	v_exp_f32_e32 v178, v178
	v_exp_f32_e32 v179, v179
	v_exp_f32_e32 v180, v180
	v_exp_f32_e32 v181, v181
	v_exp_f32_e32 v244, v244
	v_exp_f32_e32 v245, v245
	s_nop 0
	v_add_f32_e32 v176, 1.0, v176
	v_add_f32_e32 v177, 1.0, v177
	v_add_f32_e32 v178, 1.0, v178
	v_add_f32_e32 v179, 1.0, v179
	v_add_f32_e32 v180, 1.0, v180
	v_add_f32_e32 v181, 1.0, v181
	v_add_f32_e32 v244, 1.0, v244
	v_add_f32_e32 v245, 1.0, v245
	v_rcp_f32_e32 v176, v176
	v_rcp_f32_e32 v177, v177
	v_rcp_f32_e32 v180, v180
	v_rcp_f32_e32 v181, v181
	s_nop 0
	v_pk_mul_f32 v[176:177], v[176:177], v[178:179]
	v_pk_mul_f32 v[180:181], v[180:181], v[244:245]
	v_pk_mul_f32 v[34:35], v[34:35], v[176:177]
	v_pk_mul_f32 v[36:37], v[36:37], v[180:181]
	v_lshlrev_b32_e32 v148, 16, v222
	v_and_b32_e32 v149, 0xffff0000, v222
	v_lshlrev_b32_e32 v150, 16, v230
	v_and_b32_e32 v151, 0xffff0000, v230
	v_lshlrev_b32_e32 v152, 16, v223
	v_and_b32_e32 v153, 0xffff0000, v223
	v_lshlrev_b32_e32 v168, 16, v231
	v_and_b32_e32 v169, 0xffff0000, v231
	v_pk_mul_f32 v[148:149], v[148:149], v[240:241] op_sel_hi:[1,0]
	v_pk_mul_f32 v[150:151], v[150:151], v[240:241] op_sel_hi:[1,0]
	v_pk_mul_f32 v[152:153], v[152:153], v[240:241] op_sel_hi:[1,0]
	v_pk_mul_f32 v[168:169], v[168:169], v[240:241] op_sel_hi:[1,0]
	v_min_f32_e32 v148, 0x42b80000, v148
	v_min_f32_e32 v149, 0x42b80000, v149
	v_min_f32_e32 v150, 0x42b80000, v150
	v_min_f32_e32 v151, 0x42b80000, v151
	v_min_f32_e32 v152, 0x42b80000, v152
	v_min_f32_e32 v153, 0x42b80000, v153
	v_min_f32_e32 v168, 0x42b80000, v168
	v_min_f32_e32 v169, 0x42b80000, v169
	v_exp_f32_e32 v148, v148
	v_exp_f32_e32 v149, v149
	v_exp_f32_e32 v150, v150
	v_exp_f32_e32 v151, v151
	v_exp_f32_e32 v152, v152
	v_exp_f32_e32 v153, v153
	v_exp_f32_e32 v168, v168
	v_exp_f32_e32 v169, v169
	s_nop 0
	v_add_f32_e32 v148, 1.0, v148
	v_add_f32_e32 v149, 1.0, v149
	v_add_f32_e32 v150, 1.0, v150
	v_add_f32_e32 v151, 1.0, v151
	v_add_f32_e32 v152, 1.0, v152
	v_add_f32_e32 v153, 1.0, v153
	v_add_f32_e32 v168, 1.0, v168
	v_add_f32_e32 v169, 1.0, v169
	v_rcp_f32_e32 v148, v148
	v_rcp_f32_e32 v149, v149
	v_rcp_f32_e32 v152, v152
	v_rcp_f32_e32 v153, v153
	s_nop 0
	v_pk_mul_f32 v[148:149], v[148:149], v[150:151]
	v_pk_mul_f32 v[152:153], v[152:153], v[168:169]
	v_pk_mul_f32 v[26:27], v[26:27], v[148:149]
	v_pk_mul_f32 v[28:29], v[28:29], v[152:153]
	s_waitcnt vmcnt(4)
; DI float bflo(unsigned w) { return __uint_as_float(w << 16); }
; DI float bfhi(unsigned w) { return __uint_as_float(w & 0xffff0000u); }
;     DI void operator()(Acc& acc, const Unit& u, int wr, int wc, int fr, int fq) const {
;     ...
;             for (int ai = 0; ai < 2; ++ai)
; #pragma unroll
;                 for (int m = 0; m < 4; ++m)
; #pragma unroll
;                     for (int bj = 0; bj < 2; ++bj) g[ai][m][bj] = *(const u32x4*)(base + (size_t)(ai * 128 + m * 16) * NPJ + u.k * 1024 + bj * 128);
; #pragma unroll
;             for (int ai = 0; ai < 2; ++ai)
; #pragma unroll
;                 for (int m = 0; m < 4; ++m)
; #pragma unroll
;                     for (int bj = 0; bj < 2; ++bj) { const u32x4 q = g[ai][m][bj]; f32x4& v0 = acc[ai][bj][m][0]; f32x4& v1 = acc[ai][bj][m][1];
;                         v0[0] *= bflo(q.x); v0[1] *= bfhi(q.x); v0[2] *= bflo(q.y); v0[3] *= bfhi(q.y); v1[0] *= bflo(q.z); v1[1] *= bfhi(q.z); v1[2] *= bflo(q.w); v1[3] *= bfhi(q.w); }
	v_lshlrev_b32_e32 v148, 16, v184
	v_and_b32_e32 v149, 0xffff0000, v184
	v_lshlrev_b32_e32 v150, 16, v192
	v_and_b32_e32 v151, 0xffff0000, v192
	v_lshlrev_b32_e32 v152, 16, v185
	v_and_b32_e32 v153, 0xffff0000, v185
	v_lshlrev_b32_e32 v168, 16, v193
	v_and_b32_e32 v169, 0xffff0000, v193
	v_pk_mul_f32 v[148:149], v[148:149], v[240:241] op_sel_hi:[1,0]
	v_pk_mul_f32 v[150:151], v[150:151], v[240:241] op_sel_hi:[1,0]
	v_pk_mul_f32 v[152:153], v[152:153], v[240:241] op_sel_hi:[1,0]
	v_pk_mul_f32 v[168:169], v[168:169], v[240:241] op_sel_hi:[1,0]
	v_min_f32_e32 v148, 0x42b80000, v148
	v_min_f32_e32 v149, 0x42b80000, v149
	v_min_f32_e32 v150, 0x42b80000, v150
	v_min_f32_e32 v151, 0x42b80000, v151
	v_min_f32_e32 v152, 0x42b80000, v152
	v_min_f32_e32 v153, 0x42b80000, v153
	v_min_f32_e32 v168, 0x42b80000, v168
	v_min_f32_e32 v169, 0x42b80000, v169
	v_exp_f32_e32 v148, v148
	v_exp_f32_e32 v149, v149
	v_exp_f32_e32 v150, v150
	v_exp_f32_e32 v151, v151
	v_exp_f32_e32 v152, v152
	v_exp_f32_e32 v153, v153
	v_exp_f32_e32 v168, v168
	v_exp_f32_e32 v169, v169
	s_nop 0
	v_add_f32_e32 v148, 1.0, v148
	v_add_f32_e32 v149, 1.0, v149
	v_add_f32_e32 v150, 1.0, v150
	v_add_f32_e32 v151, 1.0, v151
	v_add_f32_e32 v152, 1.0, v152
	v_add_f32_e32 v153, 1.0, v153
	v_add_f32_e32 v168, 1.0, v168
	v_add_f32_e32 v169, 1.0, v169
	v_rcp_f32_e32 v148, v148
	v_rcp_f32_e32 v149, v149
	v_rcp_f32_e32 v152, v152
	v_rcp_f32_e32 v153, v153
	s_nop 0
	v_pk_mul_f32 v[148:149], v[148:149], v[150:151]
	v_pk_mul_f32 v[152:153], v[152:153], v[168:169]
	v_pk_mul_f32 v[38:39], v[38:39], v[148:149]
	v_pk_mul_f32 v[40:41], v[40:41], v[152:153]
	v_lshlrev_b32_e32 v176, 16, v186
	v_and_b32_e32 v177, 0xffff0000, v186
	v_lshlrev_b32_e32 v178, 16, v194
	v_and_b32_e32 v179, 0xffff0000, v194
	v_lshlrev_b32_e32 v180, 16, v187
	v_and_b32_e32 v181, 0xffff0000, v187
	v_lshlrev_b32_e32 v244, 16, v195
	v_and_b32_e32 v245, 0xffff0000, v195
	v_pk_mul_f32 v[176:177], v[176:177], v[240:241] op_sel_hi:[1,0]
	v_pk_mul_f32 v[178:179], v[178:179], v[240:241] op_sel_hi:[1,0]
	v_pk_mul_f32 v[180:181], v[180:181], v[240:241] op_sel_hi:[1,0]
	v_pk_mul_f32 v[244:245], v[244:245], v[240:241] op_sel_hi:[1,0]
	v_min_f32_e32 v176, 0x42b80000, v176
	v_min_f32_e32 v177, 0x42b80000, v177
	v_min_f32_e32 v178, 0x42b80000, v178
	v_min_f32_e32 v179, 0x42b80000, v179
	v_min_f32_e32 v180, 0x42b80000, v180
	v_min_f32_e32 v181, 0x42b80000, v181
	v_min_f32_e32 v244, 0x42b80000, v244
	v_min_f32_e32 v245, 0x42b80000, v245
	v_exp_f32_e32 v176, v176
	v_exp_f32_e32 v177, v177
	v_exp_f32_e32 v178, v178
	v_exp_f32_e32 v179, v179
	v_exp_f32_e32 v180, v180
	v_exp_f32_e32 v181, v181
	v_exp_f32_e32 v244, v244
	v_exp_f32_e32 v245, v245
	s_nop 0
	v_add_f32_e32 v176, 1.0, v176
	v_add_f32_e32 v177, 1.0, v177
	v_add_f32_e32 v178, 1.0, v178
	v_add_f32_e32 v179, 1.0, v179
	v_add_f32_e32 v180, 1.0, v180
	v_add_f32_e32 v181, 1.0, v181
	v_add_f32_e32 v244, 1.0, v244
	v_add_f32_e32 v245, 1.0, v245
	v_rcp_f32_e32 v176, v176
	v_rcp_f32_e32 v177, v177
	v_rcp_f32_e32 v180, v180
	v_rcp_f32_e32 v181, v181
	s_nop 0
	v_pk_mul_f32 v[176:177], v[176:177], v[178:179]
	v_pk_mul_f32 v[180:181], v[180:181], v[244:245]
	v_pk_mul_f32 v[30:31], v[30:31], v[176:177]
	v_pk_mul_f32 v[32:33], v[32:33], v[180:181]
	v_lshlrev_b32_e32 v176, 16, v188
	v_and_b32_e32 v177, 0xffff0000, v188
	v_lshlrev_b32_e32 v178, 16, v196
	v_and_b32_e32 v179, 0xffff0000, v196
	v_lshlrev_b32_e32 v180, 16, v189
	v_and_b32_e32 v181, 0xffff0000, v189
	v_lshlrev_b32_e32 v244, 16, v197
	v_and_b32_e32 v245, 0xffff0000, v197
	v_pk_mul_f32 v[176:177], v[176:177], v[240:241] op_sel_hi:[1,0]
	v_pk_mul_f32 v[178:179], v[178:179], v[240:241] op_sel_hi:[1,0]
	v_pk_mul_f32 v[180:181], v[180:181], v[240:241] op_sel_hi:[1,0]
	v_pk_mul_f32 v[244:245], v[244:245], v[240:241] op_sel_hi:[1,0]
	v_min_f32_e32 v176, 0x42b80000, v176
	v_min_f32_e32 v177, 0x42b80000, v177
	v_min_f32_e32 v178, 0x42b80000, v178
	v_min_f32_e32 v179, 0x42b80000, v179
	v_min_f32_e32 v180, 0x42b80000, v180
	v_min_f32_e32 v181, 0x42b80000, v181
	v_min_f32_e32 v244, 0x42b80000, v244
	v_min_f32_e32 v245, 0x42b80000, v245
	v_exp_f32_e32 v176, v176
	v_exp_f32_e32 v177, v177
	v_exp_f32_e32 v178, v178
	v_exp_f32_e32 v179, v179
	v_exp_f32_e32 v180, v180
	v_exp_f32_e32 v181, v181
	v_exp_f32_e32 v244, v244
	v_exp_f32_e32 v245, v245
	s_nop 0
	v_add_f32_e32 v176, 1.0, v176
	v_add_f32_e32 v177, 1.0, v177
	v_add_f32_e32 v178, 1.0, v178
	v_add_f32_e32 v179, 1.0, v179
	v_add_f32_e32 v180, 1.0, v180
	v_add_f32_e32 v181, 1.0, v181
	v_add_f32_e32 v244, 1.0, v244
	v_add_f32_e32 v245, 1.0, v245
	v_rcp_f32_e32 v176, v176
	v_rcp_f32_e32 v177, v177
	v_rcp_f32_e32 v180, v180
	v_rcp_f32_e32 v181, v181
	s_nop 0
	v_pk_mul_f32 v[176:177], v[176:177], v[178:179]
	v_pk_mul_f32 v[180:181], v[180:181], v[244:245]
	v_pk_mul_f32 v[18:19], v[18:19], v[176:177]
	v_pk_mul_f32 v[20:21], v[20:21], v[180:181]
	v_lshlrev_b32_e32 v148, 16, v190
	v_and_b32_e32 v149, 0xffff0000, v190
	v_lshlrev_b32_e32 v150, 16, v198
	v_and_b32_e32 v151, 0xffff0000, v198
	v_lshlrev_b32_e32 v152, 16, v191
	v_and_b32_e32 v153, 0xffff0000, v191
	v_lshlrev_b32_e32 v168, 16, v199
	v_and_b32_e32 v169, 0xffff0000, v199
	v_pk_mul_f32 v[148:149], v[148:149], v[240:241] op_sel_hi:[1,0]
	v_pk_mul_f32 v[150:151], v[150:151], v[240:241] op_sel_hi:[1,0]
	v_pk_mul_f32 v[152:153], v[152:153], v[240:241] op_sel_hi:[1,0]
	v_pk_mul_f32 v[168:169], v[168:169], v[240:241] op_sel_hi:[1,0]
	v_min_f32_e32 v148, 0x42b80000, v148
	v_min_f32_e32 v149, 0x42b80000, v149
	v_min_f32_e32 v150, 0x42b80000, v150
	v_min_f32_e32 v151, 0x42b80000, v151
	v_min_f32_e32 v152, 0x42b80000, v152
	v_min_f32_e32 v153, 0x42b80000, v153
	v_min_f32_e32 v168, 0x42b80000, v168
	v_min_f32_e32 v169, 0x42b80000, v169
	v_exp_f32_e32 v148, v148
	v_exp_f32_e32 v149, v149
	v_exp_f32_e32 v150, v150
	v_exp_f32_e32 v151, v151
	v_exp_f32_e32 v152, v152
	v_exp_f32_e32 v153, v153
	v_exp_f32_e32 v168, v168
	v_exp_f32_e32 v169, v169
	s_nop 0
	v_add_f32_e32 v148, 1.0, v148
	v_add_f32_e32 v149, 1.0, v149
	v_add_f32_e32 v150, 1.0, v150
	v_add_f32_e32 v151, 1.0, v151
	v_add_f32_e32 v152, 1.0, v152
	v_add_f32_e32 v153, 1.0, v153
	v_add_f32_e32 v168, 1.0, v168
	v_add_f32_e32 v169, 1.0, v169
	v_rcp_f32_e32 v148, v148
	v_rcp_f32_e32 v149, v149
	v_rcp_f32_e32 v152, v152
	v_rcp_f32_e32 v153, v153
	s_nop 0
	v_pk_mul_f32 v[148:149], v[148:149], v[150:151]
	v_pk_mul_f32 v[152:153], v[152:153], v[168:169]
	v_pk_mul_f32 v[10:11], v[10:11], v[148:149]
	v_pk_mul_f32 v[12:13], v[12:13], v[152:153]
	s_waitcnt vmcnt(0)
; DI float bflo(unsigned w) { return __uint_as_float(w << 16); }
; DI float bfhi(unsigned w) { return __uint_as_float(w & 0xffff0000u); }
;     DI void operator()(Acc& acc, const Unit& u, int wr, int wc, int fr, int fq) const {
;     ...
;             for (int ai = 0; ai < 2; ++ai)
; #pragma unroll
;                 for (int m = 0; m < 4; ++m)
; #pragma unroll
;                     for (int bj = 0; bj < 2; ++bj) g[ai][m][bj] = *(const u32x4*)(base + (size_t)(ai * 128 + m * 16) * NPJ + u.k * 1024 + bj * 128);
; #pragma unroll
;             for (int ai = 0; ai < 2; ++ai)
; #pragma unroll
;                 for (int m = 0; m < 4; ++m)
; #pragma unroll
;                     for (int bj = 0; bj < 2; ++bj) { const u32x4 q = g[ai][m][bj]; f32x4& v0 = acc[ai][bj][m][0]; f32x4& v1 = acc[ai][bj][m][1];
;                         v0[0] *= bflo(q.x); v0[1] *= bfhi(q.x); v0[2] *= bflo(q.y); v0[3] *= bfhi(q.y); v1[0] *= bflo(q.z); v1[1] *= bfhi(q.z); v1[2] *= bflo(q.w); v1[3] *= bfhi(q.w); }
	v_lshlrev_b32_e32 v148, 16, v200
	v_and_b32_e32 v149, 0xffff0000, v200
	v_lshlrev_b32_e32 v150, 16, v208
	v_and_b32_e32 v151, 0xffff0000, v208
	v_lshlrev_b32_e32 v152, 16, v201
	v_and_b32_e32 v153, 0xffff0000, v201
	v_lshlrev_b32_e32 v168, 16, v209
	v_and_b32_e32 v169, 0xffff0000, v209
	v_pk_mul_f32 v[148:149], v[148:149], v[240:241] op_sel_hi:[1,0]
	v_pk_mul_f32 v[150:151], v[150:151], v[240:241] op_sel_hi:[1,0]
	v_pk_mul_f32 v[152:153], v[152:153], v[240:241] op_sel_hi:[1,0]
	v_pk_mul_f32 v[168:169], v[168:169], v[240:241] op_sel_hi:[1,0]
	v_min_f32_e32 v148, 0x42b80000, v148
	v_min_f32_e32 v149, 0x42b80000, v149
	v_min_f32_e32 v150, 0x42b80000, v150
	v_min_f32_e32 v151, 0x42b80000, v151
	v_min_f32_e32 v152, 0x42b80000, v152
	v_min_f32_e32 v153, 0x42b80000, v153
	v_min_f32_e32 v168, 0x42b80000, v168
	v_min_f32_e32 v169, 0x42b80000, v169
	v_exp_f32_e32 v148, v148
	v_exp_f32_e32 v149, v149
	v_exp_f32_e32 v150, v150
	v_exp_f32_e32 v151, v151
	v_exp_f32_e32 v152, v152
	v_exp_f32_e32 v153, v153
	v_exp_f32_e32 v168, v168
	v_exp_f32_e32 v169, v169
	s_nop 0
	v_add_f32_e32 v148, 1.0, v148
	v_add_f32_e32 v149, 1.0, v149
	v_add_f32_e32 v150, 1.0, v150
	v_add_f32_e32 v151, 1.0, v151
	v_add_f32_e32 v152, 1.0, v152
	v_add_f32_e32 v153, 1.0, v153
	v_add_f32_e32 v168, 1.0, v168
	v_add_f32_e32 v169, 1.0, v169
	v_rcp_f32_e32 v148, v148
	v_rcp_f32_e32 v149, v149
	v_rcp_f32_e32 v152, v152
	v_rcp_f32_e32 v153, v153
	s_nop 0
	v_pk_mul_f32 v[148:149], v[148:149], v[150:151]
	v_pk_mul_f32 v[152:153], v[152:153], v[168:169]
	v_pk_mul_f32 v[22:23], v[22:23], v[148:149]
	v_pk_mul_f32 v[24:25], v[24:25], v[152:153]
	v_lshlrev_b32_e32 v176, 16, v202
	v_and_b32_e32 v177, 0xffff0000, v202
	v_lshlrev_b32_e32 v178, 16, v210
	v_and_b32_e32 v179, 0xffff0000, v210
	v_lshlrev_b32_e32 v180, 16, v203
	v_and_b32_e32 v181, 0xffff0000, v203
	v_lshlrev_b32_e32 v244, 16, v211
	v_and_b32_e32 v245, 0xffff0000, v211
	v_pk_mul_f32 v[176:177], v[176:177], v[240:241] op_sel_hi:[1,0]
	v_pk_mul_f32 v[178:179], v[178:179], v[240:241] op_sel_hi:[1,0]
	v_pk_mul_f32 v[180:181], v[180:181], v[240:241] op_sel_hi:[1,0]
	v_pk_mul_f32 v[244:245], v[244:245], v[240:241] op_sel_hi:[1,0]
	v_min_f32_e32 v176, 0x42b80000, v176
	v_min_f32_e32 v177, 0x42b80000, v177
	v_min_f32_e32 v178, 0x42b80000, v178
	v_min_f32_e32 v179, 0x42b80000, v179
	v_min_f32_e32 v180, 0x42b80000, v180
	v_min_f32_e32 v181, 0x42b80000, v181
	v_min_f32_e32 v244, 0x42b80000, v244
	v_min_f32_e32 v245, 0x42b80000, v245
	v_exp_f32_e32 v176, v176
	v_exp_f32_e32 v177, v177
	v_exp_f32_e32 v178, v178
	v_exp_f32_e32 v179, v179
	v_exp_f32_e32 v180, v180
	v_exp_f32_e32 v181, v181
	v_exp_f32_e32 v244, v244
	v_exp_f32_e32 v245, v245
	s_nop 0
	v_add_f32_e32 v176, 1.0, v176
	v_add_f32_e32 v177, 1.0, v177
	v_add_f32_e32 v178, 1.0, v178
	v_add_f32_e32 v179, 1.0, v179
	v_add_f32_e32 v180, 1.0, v180
	v_add_f32_e32 v181, 1.0, v181
	v_add_f32_e32 v244, 1.0, v244
	v_add_f32_e32 v245, 1.0, v245
	v_rcp_f32_e32 v176, v176
	v_rcp_f32_e32 v177, v177
	v_rcp_f32_e32 v180, v180
	v_rcp_f32_e32 v181, v181
	s_nop 0
	v_pk_mul_f32 v[176:177], v[176:177], v[178:179]
	v_pk_mul_f32 v[180:181], v[180:181], v[244:245]
	v_pk_mul_f32 v[14:15], v[14:15], v[176:177]
	v_pk_mul_f32 v[16:17], v[16:17], v[180:181]
	v_lshlrev_b32_e32 v176, 16, v204
	v_and_b32_e32 v177, 0xffff0000, v204
	v_lshlrev_b32_e32 v178, 16, v212
	v_and_b32_e32 v179, 0xffff0000, v212
	v_lshlrev_b32_e32 v180, 16, v205
	v_and_b32_e32 v181, 0xffff0000, v205
	v_lshlrev_b32_e32 v244, 16, v213
	v_and_b32_e32 v245, 0xffff0000, v213
	v_pk_mul_f32 v[176:177], v[176:177], v[240:241] op_sel_hi:[1,0]
	v_pk_mul_f32 v[178:179], v[178:179], v[240:241] op_sel_hi:[1,0]
	v_pk_mul_f32 v[180:181], v[180:181], v[240:241] op_sel_hi:[1,0]
	v_pk_mul_f32 v[244:245], v[244:245], v[240:241] op_sel_hi:[1,0]
	v_min_f32_e32 v176, 0x42b80000, v176
	v_min_f32_e32 v177, 0x42b80000, v177
	v_min_f32_e32 v178, 0x42b80000, v178
	v_min_f32_e32 v179, 0x42b80000, v179
	v_min_f32_e32 v180, 0x42b80000, v180
	v_min_f32_e32 v181, 0x42b80000, v181
	v_min_f32_e32 v244, 0x42b80000, v244
	v_min_f32_e32 v245, 0x42b80000, v245
	v_exp_f32_e32 v176, v176
	v_exp_f32_e32 v177, v177
	v_exp_f32_e32 v178, v178
	v_exp_f32_e32 v179, v179
	v_exp_f32_e32 v180, v180
	v_exp_f32_e32 v181, v181
	v_exp_f32_e32 v244, v244
	v_exp_f32_e32 v245, v245
	s_nop 0
	v_add_f32_e32 v176, 1.0, v176
	v_add_f32_e32 v177, 1.0, v177
	v_add_f32_e32 v178, 1.0, v178
	v_add_f32_e32 v179, 1.0, v179
	v_add_f32_e32 v180, 1.0, v180
	v_add_f32_e32 v181, 1.0, v181
	v_add_f32_e32 v244, 1.0, v244
	v_add_f32_e32 v245, 1.0, v245
	v_rcp_f32_e32 v176, v176
	v_rcp_f32_e32 v177, v177
	v_rcp_f32_e32 v180, v180
	v_rcp_f32_e32 v181, v181
	s_nop 0
	v_pk_mul_f32 v[176:177], v[176:177], v[178:179]
	v_pk_mul_f32 v[180:181], v[180:181], v[244:245]
	v_pk_mul_f32 v[6:7], v[6:7], v[176:177]
	v_pk_mul_f32 v[8:9], v[8:9], v[180:181]
	v_lshlrev_b32_e32 v148, 16, v206
	v_and_b32_e32 v149, 0xffff0000, v206
	v_lshlrev_b32_e32 v150, 16, v214
	v_and_b32_e32 v151, 0xffff0000, v214
	v_lshlrev_b32_e32 v152, 16, v207
	v_and_b32_e32 v153, 0xffff0000, v207
	v_lshlrev_b32_e32 v168, 16, v215
	v_and_b32_e32 v169, 0xffff0000, v215
	v_pk_mul_f32 v[148:149], v[148:149], v[240:241] op_sel_hi:[1,0]
	v_pk_mul_f32 v[150:151], v[150:151], v[240:241] op_sel_hi:[1,0]
	v_pk_mul_f32 v[152:153], v[152:153], v[240:241] op_sel_hi:[1,0]
	v_pk_mul_f32 v[168:169], v[168:169], v[240:241] op_sel_hi:[1,0]
	v_min_f32_e32 v148, 0x42b80000, v148
	v_min_f32_e32 v149, 0x42b80000, v149
	v_min_f32_e32 v150, 0x42b80000, v150
	v_min_f32_e32 v151, 0x42b80000, v151
	v_min_f32_e32 v152, 0x42b80000, v152
	v_min_f32_e32 v153, 0x42b80000, v153
	v_min_f32_e32 v168, 0x42b80000, v168
	v_min_f32_e32 v169, 0x42b80000, v169
	v_exp_f32_e32 v148, v148
	v_exp_f32_e32 v149, v149
	v_exp_f32_e32 v150, v150
	v_exp_f32_e32 v151, v151
	v_exp_f32_e32 v152, v152
	v_exp_f32_e32 v153, v153
	v_exp_f32_e32 v168, v168
	v_exp_f32_e32 v169, v169
	s_nop 0
	v_add_f32_e32 v148, 1.0, v148
	v_add_f32_e32 v149, 1.0, v149
	v_add_f32_e32 v150, 1.0, v150
	v_add_f32_e32 v151, 1.0, v151
	v_add_f32_e32 v152, 1.0, v152
	v_add_f32_e32 v153, 1.0, v153
	v_add_f32_e32 v168, 1.0, v168
	v_add_f32_e32 v169, 1.0, v169
	v_rcp_f32_e32 v148, v148
	v_rcp_f32_e32 v149, v149
	v_rcp_f32_e32 v152, v152
	v_rcp_f32_e32 v153, v153
	s_nop 0
	v_pk_mul_f32 v[148:149], v[148:149], v[150:151]
	v_pk_mul_f32 v[152:153], v[152:153], v[168:169]
	v_pk_mul_f32 v[2:3], v[2:3], v[148:149]
	v_pk_mul_f32 v[4:5], v[4:5], v[152:153]
	s_branch .Lup6_tail
; DI float bflo(unsigned w) { return __uint_as_float(w << 16); }
; DI float bfhi(unsigned w) { return __uint_as_float(w & 0xffff0000u); }
;     DI void operator()(Acc& acc, const Unit& u, int wr, int wc, int fr, int fq) const {
;     ...
;         bf16_t* base = proj + (size_t)(u.pm * 256 + wr * 64 + fr) * NPJ + C_GL + u.pn * 256 + wc * 32 + fq * 8;
;         {
;             u32x4 g[2][4][2];
; #pragma unroll
;             for (int ai = 0; ai < 2; ++ai)
; #pragma unroll
;                 for (int m = 0; m < 4; ++m)
; #pragma unroll
;                     for (int bj = 0; bj < 2; ++bj) g[ai][m][bj] = *(const u32x4*)(base + (size_t)(ai * 128 + m * 16) * NPJ + u.k * 1024 + bj * 128);
; #pragma unroll
;             for (int ai = 0; ai < 2; ++ai)
; #pragma unroll
;                 for (int m = 0; m < 4; ++m)
; #pragma unroll
;                     for (int bj = 0; bj < 2; ++bj) { const u32x4 q = g[ai][m][bj]; f32x4& v0 = acc[ai][bj][m][0]; f32x4& v1 = acc[ai][bj][m][1];
;                         v0[0] *= bflo(q.x); v0[1] *= bfhi(q.x); v0[2] *= bflo(q.y); v0[3] *= bfhi(q.y); v1[0] *= bflo(q.z); v1[1] *= bfhi(q.z); v1[2] *= bflo(q.w); v1[3] *= bfhi(q.w); }
;         }
;         if (u.k > 0) {
;             u32x4 g[2][4][2];
; #pragma unroll
;             for (int ai = 0; ai < 2; ++ai)
; #pragma unroll
;                 for (int m = 0; m < 4; ++m)
; #pragma unroll
;                     for (int bj = 0; bj < 2; ++bj) g[ai][m][bj] = *(const u32x4*)(base + (size_t)(ai * 128 + m * 16) * NPJ + bj * 128);
; #pragma unroll
;             for (int ai = 0; ai < 2; ++ai)
; #pragma unroll
;                 for (int m = 0; m < 4; ++m)
; #pragma unroll
;                     for (int bj = 0; bj < 2; ++bj) { const u32x4 q = g[ai][m][bj]; f32x4& v0 = acc[ai][bj][m][0]; f32x4& v1 = acc[ai][bj][m][1];
;                         v0[0] += bflo(q.x); v0[1] += bfhi(q.x); v0[2] += bflo(q.y); v0[3] += bfhi(q.y); v1[0] += bflo(q.z); v1[1] += bfhi(q.z); v1[2] += bflo(q.w); v1[3] += bfhi(q.w); }
;         }
;         if (!dry) {
; #pragma unroll
;             for (int ai = 0; ai < 2; ++ai)
; #pragma unroll
;                 for (int m = 0; m < 4; ++m)
; #pragma unroll
;                     for (int bj = 0; bj < 2; ++bj) *(u32x4*)(base + (size_t)(ai * 128 + m * 16) * NPJ + bj * 128) = pack8(acc[ai][bj][m][0], acc[ai][bj][m][1]);
.Lup6_final:
	s_mov_b32 s101, 0
	s_mov_b32 s100, 0x32000
	v_lshl_add_u64 v[132:133], v[166:167], 0, s[100:101]
	s_mov_b32 s100, 0x64000
	v_lshl_add_u64 v[134:135], v[166:167], 0, s[100:101]
	s_mov_b32 s100, 0x96000
	v_lshl_add_u64 v[136:137], v[166:167], 0, s[100:101]
	s_mov_b32 s100, 0x190000
	v_lshl_add_u64 v[138:139], v[166:167], 0, s[100:101]
	s_mov_b32 s100, 0x1c2000
	v_lshl_add_u64 v[140:141], v[166:167], 0, s[100:101]
	s_mov_b32 s100, 0x1f4000
	v_lshl_add_u64 v[142:143], v[166:167], 0, s[100:101]
	s_mov_b32 s100, 0x226000
	v_lshl_add_u64 v[144:145], v[166:167], 0, s[100:101]
	s_add_u32 s100, s98, 0x0
	s_addc_u32 s101, s99, 0
	global_load_dwordx4 v[184:187], v243, s[100:101]
	s_add_u32 s100, s98, 0x19000
	s_addc_u32 s101, s99, 0
	global_load_dwordx4 v[188:191], v243, s[100:101]
	s_add_u32 s100, s98, 0x32000
	s_addc_u32 s101, s99, 0
	global_load_dwordx4 v[192:195], v243, s[100:101]
	s_add_u32 s100, s98, 0x4b000
	s_addc_u32 s101, s99, 0
	global_load_dwordx4 v[196:199], v243, s[100:101]
	s_add_u32 s100, s98, 0x64000
	s_addc_u32 s101, s99, 0
	global_load_dwordx4 v[200:203], v243, s[100:101]
	s_add_u32 s100, s98, 0x7d000
	s_addc_u32 s101, s99, 0
	global_load_dwordx4 v[204:207], v243, s[100:101]
	s_add_u32 s100, s98, 0x96000
	s_addc_u32 s101, s99, 0
	global_load_dwordx4 v[208:211], v243, s[100:101]
	s_add_u32 s100, s98, 0xaf000
	s_addc_u32 s101, s99, 0
	global_load_dwordx4 v[212:215], v243, s[100:101]
	s_add_u32 s100, s98, 0x190000
	s_addc_u32 s101, s99, 0
	global_load_dwordx4 v[216:219], v243, s[100:101]
	s_add_u32 s100, s98, 0x1a9000
	s_addc_u32 s101, s99, 0
	global_load_dwordx4 v[220:223], v243, s[100:101]
	s_add_u32 s100, s98, 0x1c2000
	s_addc_u32 s101, s99, 0
	global_load_dwordx4 v[224:227], v243, s[100:101]
	s_add_u32 s100, s98, 0x1db000
	s_addc_u32 s101, s99, 0
	global_load_dwordx4 v[228:231], v243, s[100:101]
	s_waitcnt vmcnt(10)
	v_lshlrev_b32_e32 v148, 16, v184
	v_and_b32_e32 v149, 0xffff0000, v184
	v_lshlrev_b32_e32 v150, 16, v185
	v_and_b32_e32 v151, 0xffff0000, v185
	v_lshlrev_b32_e32 v152, 16, v186
	v_and_b32_e32 v153, 0xffff0000, v186
	v_lshlrev_b32_e32 v168, 16, v187
	v_and_b32_e32 v169, 0xffff0000, v187
	v_pk_mul_f32 v[148:149], v[148:149], v[240:241] op_sel_hi:[1,0]
	v_pk_mul_f32 v[150:151], v[150:151], v[240:241] op_sel_hi:[1,0]
	v_pk_mul_f32 v[152:153], v[152:153], v[240:241] op_sel_hi:[1,0]
	v_pk_mul_f32 v[168:169], v[168:169], v[240:241] op_sel_hi:[1,0]
	v_min_f32_e32 v148, 0x42b80000, v148
	v_min_f32_e32 v149, 0x42b80000, v149
	v_min_f32_e32 v150, 0x42b80000, v150
	v_min_f32_e32 v151, 0x42b80000, v151
	v_min_f32_e32 v152, 0x42b80000, v152
	v_min_f32_e32 v153, 0x42b80000, v153
	v_min_f32_e32 v168, 0x42b80000, v168
	v_min_f32_e32 v169, 0x42b80000, v169
	v_exp_f32_e32 v148, v148
	v_exp_f32_e32 v149, v149
	v_exp_f32_e32 v150, v150
	v_exp_f32_e32 v151, v151
	v_exp_f32_e32 v152, v152
	v_exp_f32_e32 v153, v153
	v_exp_f32_e32 v168, v168
	v_exp_f32_e32 v169, v169
	s_nop 0
	v_add_f32_e32 v148, 1.0, v148
	v_add_f32_e32 v149, 1.0, v149
	v_add_f32_e32 v150, 1.0, v150
	v_add_f32_e32 v151, 1.0, v151
	v_add_f32_e32 v152, 1.0, v152
	v_add_f32_e32 v153, 1.0, v153
	v_add_f32_e32 v168, 1.0, v168
	v_add_f32_e32 v169, 1.0, v169
	v_rcp_f32_e32 v148, v148
	v_rcp_f32_e32 v149, v149
	v_rcp_f32_e32 v150, v150
	v_rcp_f32_e32 v151, v151
	v_rcp_f32_e32 v152, v152
	v_rcp_f32_e32 v153, v153
	v_rcp_f32_e32 v168, v168
	v_rcp_f32_e32 v169, v169
	s_nop 0
	v_pk_mul_f32 v[126:127], v[126:127], v[148:149]
	v_pk_mul_f32 v[128:129], v[128:129], v[150:151]
	v_pk_mul_f32 v[122:123], v[122:123], v[152:153]
	v_pk_mul_f32 v[124:125], v[124:125], v[168:169]
	v_cvt_pk_bf16_f32 v184, v126, v127
	v_cvt_pk_bf16_f32 v185, v128, v129
	v_cvt_pk_bf16_f32 v186, v122, v123
	v_cvt_pk_bf16_f32 v187, v124, v125
	v_lshlrev_b32_e32 v176, 16, v188
	v_and_b32_e32 v177, 0xffff0000, v188
	v_lshlrev_b32_e32 v178, 16, v189
	v_and_b32_e32 v179, 0xffff0000, v189
	v_lshlrev_b32_e32 v180, 16, v190
	v_and_b32_e32 v181, 0xffff0000, v190
	v_lshlrev_b32_e32 v244, 16, v191
	v_and_b32_e32 v245, 0xffff0000, v191
	v_pk_mul_f32 v[176:177], v[176:177], v[240:241] op_sel_hi:[1,0]
	v_pk_mul_f32 v[178:179], v[178:179], v[240:241] op_sel_hi:[1,0]
	v_pk_mul_f32 v[180:181], v[180:181], v[240:241] op_sel_hi:[1,0]
	v_pk_mul_f32 v[244:245], v[244:245], v[240:241] op_sel_hi:[1,0]
	v_min_f32_e32 v176, 0x42b80000, v176
	v_min_f32_e32 v177, 0x42b80000, v177
	v_min_f32_e32 v178, 0x42b80000, v178
	v_min_f32_e32 v179, 0x42b80000, v179
	v_min_f32_e32 v180, 0x42b80000, v180
	v_min_f32_e32 v181, 0x42b80000, v181
	v_min_f32_e32 v244, 0x42b80000, v244
	v_min_f32_e32 v245, 0x42b80000, v245
	v_exp_f32_e32 v176, v176
	v_exp_f32_e32 v177, v177
	v_exp_f32_e32 v178, v178
	v_exp_f32_e32 v179, v179
	v_exp_f32_e32 v180, v180
	v_exp_f32_e32 v181, v181
	v_exp_f32_e32 v244, v244
	v_exp_f32_e32 v245, v245
	s_nop 0
	v_add_f32_e32 v176, 1.0, v176
	v_add_f32_e32 v177, 1.0, v177
	v_add_f32_e32 v178, 1.0, v178
	v_add_f32_e32 v179, 1.0, v179
	v_add_f32_e32 v180, 1.0, v180
	v_add_f32_e32 v181, 1.0, v181
	v_add_f32_e32 v244, 1.0, v244
	v_add_f32_e32 v245, 1.0, v245
	v_rcp_f32_e32 v176, v176
	v_rcp_f32_e32 v177, v177
	v_rcp_f32_e32 v178, v178
	v_rcp_f32_e32 v179, v179
	v_rcp_f32_e32 v180, v180
	v_rcp_f32_e32 v181, v181
	v_rcp_f32_e32 v244, v244
	v_rcp_f32_e32 v245, v245
	s_nop 0
	v_pk_mul_f32 v[114:115], v[114:115], v[176:177]
	v_pk_mul_f32 v[116:117], v[116:117], v[178:179]
	v_pk_mul_f32 v[110:111], v[110:111], v[180:181]
	v_pk_mul_f32 v[112:113], v[112:113], v[244:245]
	v_cvt_pk_bf16_f32 v188, v114, v115
	v_cvt_pk_bf16_f32 v189, v116, v117
	v_cvt_pk_bf16_f32 v190, v110, v111
	v_cvt_pk_bf16_f32 v191, v112, v113
	global_store_dwordx4 v[166:167], v[184:187], off
	global_store_dwordx4 v[166:167], v[188:191], off offset:256
	s_nop 1
	s_add_u32 s100, s98, 0x1f4000
	s_addc_u32 s101, s99, 0
	global_load_dwordx4 v[184:187], v243, s[100:101]
	s_add_u32 s100, s98, 0x20d000
	s_addc_u32 s101, s99, 0
	global_load_dwordx4 v[188:191], v243, s[100:101]
	s_waitcnt vmcnt(12)
; DI float bflo(unsigned w) { return __uint_as_float(w << 16); }
; DI float bfhi(unsigned w) { return __uint_as_float(w & 0xffff0000u); }
; DI u32x4 pack8(f32x4 a, f32x4 b) { u32x4 w; w.x = pk2(a[0], a[1]); w.y = pk2(a[2], a[3]); w.z = pk2(b[0], b[1]); w.w = pk2(b[2], b[3]); return w; }
;     DI void operator()(Acc& acc, const Unit& u, int wr, int wc, int fr, int fq) const {
;     ...
;             for (int ai = 0; ai < 2; ++ai)
; #pragma unroll
;                 for (int m = 0; m < 4; ++m)
; #pragma unroll
;                     for (int bj = 0; bj < 2; ++bj) { const u32x4 q = g[ai][m][bj]; f32x4& v0 = acc[ai][bj][m][0]; f32x4& v1 = acc[ai][bj][m][1];
;                         v0[0] *= bflo(q.x); v0[1] *= bfhi(q.x); v0[2] *= bflo(q.y); v0[3] *= bfhi(q.y); v1[0] *= bflo(q.z); v1[1] *= bfhi(q.z); v1[2] *= bflo(q.w); v1[3] *= bfhi(q.w); }
;         }
;         if (u.k > 0) {
;             u32x4 g[2][4][2];
; #pragma unroll
;             for (int ai = 0; ai < 2; ++ai)
; #pragma unroll
;                 for (int m = 0; m < 4; ++m)
; #pragma unroll
;                     for (int bj = 0; bj < 2; ++bj) g[ai][m][bj] = *(const u32x4*)(base + (size_t)(ai * 128 + m * 16) * NPJ + bj * 128);
; #pragma unroll
;             for (int ai = 0; ai < 2; ++ai)
; #pragma unroll
;                 for (int m = 0; m < 4; ++m)
; #pragma unroll
;                     for (int bj = 0; bj < 2; ++bj) { const u32x4 q = g[ai][m][bj]; f32x4& v0 = acc[ai][bj][m][0]; f32x4& v1 = acc[ai][bj][m][1];
;                         v0[0] += bflo(q.x); v0[1] += bfhi(q.x); v0[2] += bflo(q.y); v0[3] += bfhi(q.y); v1[0] += bflo(q.z); v1[1] += bfhi(q.z); v1[2] += bflo(q.w); v1[3] += bfhi(q.w); }
;         }
;         if (!dry) {
; #pragma unroll
;             for (int ai = 0; ai < 2; ++ai)
; #pragma unroll
;                 for (int m = 0; m < 4; ++m)
; #pragma unroll
;                     for (int bj = 0; bj < 2; ++bj) *(u32x4*)(base + (size_t)(ai * 128 + m * 16) * NPJ + bj * 128) = pack8(acc[ai][bj][m][0], acc[ai][bj][m][1]);
	v_lshlrev_b32_e32 v148, 16, v192
	v_and_b32_e32 v149, 0xffff0000, v192
	v_lshlrev_b32_e32 v150, 16, v193
	v_and_b32_e32 v151, 0xffff0000, v193
	v_lshlrev_b32_e32 v152, 16, v194
	v_and_b32_e32 v153, 0xffff0000, v194
	v_lshlrev_b32_e32 v168, 16, v195
	v_and_b32_e32 v169, 0xffff0000, v195
	v_pk_mul_f32 v[148:149], v[148:149], v[240:241] op_sel_hi:[1,0]
	v_pk_mul_f32 v[150:151], v[150:151], v[240:241] op_sel_hi:[1,0]
	v_pk_mul_f32 v[152:153], v[152:153], v[240:241] op_sel_hi:[1,0]
	v_pk_mul_f32 v[168:169], v[168:169], v[240:241] op_sel_hi:[1,0]
	v_min_f32_e32 v148, 0x42b80000, v148
	v_min_f32_e32 v149, 0x42b80000, v149
	v_min_f32_e32 v150, 0x42b80000, v150
	v_min_f32_e32 v151, 0x42b80000, v151
	v_min_f32_e32 v152, 0x42b80000, v152
	v_min_f32_e32 v153, 0x42b80000, v153
	v_min_f32_e32 v168, 0x42b80000, v168
	v_min_f32_e32 v169, 0x42b80000, v169
	v_exp_f32_e32 v148, v148
	v_exp_f32_e32 v149, v149
	v_exp_f32_e32 v150, v150
	v_exp_f32_e32 v151, v151
	v_exp_f32_e32 v152, v152
	v_exp_f32_e32 v153, v153
	v_exp_f32_e32 v168, v168
	v_exp_f32_e32 v169, v169
	s_nop 0
	v_add_f32_e32 v148, 1.0, v148
	v_add_f32_e32 v149, 1.0, v149
	v_add_f32_e32 v150, 1.0, v150
	v_add_f32_e32 v151, 1.0, v151
	v_add_f32_e32 v152, 1.0, v152
	v_add_f32_e32 v153, 1.0, v153
	v_add_f32_e32 v168, 1.0, v168
	v_add_f32_e32 v169, 1.0, v169
	v_rcp_f32_e32 v148, v148
	v_rcp_f32_e32 v149, v149
	v_rcp_f32_e32 v150, v150
	v_rcp_f32_e32 v151, v151
	v_rcp_f32_e32 v152, v152
	v_rcp_f32_e32 v153, v153
	v_rcp_f32_e32 v168, v168
	v_rcp_f32_e32 v169, v169
	s_nop 0
	v_pk_mul_f32 v[118:119], v[118:119], v[148:149]
	v_pk_mul_f32 v[120:121], v[120:121], v[150:151]
	v_pk_mul_f32 v[106:107], v[106:107], v[152:153]
	v_pk_mul_f32 v[108:109], v[108:109], v[168:169]
	v_cvt_pk_bf16_f32 v192, v118, v119
	v_cvt_pk_bf16_f32 v193, v120, v121
	v_cvt_pk_bf16_f32 v194, v106, v107
	v_cvt_pk_bf16_f32 v195, v108, v109
	v_lshlrev_b32_e32 v176, 16, v196
	v_and_b32_e32 v177, 0xffff0000, v196
	v_lshlrev_b32_e32 v178, 16, v197
	v_and_b32_e32 v179, 0xffff0000, v197
	v_lshlrev_b32_e32 v180, 16, v198
	v_and_b32_e32 v181, 0xffff0000, v198
	v_lshlrev_b32_e32 v244, 16, v199
	v_and_b32_e32 v245, 0xffff0000, v199
	v_pk_mul_f32 v[176:177], v[176:177], v[240:241] op_sel_hi:[1,0]
	v_pk_mul_f32 v[178:179], v[178:179], v[240:241] op_sel_hi:[1,0]
	v_pk_mul_f32 v[180:181], v[180:181], v[240:241] op_sel_hi:[1,0]
	v_pk_mul_f32 v[244:245], v[244:245], v[240:241] op_sel_hi:[1,0]
	v_min_f32_e32 v176, 0x42b80000, v176
	v_min_f32_e32 v177, 0x42b80000, v177
	v_min_f32_e32 v178, 0x42b80000, v178
	v_min_f32_e32 v179, 0x42b80000, v179
	v_min_f32_e32 v180, 0x42b80000, v180
	v_min_f32_e32 v181, 0x42b80000, v181
	v_min_f32_e32 v244, 0x42b80000, v244
	v_min_f32_e32 v245, 0x42b80000, v245
	v_exp_f32_e32 v176, v176
	v_exp_f32_e32 v177, v177
	v_exp_f32_e32 v178, v178
	v_exp_f32_e32 v179, v179
	v_exp_f32_e32 v180, v180
	v_exp_f32_e32 v181, v181
	v_exp_f32_e32 v244, v244
	v_exp_f32_e32 v245, v245
	s_nop 0
	v_add_f32_e32 v176, 1.0, v176
	v_add_f32_e32 v177, 1.0, v177
	v_add_f32_e32 v178, 1.0, v178
	v_add_f32_e32 v179, 1.0, v179
	v_add_f32_e32 v180, 1.0, v180
	v_add_f32_e32 v181, 1.0, v181
	v_add_f32_e32 v244, 1.0, v244
	v_add_f32_e32 v245, 1.0, v245
	v_rcp_f32_e32 v176, v176
	v_rcp_f32_e32 v177, v177
	v_rcp_f32_e32 v178, v178
	v_rcp_f32_e32 v179, v179
	v_rcp_f32_e32 v180, v180
	v_rcp_f32_e32 v181, v181
	v_rcp_f32_e32 v244, v244
	v_rcp_f32_e32 v245, v245
	s_nop 0
	v_pk_mul_f32 v[98:99], v[98:99], v[176:177]
	v_pk_mul_f32 v[100:101], v[100:101], v[178:179]
	v_pk_mul_f32 v[90:91], v[90:91], v[180:181]
	v_pk_mul_f32 v[92:93], v[92:93], v[244:245]
	v_cvt_pk_bf16_f32 v196, v98, v99
	v_cvt_pk_bf16_f32 v197, v100, v101
	v_cvt_pk_bf16_f32 v198, v90, v91
	v_cvt_pk_bf16_f32 v199, v92, v93
	global_store_dwordx4 v[132:133], v[192:195], off
	global_store_dwordx4 v[132:133], v[196:199], off offset:256
	s_nop 1
	s_add_u32 s100, s98, 0x226000
	s_addc_u32 s101, s99, 0
	global_load_dwordx4 v[192:195], v243, s[100:101]
	s_add_u32 s100, s98, 0x23f000
	s_addc_u32 s101, s99, 0
	global_load_dwordx4 v[196:199], v243, s[100:101]
	s_waitcnt vmcnt(14)
	v_lshlrev_b32_e32 v148, 16, v200
	v_and_b32_e32 v149, 0xffff0000, v200
	v_lshlrev_b32_e32 v150, 16, v201
	v_and_b32_e32 v151, 0xffff0000, v201
	v_lshlrev_b32_e32 v152, 16, v202
	v_and_b32_e32 v153, 0xffff0000, v202
	v_lshlrev_b32_e32 v168, 16, v203
	v_and_b32_e32 v169, 0xffff0000, v203
	v_pk_mul_f32 v[148:149], v[148:149], v[240:241] op_sel_hi:[1,0]
	v_pk_mul_f32 v[150:151], v[150:151], v[240:241] op_sel_hi:[1,0]
	v_pk_mul_f32 v[152:153], v[152:153], v[240:241] op_sel_hi:[1,0]
	v_pk_mul_f32 v[168:169], v[168:169], v[240:241] op_sel_hi:[1,0]
	v_min_f32_e32 v148, 0x42b80000, v148
	v_min_f32_e32 v149, 0x42b80000, v149
	v_min_f32_e32 v150, 0x42b80000, v150
	v_min_f32_e32 v151, 0x42b80000, v151
	v_min_f32_e32 v152, 0x42b80000, v152
	v_min_f32_e32 v153, 0x42b80000, v153
	v_min_f32_e32 v168, 0x42b80000, v168
	v_min_f32_e32 v169, 0x42b80000, v169
	v_exp_f32_e32 v148, v148
	v_exp_f32_e32 v149, v149
	v_exp_f32_e32 v150, v150
	v_exp_f32_e32 v151, v151
	v_exp_f32_e32 v152, v152
	v_exp_f32_e32 v153, v153
	v_exp_f32_e32 v168, v168
	v_exp_f32_e32 v169, v169
	s_nop 0
	v_add_f32_e32 v148, 1.0, v148
	v_add_f32_e32 v149, 1.0, v149
	v_add_f32_e32 v150, 1.0, v150
	v_add_f32_e32 v151, 1.0, v151
	v_add_f32_e32 v152, 1.0, v152
	v_add_f32_e32 v153, 1.0, v153
	v_add_f32_e32 v168, 1.0, v168
	v_add_f32_e32 v169, 1.0, v169
	v_rcp_f32_e32 v148, v148
	v_rcp_f32_e32 v149, v149
	v_rcp_f32_e32 v150, v150
	v_rcp_f32_e32 v151, v151
	v_rcp_f32_e32 v152, v152
	v_rcp_f32_e32 v153, v153
	v_rcp_f32_e32 v168, v168
	v_rcp_f32_e32 v169, v169
	s_nop 0
; DI float bflo(unsigned w) { return __uint_as_float(w << 16); }
; DI float bfhi(unsigned w) { return __uint_as_float(w & 0xffff0000u); }
; DI u32x4 pack8(f32x4 a, f32x4 b) { u32x4 w; w.x = pk2(a[0], a[1]); w.y = pk2(a[2], a[3]); w.z = pk2(b[0], b[1]); w.w = pk2(b[2], b[3]); return w; }
;     DI void operator()(Acc& acc, const Unit& u, int wr, int wc, int fr, int fq) const {
;     ...
;             for (int ai = 0; ai < 2; ++ai)
; #pragma unroll
;                 for (int m = 0; m < 4; ++m)
; #pragma unroll
;                     for (int bj = 0; bj < 2; ++bj) { const u32x4 q = g[ai][m][bj]; f32x4& v0 = acc[ai][bj][m][0]; f32x4& v1 = acc[ai][bj][m][1];
;                         v0[0] *= bflo(q.x); v0[1] *= bfhi(q.x); v0[2] *= bflo(q.y); v0[3] *= bfhi(q.y); v1[0] *= bflo(q.z); v1[1] *= bfhi(q.z); v1[2] *= bflo(q.w); v1[3] *= bfhi(q.w); }
;         }
;         if (u.k > 0) {
;             u32x4 g[2][4][2];
; #pragma unroll
;             for (int ai = 0; ai < 2; ++ai)
; #pragma unroll
;                 for (int m = 0; m < 4; ++m)
; #pragma unroll
;                     for (int bj = 0; bj < 2; ++bj) g[ai][m][bj] = *(const u32x4*)(base + (size_t)(ai * 128 + m * 16) * NPJ + bj * 128);
; #pragma unroll
;             for (int ai = 0; ai < 2; ++ai)
; #pragma unroll
;                 for (int m = 0; m < 4; ++m)
; #pragma unroll
;                     for (int bj = 0; bj < 2; ++bj) { const u32x4 q = g[ai][m][bj]; f32x4& v0 = acc[ai][bj][m][0]; f32x4& v1 = acc[ai][bj][m][1];
;                         v0[0] += bflo(q.x); v0[1] += bfhi(q.x); v0[2] += bflo(q.y); v0[3] += bfhi(q.y); v1[0] += bflo(q.z); v1[1] += bfhi(q.z); v1[2] += bflo(q.w); v1[3] += bfhi(q.w); }
;         }
;         if (!dry) {
; #pragma unroll
;             for (int ai = 0; ai < 2; ++ai)
; #pragma unroll
;                 for (int m = 0; m < 4; ++m)
; #pragma unroll
;                     for (int bj = 0; bj < 2; ++bj) *(u32x4*)(base + (size_t)(ai * 128 + m * 16) * NPJ + bj * 128) = pack8(acc[ai][bj][m][0], acc[ai][bj][m][1]);
	v_pk_mul_f32 v[102:103], v[102:103], v[148:149]
	v_pk_mul_f32 v[104:105], v[104:105], v[150:151]
	v_pk_mul_f32 v[94:95], v[94:95], v[152:153]
	v_pk_mul_f32 v[96:97], v[96:97], v[168:169]
	v_cvt_pk_bf16_f32 v200, v102, v103
	v_cvt_pk_bf16_f32 v201, v104, v105
	v_cvt_pk_bf16_f32 v202, v94, v95
	v_cvt_pk_bf16_f32 v203, v96, v97
	v_lshlrev_b32_e32 v176, 16, v204
	v_and_b32_e32 v177, 0xffff0000, v204
	v_lshlrev_b32_e32 v178, 16, v205
	v_and_b32_e32 v179, 0xffff0000, v205
	v_lshlrev_b32_e32 v180, 16, v206
	v_and_b32_e32 v181, 0xffff0000, v206
	v_lshlrev_b32_e32 v244, 16, v207
	v_and_b32_e32 v245, 0xffff0000, v207
	v_pk_mul_f32 v[176:177], v[176:177], v[240:241] op_sel_hi:[1,0]
	v_pk_mul_f32 v[178:179], v[178:179], v[240:241] op_sel_hi:[1,0]
	v_pk_mul_f32 v[180:181], v[180:181], v[240:241] op_sel_hi:[1,0]
	v_pk_mul_f32 v[244:245], v[244:245], v[240:241] op_sel_hi:[1,0]
	v_min_f32_e32 v176, 0x42b80000, v176
	v_min_f32_e32 v177, 0x42b80000, v177
	v_min_f32_e32 v178, 0x42b80000, v178
	v_min_f32_e32 v179, 0x42b80000, v179
	v_min_f32_e32 v180, 0x42b80000, v180
	v_min_f32_e32 v181, 0x42b80000, v181
	v_min_f32_e32 v244, 0x42b80000, v244
	v_min_f32_e32 v245, 0x42b80000, v245
	v_exp_f32_e32 v176, v176
	v_exp_f32_e32 v177, v177
	v_exp_f32_e32 v178, v178
	v_exp_f32_e32 v179, v179
	v_exp_f32_e32 v180, v180
	v_exp_f32_e32 v181, v181
	v_exp_f32_e32 v244, v244
	v_exp_f32_e32 v245, v245
	s_nop 0
	v_add_f32_e32 v176, 1.0, v176
	v_add_f32_e32 v177, 1.0, v177
	v_add_f32_e32 v178, 1.0, v178
	v_add_f32_e32 v179, 1.0, v179
	v_add_f32_e32 v180, 1.0, v180
	v_add_f32_e32 v181, 1.0, v181
	v_add_f32_e32 v244, 1.0, v244
	v_add_f32_e32 v245, 1.0, v245
	v_rcp_f32_e32 v176, v176
	v_rcp_f32_e32 v177, v177
	v_rcp_f32_e32 v178, v178
	v_rcp_f32_e32 v179, v179
	v_rcp_f32_e32 v180, v180
	v_rcp_f32_e32 v181, v181
	v_rcp_f32_e32 v244, v244
	v_rcp_f32_e32 v245, v245
	s_nop 0
	v_pk_mul_f32 v[82:83], v[82:83], v[176:177]
	v_pk_mul_f32 v[84:85], v[84:85], v[178:179]
	v_pk_mul_f32 v[74:75], v[74:75], v[180:181]
	v_pk_mul_f32 v[76:77], v[76:77], v[244:245]
	v_cvt_pk_bf16_f32 v204, v82, v83
	v_cvt_pk_bf16_f32 v205, v84, v85
	v_cvt_pk_bf16_f32 v206, v74, v75
	v_cvt_pk_bf16_f32 v207, v76, v77
	global_store_dwordx4 v[134:135], v[200:203], off
	global_store_dwordx4 v[134:135], v[204:207], off offset:256
	s_waitcnt vmcnt(14)
	v_lshlrev_b32_e32 v148, 16, v208
	v_and_b32_e32 v149, 0xffff0000, v208
	v_lshlrev_b32_e32 v150, 16, v209
	v_and_b32_e32 v151, 0xffff0000, v209
	v_lshlrev_b32_e32 v152, 16, v210
	v_and_b32_e32 v153, 0xffff0000, v210
	v_lshlrev_b32_e32 v168, 16, v211
	v_and_b32_e32 v169, 0xffff0000, v211
	v_pk_mul_f32 v[148:149], v[148:149], v[240:241] op_sel_hi:[1,0]
	v_pk_mul_f32 v[150:151], v[150:151], v[240:241] op_sel_hi:[1,0]
	v_pk_mul_f32 v[152:153], v[152:153], v[240:241] op_sel_hi:[1,0]
	v_pk_mul_f32 v[168:169], v[168:169], v[240:241] op_sel_hi:[1,0]
	v_min_f32_e32 v148, 0x42b80000, v148
	v_min_f32_e32 v149, 0x42b80000, v149
	v_min_f32_e32 v150, 0x42b80000, v150
	v_min_f32_e32 v151, 0x42b80000, v151
	v_min_f32_e32 v152, 0x42b80000, v152
	v_min_f32_e32 v153, 0x42b80000, v153
	v_min_f32_e32 v168, 0x42b80000, v168
	v_min_f32_e32 v169, 0x42b80000, v169
	v_exp_f32_e32 v148, v148
	v_exp_f32_e32 v149, v149
	v_exp_f32_e32 v150, v150
	v_exp_f32_e32 v151, v151
	v_exp_f32_e32 v152, v152
	v_exp_f32_e32 v153, v153
	v_exp_f32_e32 v168, v168
	v_exp_f32_e32 v169, v169
	s_nop 0
	v_add_f32_e32 v148, 1.0, v148
	v_add_f32_e32 v149, 1.0, v149
	v_add_f32_e32 v150, 1.0, v150
	v_add_f32_e32 v151, 1.0, v151
	v_add_f32_e32 v152, 1.0, v152
	v_add_f32_e32 v153, 1.0, v153
	v_add_f32_e32 v168, 1.0, v168
	v_add_f32_e32 v169, 1.0, v169
	v_rcp_f32_e32 v148, v148
	v_rcp_f32_e32 v149, v149
	v_rcp_f32_e32 v150, v150
	v_rcp_f32_e32 v151, v151
	v_rcp_f32_e32 v152, v152
	v_rcp_f32_e32 v153, v153
	v_rcp_f32_e32 v168, v168
	v_rcp_f32_e32 v169, v169
	s_nop 0
	v_pk_mul_f32 v[86:87], v[86:87], v[148:149]
	v_pk_mul_f32 v[88:89], v[88:89], v[150:151]
	v_pk_mul_f32 v[78:79], v[78:79], v[152:153]
	v_pk_mul_f32 v[80:81], v[80:81], v[168:169]
	v_cvt_pk_bf16_f32 v208, v86, v87
	v_cvt_pk_bf16_f32 v209, v88, v89
	v_cvt_pk_bf16_f32 v210, v78, v79
	v_cvt_pk_bf16_f32 v211, v80, v81
	v_lshlrev_b32_e32 v176, 16, v212
	v_and_b32_e32 v177, 0xffff0000, v212
	v_lshlrev_b32_e32 v178, 16, v213
	v_and_b32_e32 v179, 0xffff0000, v213
	v_lshlrev_b32_e32 v180, 16, v214
	v_and_b32_e32 v181, 0xffff0000, v214
	v_lshlrev_b32_e32 v244, 16, v215
	v_and_b32_e32 v245, 0xffff0000, v215
	v_pk_mul_f32 v[176:177], v[176:177], v[240:241] op_sel_hi:[1,0]
	v_pk_mul_f32 v[178:179], v[178:179], v[240:241] op_sel_hi:[1,0]
	v_pk_mul_f32 v[180:181], v[180:181], v[240:241] op_sel_hi:[1,0]
	v_pk_mul_f32 v[244:245], v[244:245], v[240:241] op_sel_hi:[1,0]
	v_min_f32_e32 v176, 0x42b80000, v176
	v_min_f32_e32 v177, 0x42b80000, v177
	v_min_f32_e32 v178, 0x42b80000, v178
	v_min_f32_e32 v179, 0x42b80000, v179
	v_min_f32_e32 v180, 0x42b80000, v180
	v_min_f32_e32 v181, 0x42b80000, v181
	v_min_f32_e32 v244, 0x42b80000, v244
	v_min_f32_e32 v245, 0x42b80000, v245
	v_exp_f32_e32 v176, v176
	v_exp_f32_e32 v177, v177
	v_exp_f32_e32 v178, v178
	v_exp_f32_e32 v179, v179
	v_exp_f32_e32 v180, v180
	v_exp_f32_e32 v181, v181
	v_exp_f32_e32 v244, v244
	v_exp_f32_e32 v245, v245
	s_nop 0
	v_add_f32_e32 v176, 1.0, v176
	v_add_f32_e32 v177, 1.0, v177
	v_add_f32_e32 v178, 1.0, v178
	v_add_f32_e32 v179, 1.0, v179
	v_add_f32_e32 v180, 1.0, v180
	v_add_f32_e32 v181, 1.0, v181
	v_add_f32_e32 v244, 1.0, v244
	v_add_f32_e32 v245, 1.0, v245
	v_rcp_f32_e32 v176, v176
	v_rcp_f32_e32 v177, v177
	v_rcp_f32_e32 v178, v178
	v_rcp_f32_e32 v179, v179
	v_rcp_f32_e32 v180, v180
	v_rcp_f32_e32 v181, v181
	v_rcp_f32_e32 v244, v244
	v_rcp_f32_e32 v245, v245
	s_nop 0
	v_pk_mul_f32 v[70:71], v[70:71], v[176:177]
	v_pk_mul_f32 v[72:73], v[72:73], v[178:179]
	v_pk_mul_f32 v[66:67], v[66:67], v[180:181]
	v_pk_mul_f32 v[68:69], v[68:69], v[244:245]
	v_cvt_pk_bf16_f32 v212, v70, v71
	v_cvt_pk_bf16_f32 v213, v72, v73
	v_cvt_pk_bf16_f32 v214, v66, v67
	v_cvt_pk_bf16_f32 v215, v68, v69
	global_store_dwordx4 v[136:137], v[208:211], off
	global_store_dwordx4 v[136:137], v[212:215], off offset:256
	s_waitcnt vmcnt(14)
; DI float bflo(unsigned w) { return __uint_as_float(w << 16); }
; DI float bfhi(unsigned w) { return __uint_as_float(w & 0xffff0000u); }
; DI u32x4 pack8(f32x4 a, f32x4 b) { u32x4 w; w.x = pk2(a[0], a[1]); w.y = pk2(a[2], a[3]); w.z = pk2(b[0], b[1]); w.w = pk2(b[2], b[3]); return w; }
;     DI void operator()(Acc& acc, const Unit& u, int wr, int wc, int fr, int fq) const {
;     ...
;             for (int ai = 0; ai < 2; ++ai)
; #pragma unroll
;                 for (int m = 0; m < 4; ++m)
; #pragma unroll
;                     for (int bj = 0; bj < 2; ++bj) { const u32x4 q = g[ai][m][bj]; f32x4& v0 = acc[ai][bj][m][0]; f32x4& v1 = acc[ai][bj][m][1];
;                         v0[0] *= bflo(q.x); v0[1] *= bfhi(q.x); v0[2] *= bflo(q.y); v0[3] *= bfhi(q.y); v1[0] *= bflo(q.z); v1[1] *= bfhi(q.z); v1[2] *= bflo(q.w); v1[3] *= bfhi(q.w); }
;         }
;         if (u.k > 0) {
;             u32x4 g[2][4][2];
; #pragma unroll
;             for (int ai = 0; ai < 2; ++ai)
; #pragma unroll
;                 for (int m = 0; m < 4; ++m)
; #pragma unroll
;                     for (int bj = 0; bj < 2; ++bj) g[ai][m][bj] = *(const u32x4*)(base + (size_t)(ai * 128 + m * 16) * NPJ + bj * 128);
; #pragma unroll
;             for (int ai = 0; ai < 2; ++ai)
; #pragma unroll
;                 for (int m = 0; m < 4; ++m)
; #pragma unroll
;                     for (int bj = 0; bj < 2; ++bj) { const u32x4 q = g[ai][m][bj]; f32x4& v0 = acc[ai][bj][m][0]; f32x4& v1 = acc[ai][bj][m][1];
;                         v0[0] += bflo(q.x); v0[1] += bfhi(q.x); v0[2] += bflo(q.y); v0[3] += bfhi(q.y); v1[0] += bflo(q.z); v1[1] += bfhi(q.z); v1[2] += bflo(q.w); v1[3] += bfhi(q.w); }
;         }
;         if (!dry) {
; #pragma unroll
;             for (int ai = 0; ai < 2; ++ai)
; #pragma unroll
;                 for (int m = 0; m < 4; ++m)
; #pragma unroll
;                     for (int bj = 0; bj < 2; ++bj) *(u32x4*)(base + (size_t)(ai * 128 + m * 16) * NPJ + bj * 128) = pack8(acc[ai][bj][m][0], acc[ai][bj][m][1]);
	v_lshlrev_b32_e32 v148, 16, v216
	v_and_b32_e32 v149, 0xffff0000, v216
	v_lshlrev_b32_e32 v150, 16, v217
	v_and_b32_e32 v151, 0xffff0000, v217
	v_lshlrev_b32_e32 v152, 16, v218
	v_and_b32_e32 v153, 0xffff0000, v218
	v_lshlrev_b32_e32 v168, 16, v219
	v_and_b32_e32 v169, 0xffff0000, v219
	v_pk_mul_f32 v[148:149], v[148:149], v[240:241] op_sel_hi:[1,0]
	v_pk_mul_f32 v[150:151], v[150:151], v[240:241] op_sel_hi:[1,0]
	v_pk_mul_f32 v[152:153], v[152:153], v[240:241] op_sel_hi:[1,0]
	v_pk_mul_f32 v[168:169], v[168:169], v[240:241] op_sel_hi:[1,0]
	v_min_f32_e32 v148, 0x42b80000, v148
	v_min_f32_e32 v149, 0x42b80000, v149
	v_min_f32_e32 v150, 0x42b80000, v150
	v_min_f32_e32 v151, 0x42b80000, v151
	v_min_f32_e32 v152, 0x42b80000, v152
	v_min_f32_e32 v153, 0x42b80000, v153
	v_min_f32_e32 v168, 0x42b80000, v168
	v_min_f32_e32 v169, 0x42b80000, v169
	v_exp_f32_e32 v148, v148
	v_exp_f32_e32 v149, v149
	v_exp_f32_e32 v150, v150
	v_exp_f32_e32 v151, v151
	v_exp_f32_e32 v152, v152
	v_exp_f32_e32 v153, v153
	v_exp_f32_e32 v168, v168
	v_exp_f32_e32 v169, v169
	s_nop 0
	v_add_f32_e32 v148, 1.0, v148
	v_add_f32_e32 v149, 1.0, v149
	v_add_f32_e32 v150, 1.0, v150
	v_add_f32_e32 v151, 1.0, v151
	v_add_f32_e32 v152, 1.0, v152
	v_add_f32_e32 v153, 1.0, v153
	v_add_f32_e32 v168, 1.0, v168
	v_add_f32_e32 v169, 1.0, v169
	v_rcp_f32_e32 v148, v148
	v_rcp_f32_e32 v149, v149
	v_rcp_f32_e32 v150, v150
	v_rcp_f32_e32 v151, v151
	v_rcp_f32_e32 v152, v152
	v_rcp_f32_e32 v153, v153
	v_rcp_f32_e32 v168, v168
	v_rcp_f32_e32 v169, v169
	s_nop 0
	v_pk_mul_f32 v[62:63], v[62:63], v[148:149]
	v_pk_mul_f32 v[64:65], v[64:65], v[150:151]
	v_pk_mul_f32 v[58:59], v[58:59], v[152:153]
	v_pk_mul_f32 v[60:61], v[60:61], v[168:169]
	v_cvt_pk_bf16_f32 v216, v62, v63
	v_cvt_pk_bf16_f32 v217, v64, v65
	v_cvt_pk_bf16_f32 v218, v58, v59
	v_cvt_pk_bf16_f32 v219, v60, v61
	v_lshlrev_b32_e32 v176, 16, v220
	v_and_b32_e32 v177, 0xffff0000, v220
	v_lshlrev_b32_e32 v178, 16, v221
	v_and_b32_e32 v179, 0xffff0000, v221
	v_lshlrev_b32_e32 v180, 16, v222
	v_and_b32_e32 v181, 0xffff0000, v222
	v_lshlrev_b32_e32 v244, 16, v223
	v_and_b32_e32 v245, 0xffff0000, v223
	v_pk_mul_f32 v[176:177], v[176:177], v[240:241] op_sel_hi:[1,0]
	v_pk_mul_f32 v[178:179], v[178:179], v[240:241] op_sel_hi:[1,0]
	v_pk_mul_f32 v[180:181], v[180:181], v[240:241] op_sel_hi:[1,0]
	v_pk_mul_f32 v[244:245], v[244:245], v[240:241] op_sel_hi:[1,0]
	v_min_f32_e32 v176, 0x42b80000, v176
	v_min_f32_e32 v177, 0x42b80000, v177
	v_min_f32_e32 v178, 0x42b80000, v178
	v_min_f32_e32 v179, 0x42b80000, v179
	v_min_f32_e32 v180, 0x42b80000, v180
	v_min_f32_e32 v181, 0x42b80000, v181
	v_min_f32_e32 v244, 0x42b80000, v244
	v_min_f32_e32 v245, 0x42b80000, v245
	v_exp_f32_e32 v176, v176
	v_exp_f32_e32 v177, v177
	v_exp_f32_e32 v178, v178
	v_exp_f32_e32 v179, v179
	v_exp_f32_e32 v180, v180
	v_exp_f32_e32 v181, v181
	v_exp_f32_e32 v244, v244
	v_exp_f32_e32 v245, v245
	s_nop 0
	v_add_f32_e32 v176, 1.0, v176
	v_add_f32_e32 v177, 1.0, v177
	v_add_f32_e32 v178, 1.0, v178
	v_add_f32_e32 v179, 1.0, v179
	v_add_f32_e32 v180, 1.0, v180
	v_add_f32_e32 v181, 1.0, v181
	v_add_f32_e32 v244, 1.0, v244
	v_add_f32_e32 v245, 1.0, v245
	v_rcp_f32_e32 v176, v176
	v_rcp_f32_e32 v177, v177
	v_rcp_f32_e32 v178, v178
	v_rcp_f32_e32 v179, v179
	v_rcp_f32_e32 v180, v180
	v_rcp_f32_e32 v181, v181
	v_rcp_f32_e32 v244, v244
	v_rcp_f32_e32 v245, v245
	s_nop 0
	v_pk_mul_f32 v[50:51], v[50:51], v[176:177]
	v_pk_mul_f32 v[52:53], v[52:53], v[178:179]
	v_pk_mul_f32 v[42:43], v[42:43], v[180:181]
	v_pk_mul_f32 v[44:45], v[44:45], v[244:245]
	v_cvt_pk_bf16_f32 v220, v50, v51
	v_cvt_pk_bf16_f32 v221, v52, v53
	v_cvt_pk_bf16_f32 v222, v42, v43
	v_cvt_pk_bf16_f32 v223, v44, v45
	global_store_dwordx4 v[138:139], v[216:219], off
	global_store_dwordx4 v[138:139], v[220:223], off offset:256
	s_waitcnt vmcnt(14)
	v_lshlrev_b32_e32 v148, 16, v224
	v_and_b32_e32 v149, 0xffff0000, v224
	v_lshlrev_b32_e32 v150, 16, v225
	v_and_b32_e32 v151, 0xffff0000, v225
	v_lshlrev_b32_e32 v152, 16, v226
	v_and_b32_e32 v153, 0xffff0000, v226
	v_lshlrev_b32_e32 v168, 16, v227
	v_and_b32_e32 v169, 0xffff0000, v227
	v_pk_mul_f32 v[148:149], v[148:149], v[240:241] op_sel_hi:[1,0]
	v_pk_mul_f32 v[150:151], v[150:151], v[240:241] op_sel_hi:[1,0]
	v_pk_mul_f32 v[152:153], v[152:153], v[240:241] op_sel_hi:[1,0]
	v_pk_mul_f32 v[168:169], v[168:169], v[240:241] op_sel_hi:[1,0]
	v_min_f32_e32 v148, 0x42b80000, v148
	v_min_f32_e32 v149, 0x42b80000, v149
	v_min_f32_e32 v150, 0x42b80000, v150
	v_min_f32_e32 v151, 0x42b80000, v151
	v_min_f32_e32 v152, 0x42b80000, v152
	v_min_f32_e32 v153, 0x42b80000, v153
	v_min_f32_e32 v168, 0x42b80000, v168
	v_min_f32_e32 v169, 0x42b80000, v169
	v_exp_f32_e32 v148, v148
	v_exp_f32_e32 v149, v149
	v_exp_f32_e32 v150, v150
	v_exp_f32_e32 v151, v151
	v_exp_f32_e32 v152, v152
	v_exp_f32_e32 v153, v153
	v_exp_f32_e32 v168, v168
	v_exp_f32_e32 v169, v169
	s_nop 0
	v_add_f32_e32 v148, 1.0, v148
	v_add_f32_e32 v149, 1.0, v149
	v_add_f32_e32 v150, 1.0, v150
	v_add_f32_e32 v151, 1.0, v151
	v_add_f32_e32 v152, 1.0, v152
	v_add_f32_e32 v153, 1.0, v153
	v_add_f32_e32 v168, 1.0, v168
	v_add_f32_e32 v169, 1.0, v169
	v_rcp_f32_e32 v148, v148
	v_rcp_f32_e32 v149, v149
	v_rcp_f32_e32 v150, v150
	v_rcp_f32_e32 v151, v151
	v_rcp_f32_e32 v152, v152
	v_rcp_f32_e32 v153, v153
	v_rcp_f32_e32 v168, v168
	v_rcp_f32_e32 v169, v169
	s_nop 0
	v_pk_mul_f32 v[54:55], v[54:55], v[148:149]
	v_pk_mul_f32 v[56:57], v[56:57], v[150:151]
	v_pk_mul_f32 v[46:47], v[46:47], v[152:153]
	v_pk_mul_f32 v[48:49], v[48:49], v[168:169]
	v_cvt_pk_bf16_f32 v224, v54, v55
	v_cvt_pk_bf16_f32 v225, v56, v57
	v_cvt_pk_bf16_f32 v226, v46, v47
; DI float bflo(unsigned w) { return __uint_as_float(w << 16); }
; DI float bfhi(unsigned w) { return __uint_as_float(w & 0xffff0000u); }
; DI u32x4 pack8(f32x4 a, f32x4 b) { u32x4 w; w.x = pk2(a[0], a[1]); w.y = pk2(a[2], a[3]); w.z = pk2(b[0], b[1]); w.w = pk2(b[2], b[3]); return w; }
;     DI void operator()(Acc& acc, const Unit& u, int wr, int wc, int fr, int fq) const {
;     ...
;             for (int ai = 0; ai < 2; ++ai)
; #pragma unroll
;                 for (int m = 0; m < 4; ++m)
; #pragma unroll
;                     for (int bj = 0; bj < 2; ++bj) { const u32x4 q = g[ai][m][bj]; f32x4& v0 = acc[ai][bj][m][0]; f32x4& v1 = acc[ai][bj][m][1];
;                         v0[0] *= bflo(q.x); v0[1] *= bfhi(q.x); v0[2] *= bflo(q.y); v0[3] *= bfhi(q.y); v1[0] *= bflo(q.z); v1[1] *= bfhi(q.z); v1[2] *= bflo(q.w); v1[3] *= bfhi(q.w); }
;         }
;         if (u.k > 0) {
;             u32x4 g[2][4][2];
; #pragma unroll
;             for (int ai = 0; ai < 2; ++ai)
; #pragma unroll
;                 for (int m = 0; m < 4; ++m)
; #pragma unroll
;                     for (int bj = 0; bj < 2; ++bj) g[ai][m][bj] = *(const u32x4*)(base + (size_t)(ai * 128 + m * 16) * NPJ + bj * 128);
; #pragma unroll
;             for (int ai = 0; ai < 2; ++ai)
; #pragma unroll
;                 for (int m = 0; m < 4; ++m)
; #pragma unroll
;                     for (int bj = 0; bj < 2; ++bj) { const u32x4 q = g[ai][m][bj]; f32x4& v0 = acc[ai][bj][m][0]; f32x4& v1 = acc[ai][bj][m][1];
;                         v0[0] += bflo(q.x); v0[1] += bfhi(q.x); v0[2] += bflo(q.y); v0[3] += bfhi(q.y); v1[0] += bflo(q.z); v1[1] += bfhi(q.z); v1[2] += bflo(q.w); v1[3] += bfhi(q.w); }
;         }
;         if (!dry) {
; #pragma unroll
;             for (int ai = 0; ai < 2; ++ai)
; #pragma unroll
;                 for (int m = 0; m < 4; ++m)
; #pragma unroll
;                     for (int bj = 0; bj < 2; ++bj) *(u32x4*)(base + (size_t)(ai * 128 + m * 16) * NPJ + bj * 128) = pack8(acc[ai][bj][m][0], acc[ai][bj][m][1]);
	v_cvt_pk_bf16_f32 v227, v48, v49
	v_lshlrev_b32_e32 v176, 16, v228
	v_and_b32_e32 v177, 0xffff0000, v228
	v_lshlrev_b32_e32 v178, 16, v229
	v_and_b32_e32 v179, 0xffff0000, v229
	v_lshlrev_b32_e32 v180, 16, v230
	v_and_b32_e32 v181, 0xffff0000, v230
	v_lshlrev_b32_e32 v244, 16, v231
	v_and_b32_e32 v245, 0xffff0000, v231
	v_pk_mul_f32 v[176:177], v[176:177], v[240:241] op_sel_hi:[1,0]
	v_pk_mul_f32 v[178:179], v[178:179], v[240:241] op_sel_hi:[1,0]
	v_pk_mul_f32 v[180:181], v[180:181], v[240:241] op_sel_hi:[1,0]
	v_pk_mul_f32 v[244:245], v[244:245], v[240:241] op_sel_hi:[1,0]
	v_min_f32_e32 v176, 0x42b80000, v176
	v_min_f32_e32 v177, 0x42b80000, v177
	v_min_f32_e32 v178, 0x42b80000, v178
	v_min_f32_e32 v179, 0x42b80000, v179
	v_min_f32_e32 v180, 0x42b80000, v180
	v_min_f32_e32 v181, 0x42b80000, v181
	v_min_f32_e32 v244, 0x42b80000, v244
	v_min_f32_e32 v245, 0x42b80000, v245
	v_exp_f32_e32 v176, v176
	v_exp_f32_e32 v177, v177
	v_exp_f32_e32 v178, v178
	v_exp_f32_e32 v179, v179
	v_exp_f32_e32 v180, v180
	v_exp_f32_e32 v181, v181
	v_exp_f32_e32 v244, v244
	v_exp_f32_e32 v245, v245
	s_nop 0
	v_add_f32_e32 v176, 1.0, v176
	v_add_f32_e32 v177, 1.0, v177
	v_add_f32_e32 v178, 1.0, v178
	v_add_f32_e32 v179, 1.0, v179
	v_add_f32_e32 v180, 1.0, v180
	v_add_f32_e32 v181, 1.0, v181
	v_add_f32_e32 v244, 1.0, v244
	v_add_f32_e32 v245, 1.0, v245
	v_rcp_f32_e32 v176, v176
	v_rcp_f32_e32 v177, v177
	v_rcp_f32_e32 v178, v178
	v_rcp_f32_e32 v179, v179
	v_rcp_f32_e32 v180, v180
	v_rcp_f32_e32 v181, v181
	v_rcp_f32_e32 v244, v244
	v_rcp_f32_e32 v245, v245
	s_nop 0
	v_pk_mul_f32 v[34:35], v[34:35], v[176:177]
	v_pk_mul_f32 v[36:37], v[36:37], v[178:179]
	v_pk_mul_f32 v[26:27], v[26:27], v[180:181]
	v_pk_mul_f32 v[28:29], v[28:29], v[244:245]
	v_cvt_pk_bf16_f32 v228, v34, v35
	v_cvt_pk_bf16_f32 v229, v36, v37
	v_cvt_pk_bf16_f32 v230, v26, v27
	v_cvt_pk_bf16_f32 v231, v28, v29
	global_store_dwordx4 v[140:141], v[224:227], off
	global_store_dwordx4 v[140:141], v[228:231], off offset:256
	s_waitcnt vmcnt(12)
	v_lshlrev_b32_e32 v148, 16, v184
	v_and_b32_e32 v149, 0xffff0000, v184
	v_lshlrev_b32_e32 v150, 16, v185
	v_and_b32_e32 v151, 0xffff0000, v185
	v_lshlrev_b32_e32 v152, 16, v186
	v_and_b32_e32 v153, 0xffff0000, v186
	v_lshlrev_b32_e32 v168, 16, v187
	v_and_b32_e32 v169, 0xffff0000, v187
	v_pk_mul_f32 v[148:149], v[148:149], v[240:241] op_sel_hi:[1,0]
	v_pk_mul_f32 v[150:151], v[150:151], v[240:241] op_sel_hi:[1,0]
	v_pk_mul_f32 v[152:153], v[152:153], v[240:241] op_sel_hi:[1,0]
	v_pk_mul_f32 v[168:169], v[168:169], v[240:241] op_sel_hi:[1,0]
	v_min_f32_e32 v148, 0x42b80000, v148
	v_min_f32_e32 v149, 0x42b80000, v149
	v_min_f32_e32 v150, 0x42b80000, v150
	v_min_f32_e32 v151, 0x42b80000, v151
	v_min_f32_e32 v152, 0x42b80000, v152
	v_min_f32_e32 v153, 0x42b80000, v153
	v_min_f32_e32 v168, 0x42b80000, v168
	v_min_f32_e32 v169, 0x42b80000, v169
	v_exp_f32_e32 v148, v148
	v_exp_f32_e32 v149, v149
	v_exp_f32_e32 v150, v150
	v_exp_f32_e32 v151, v151
	v_exp_f32_e32 v152, v152
	v_exp_f32_e32 v153, v153
	v_exp_f32_e32 v168, v168
	v_exp_f32_e32 v169, v169
	s_nop 0
	v_add_f32_e32 v148, 1.0, v148
	v_add_f32_e32 v149, 1.0, v149
	v_add_f32_e32 v150, 1.0, v150
	v_add_f32_e32 v151, 1.0, v151
	v_add_f32_e32 v152, 1.0, v152
	v_add_f32_e32 v153, 1.0, v153
	v_add_f32_e32 v168, 1.0, v168
	v_add_f32_e32 v169, 1.0, v169
	v_rcp_f32_e32 v148, v148
	v_rcp_f32_e32 v149, v149
	v_rcp_f32_e32 v150, v150
	v_rcp_f32_e32 v151, v151
	v_rcp_f32_e32 v152, v152
	v_rcp_f32_e32 v153, v153
	v_rcp_f32_e32 v168, v168
	v_rcp_f32_e32 v169, v169
	s_nop 0
	v_pk_mul_f32 v[38:39], v[38:39], v[148:149]
	v_pk_mul_f32 v[40:41], v[40:41], v[150:151]
	v_pk_mul_f32 v[30:31], v[30:31], v[152:153]
	v_pk_mul_f32 v[32:33], v[32:33], v[168:169]
	v_cvt_pk_bf16_f32 v184, v38, v39
	v_cvt_pk_bf16_f32 v185, v40, v41
	v_cvt_pk_bf16_f32 v186, v30, v31
	v_cvt_pk_bf16_f32 v187, v32, v33
	v_lshlrev_b32_e32 v176, 16, v188
	v_and_b32_e32 v177, 0xffff0000, v188
	v_lshlrev_b32_e32 v178, 16, v189
	v_and_b32_e32 v179, 0xffff0000, v189
	v_lshlrev_b32_e32 v180, 16, v190
	v_and_b32_e32 v181, 0xffff0000, v190
	v_lshlrev_b32_e32 v244, 16, v191
	v_and_b32_e32 v245, 0xffff0000, v191
	v_pk_mul_f32 v[176:177], v[176:177], v[240:241] op_sel_hi:[1,0]
	v_pk_mul_f32 v[178:179], v[178:179], v[240:241] op_sel_hi:[1,0]
	v_pk_mul_f32 v[180:181], v[180:181], v[240:241] op_sel_hi:[1,0]
	v_pk_mul_f32 v[244:245], v[244:245], v[240:241] op_sel_hi:[1,0]
	v_min_f32_e32 v176, 0x42b80000, v176
	v_min_f32_e32 v177, 0x42b80000, v177
	v_min_f32_e32 v178, 0x42b80000, v178
	v_min_f32_e32 v179, 0x42b80000, v179
	v_min_f32_e32 v180, 0x42b80000, v180
	v_min_f32_e32 v181, 0x42b80000, v181
	v_min_f32_e32 v244, 0x42b80000, v244
	v_min_f32_e32 v245, 0x42b80000, v245
	v_exp_f32_e32 v176, v176
	v_exp_f32_e32 v177, v177
	v_exp_f32_e32 v178, v178
	v_exp_f32_e32 v179, v179
	v_exp_f32_e32 v180, v180
	v_exp_f32_e32 v181, v181
	v_exp_f32_e32 v244, v244
	v_exp_f32_e32 v245, v245
	s_nop 0
	v_add_f32_e32 v176, 1.0, v176
	v_add_f32_e32 v177, 1.0, v177
	v_add_f32_e32 v178, 1.0, v178
	v_add_f32_e32 v179, 1.0, v179
	v_add_f32_e32 v180, 1.0, v180
	v_add_f32_e32 v181, 1.0, v181
	v_add_f32_e32 v244, 1.0, v244
	v_add_f32_e32 v245, 1.0, v245
	v_rcp_f32_e32 v176, v176
	v_rcp_f32_e32 v177, v177
	v_rcp_f32_e32 v178, v178
	v_rcp_f32_e32 v179, v179
	v_rcp_f32_e32 v180, v180
	v_rcp_f32_e32 v181, v181
	v_rcp_f32_e32 v244, v244
	v_rcp_f32_e32 v245, v245
	s_nop 0
	v_pk_mul_f32 v[18:19], v[18:19], v[176:177]
	v_pk_mul_f32 v[20:21], v[20:21], v[178:179]
	v_pk_mul_f32 v[10:11], v[10:11], v[180:181]
	v_pk_mul_f32 v[12:13], v[12:13], v[244:245]
	v_cvt_pk_bf16_f32 v188, v18, v19
	v_cvt_pk_bf16_f32 v189, v20, v21
	v_cvt_pk_bf16_f32 v190, v10, v11
	v_cvt_pk_bf16_f32 v191, v12, v13
	global_store_dwordx4 v[142:143], v[184:187], off
	global_store_dwordx4 v[142:143], v[188:191], off offset:256
	s_waitcnt vmcnt(10)
; DI float bflo(unsigned w) { return __uint_as_float(w << 16); }
; DI float bfhi(unsigned w) { return __uint_as_float(w & 0xffff0000u); }
; DI u32x4 pack8(f32x4 a, f32x4 b) { u32x4 w; w.x = pk2(a[0], a[1]); w.y = pk2(a[2], a[3]); w.z = pk2(b[0], b[1]); w.w = pk2(b[2], b[3]); return w; }
;     DI void operator()(Acc& acc, const Unit& u, int wr, int wc, int fr, int fq) const {
;     ...
;                     for (int bj = 0; bj < 2; ++bj) { const u32x4 q = g[ai][m][bj]; f32x4& v0 = acc[ai][bj][m][0]; f32x4& v1 = acc[ai][bj][m][1];
;                         v0[0] *= bflo(q.x); v0[1] *= bfhi(q.x); v0[2] *= bflo(q.y); v0[3] *= bfhi(q.y); v1[0] *= bflo(q.z); v1[1] *= bfhi(q.z); v1[2] *= bflo(q.w); v1[3] *= bfhi(q.w); }
;         }
;         if (u.k > 0) {
;             u32x4 g[2][4][2];
; #pragma unroll
;             for (int ai = 0; ai < 2; ++ai)
; #pragma unroll
;                 for (int m = 0; m < 4; ++m)
; #pragma unroll
;                     for (int bj = 0; bj < 2; ++bj) g[ai][m][bj] = *(const u32x4*)(base + (size_t)(ai * 128 + m * 16) * NPJ + bj * 128);
; #pragma unroll
;             for (int ai = 0; ai < 2; ++ai)
; #pragma unroll
;                 for (int m = 0; m < 4; ++m)
; #pragma unroll
;                     for (int bj = 0; bj < 2; ++bj) { const u32x4 q = g[ai][m][bj]; f32x4& v0 = acc[ai][bj][m][0]; f32x4& v1 = acc[ai][bj][m][1];
;                         v0[0] += bflo(q.x); v0[1] += bfhi(q.x); v0[2] += bflo(q.y); v0[3] += bfhi(q.y); v1[0] += bflo(q.z); v1[1] += bfhi(q.z); v1[2] += bflo(q.w); v1[3] += bfhi(q.w); }
;         }
;         if (!dry) {
; #pragma unroll
;             for (int ai = 0; ai < 2; ++ai)
; #pragma unroll
;                 for (int m = 0; m < 4; ++m)
; #pragma unroll
;                     for (int bj = 0; bj < 2; ++bj) *(u32x4*)(base + (size_t)(ai * 128 + m * 16) * NPJ + bj * 128) = pack8(acc[ai][bj][m][0], acc[ai][bj][m][1]);
	v_lshlrev_b32_e32 v148, 16, v192
	v_and_b32_e32 v149, 0xffff0000, v192
	v_lshlrev_b32_e32 v150, 16, v193
	v_and_b32_e32 v151, 0xffff0000, v193
	v_lshlrev_b32_e32 v152, 16, v194
	v_and_b32_e32 v153, 0xffff0000, v194
	v_lshlrev_b32_e32 v168, 16, v195
	v_and_b32_e32 v169, 0xffff0000, v195
	v_pk_mul_f32 v[148:149], v[148:149], v[240:241] op_sel_hi:[1,0]
	v_pk_mul_f32 v[150:151], v[150:151], v[240:241] op_sel_hi:[1,0]
	v_pk_mul_f32 v[152:153], v[152:153], v[240:241] op_sel_hi:[1,0]
	v_pk_mul_f32 v[168:169], v[168:169], v[240:241] op_sel_hi:[1,0]
	v_min_f32_e32 v148, 0x42b80000, v148
	v_min_f32_e32 v149, 0x42b80000, v149
	v_min_f32_e32 v150, 0x42b80000, v150
	v_min_f32_e32 v151, 0x42b80000, v151
	v_min_f32_e32 v152, 0x42b80000, v152
	v_min_f32_e32 v153, 0x42b80000, v153
	v_min_f32_e32 v168, 0x42b80000, v168
	v_min_f32_e32 v169, 0x42b80000, v169
	v_exp_f32_e32 v148, v148
	v_exp_f32_e32 v149, v149
	v_exp_f32_e32 v150, v150
	v_exp_f32_e32 v151, v151
	v_exp_f32_e32 v152, v152
	v_exp_f32_e32 v153, v153
	v_exp_f32_e32 v168, v168
	v_exp_f32_e32 v169, v169
	s_nop 0
	v_add_f32_e32 v148, 1.0, v148
	v_add_f32_e32 v149, 1.0, v149
	v_add_f32_e32 v150, 1.0, v150
	v_add_f32_e32 v151, 1.0, v151
	v_add_f32_e32 v152, 1.0, v152
	v_add_f32_e32 v153, 1.0, v153
	v_add_f32_e32 v168, 1.0, v168
	v_add_f32_e32 v169, 1.0, v169
	v_rcp_f32_e32 v148, v148
	v_rcp_f32_e32 v149, v149
	v_rcp_f32_e32 v150, v150
	v_rcp_f32_e32 v151, v151
	v_rcp_f32_e32 v152, v152
	v_rcp_f32_e32 v153, v153
	v_rcp_f32_e32 v168, v168
	v_rcp_f32_e32 v169, v169
	s_nop 0
	v_pk_mul_f32 v[22:23], v[22:23], v[148:149]
	v_pk_mul_f32 v[24:25], v[24:25], v[150:151]
	v_pk_mul_f32 v[14:15], v[14:15], v[152:153]
	v_pk_mul_f32 v[16:17], v[16:17], v[168:169]
	v_cvt_pk_bf16_f32 v192, v22, v23
	v_cvt_pk_bf16_f32 v193, v24, v25
	v_cvt_pk_bf16_f32 v194, v14, v15
	v_cvt_pk_bf16_f32 v195, v16, v17
	v_lshlrev_b32_e32 v176, 16, v196
	v_and_b32_e32 v177, 0xffff0000, v196
	v_lshlrev_b32_e32 v178, 16, v197
	v_and_b32_e32 v179, 0xffff0000, v197
	v_lshlrev_b32_e32 v180, 16, v198
	v_and_b32_e32 v181, 0xffff0000, v198
	v_lshlrev_b32_e32 v244, 16, v199
	v_and_b32_e32 v245, 0xffff0000, v199
	v_pk_mul_f32 v[176:177], v[176:177], v[240:241] op_sel_hi:[1,0]
	v_pk_mul_f32 v[178:179], v[178:179], v[240:241] op_sel_hi:[1,0]
	v_pk_mul_f32 v[180:181], v[180:181], v[240:241] op_sel_hi:[1,0]
	v_pk_mul_f32 v[244:245], v[244:245], v[240:241] op_sel_hi:[1,0]
	v_min_f32_e32 v176, 0x42b80000, v176
	v_min_f32_e32 v177, 0x42b80000, v177
	v_min_f32_e32 v178, 0x42b80000, v178
	v_min_f32_e32 v179, 0x42b80000, v179
	v_min_f32_e32 v180, 0x42b80000, v180
	v_min_f32_e32 v181, 0x42b80000, v181
	v_min_f32_e32 v244, 0x42b80000, v244
	v_min_f32_e32 v245, 0x42b80000, v245
	v_exp_f32_e32 v176, v176
	v_exp_f32_e32 v177, v177
	v_exp_f32_e32 v178, v178
	v_exp_f32_e32 v179, v179
	v_exp_f32_e32 v180, v180
	v_exp_f32_e32 v181, v181
	v_exp_f32_e32 v244, v244
	v_exp_f32_e32 v245, v245
	s_nop 0
	v_add_f32_e32 v176, 1.0, v176
	v_add_f32_e32 v177, 1.0, v177
	v_add_f32_e32 v178, 1.0, v178
	v_add_f32_e32 v179, 1.0, v179
	v_add_f32_e32 v180, 1.0, v180
	v_add_f32_e32 v181, 1.0, v181
	v_add_f32_e32 v244, 1.0, v244
	v_add_f32_e32 v245, 1.0, v245
	v_rcp_f32_e32 v176, v176
	v_rcp_f32_e32 v177, v177
	v_rcp_f32_e32 v178, v178
	v_rcp_f32_e32 v179, v179
	v_rcp_f32_e32 v180, v180
	v_rcp_f32_e32 v181, v181
	v_rcp_f32_e32 v244, v244
	v_rcp_f32_e32 v245, v245
	s_nop 0
	v_pk_mul_f32 v[6:7], v[6:7], v[176:177]
	v_pk_mul_f32 v[8:9], v[8:9], v[178:179]
	v_pk_mul_f32 v[2:3], v[2:3], v[180:181]
	v_pk_mul_f32 v[4:5], v[4:5], v[244:245]
	v_cvt_pk_bf16_f32 v196, v6, v7
	v_cvt_pk_bf16_f32 v197, v8, v9
	v_cvt_pk_bf16_f32 v198, v2, v3
	v_cvt_pk_bf16_f32 v199, v4, v5
	global_store_dwordx4 v[144:145], v[192:195], off
	global_store_dwordx4 v[144:145], v[196:199], off offset:256
